# plus batched rope/ssq epilogue loads (P3,P19,P7) and static priority for waves 4-7 in attention phases
# speedup vs baseline: 1.0564x; 1.0174x over previous
.LBB0_875:
	s_waitcnt lgkmcnt(0)
	s_barrier
	ds_read_b128 v[170:173], v169
	ds_read_b128 v[174:177], v215
	ds_read_b128 v[178:181], v215 offset:32
	ds_read_b128 v[182:185], v169 offset:32
	ds_read_b128 v[186:189], v169 offset:4608
	ds_read_b128 v[190:193], v169 offset:4640
	s_waitcnt lgkmcnt(4)
	v_mfma_f32_32x32x16_bf16 v[96:111], v[170:173], v[174:177], v[96:111]
	s_waitcnt lgkmcnt(1)
	v_mfma_f32_32x32x16_bf16 v[32:47], v[186:189], v[174:177], v[32:47]
	ds_read_b128 v[174:177], v215 offset:4608
	ds_read_b128 v[194:197], v215 offset:4640
	s_waitcnt lgkmcnt(1)
	v_mfma_f32_32x32x16_bf16 v[112:127], v[170:173], v[174:177], v[112:127]
	v_mfma_f32_32x32x16_bf16 v[48:63], v[186:189], v[174:177], v[48:63]
	ds_read_b128 v[174:177], v215 offset:9216
	ds_read_b128 v[198:201], v215 offset:9248
	s_waitcnt lgkmcnt(1)
	v_mfma_f32_32x32x16_bf16 v[64:79], v[170:173], v[174:177], v[64:79]
	v_mfma_f32_32x32x16_bf16 v[0:15], v[186:189], v[174:177], v[0:15]
	ds_read_b128 v[174:177], v215 offset:13824
	ds_read_b128 v[202:205], v215 offset:13856
	s_waitcnt lgkmcnt(1)
	v_mfma_f32_32x32x16_bf16 v[80:95], v[170:173], v[174:177], v[80:95]
	v_mfma_f32_32x32x16_bf16 v[16:31], v[186:189], v[174:177], v[16:31]
	v_mfma_f32_32x32x16_bf16 v[96:111], v[182:185], v[178:181], v[96:111]
	v_mfma_f32_32x32x16_bf16 v[32:47], v[190:193], v[178:181], v[32:47]
	v_mfma_f32_32x32x16_bf16 v[112:127], v[182:185], v[194:197], v[112:127]
	v_mfma_f32_32x32x16_bf16 v[48:63], v[190:193], v[194:197], v[48:63]
	v_mfma_f32_32x32x16_bf16 v[64:79], v[182:185], v[198:201], v[64:79]
	v_mfma_f32_32x32x16_bf16 v[0:15], v[190:193], v[198:201], v[0:15]
	s_waitcnt lgkmcnt(0)
	v_mfma_f32_32x32x16_bf16 v[80:95], v[182:185], v[202:205], v[80:95]
	v_mfma_f32_32x32x16_bf16 v[16:31], v[190:193], v[202:205], v[16:31]
	ds_read_b128 v[170:173], v169 offset:64
	ds_read_b128 v[174:177], v215 offset:64
	ds_read_b128 v[178:181], v215 offset:96
	ds_read_b128 v[182:185], v169 offset:96
	ds_read_b128 v[186:189], v169 offset:4672
	ds_read_b128 v[190:193], v169 offset:4704
	v_mov_b32_e32 v218, v209
	s_waitcnt lgkmcnt(4)
	v_mfma_f32_32x32x16_bf16 v[96:111], v[170:173], v[174:177], v[96:111]
	s_add_i32 s55, s55, s30
	s_add_i32 s3, s36, s37
	s_add_i32 s3, s3, s2
	s_ashr_i32 s24, s3, 6
	s_mul_hi_i32 s53, s24, 0x55555556
	s_lshr_b32 s2, s53, 31
	s_add_i32 s53, s53, s2
	s_waitcnt lgkmcnt(1)
	v_mfma_f32_32x32x16_bf16 v[32:47], v[186:189], v[174:177], v[32:47]
	ds_read_b128 v[174:177], v215 offset:4672
	ds_read_b128 v[194:197], v215 offset:4704
	s_mul_i32 s2, s53, 3
	s_sub_i32 s2, s24, s2
	s_cmp_eq_u32 s2, 2
	s_cselect_b64 s[6:7], -1, 0
	s_cmp_lg_u32 s2, 2
	s_waitcnt lgkmcnt(1)
	v_mfma_f32_32x32x16_bf16 v[112:127], v[170:173], v[174:177], v[112:127]
	v_mfma_f32_32x32x16_bf16 v[48:63], v[186:189], v[174:177], v[48:63]
	ds_read_b128 v[174:177], v215 offset:9280
	ds_read_b128 v[198:201], v215 offset:9312
	s_waitcnt lgkmcnt(1)
	v_mfma_f32_32x32x16_bf16 v[64:79], v[170:173], v[174:177], v[64:79]
	v_mfma_f32_32x32x16_bf16 v[0:15], v[186:189], v[174:177], v[0:15]
	ds_read_b128 v[174:177], v215 offset:13888
	ds_read_b128 v[222:225], v215 offset:13920
	s_waitcnt lgkmcnt(0)
	s_barrier
	s_load_dwordx2 s[18:19], s[0:1], 0x210
	v_ashrrev_i32_e32 v219, 3, v218
	v_and_b32_e32 v220, -4, v219
	v_add_u32_e32 v204, s55, v220
	v_mfma_f32_32x32x16_bf16 v[80:95], v[170:173], v[174:177], v[80:95]
	v_min_i32_e32 v170, 0x7fff, v204
	v_ashrrev_i32_e32 v171, 31, v170
	s_waitcnt lgkmcnt(0)
	v_lshl_add_u64 v[172:173], v[170:171], 2, s[18:19]
	global_load_dword v242, v[172:173], off
	global_load_dword v243, v[172:173], off offset:4
	global_load_dword v244, v[172:173], off offset:8
	global_load_dword v245, v[172:173], off offset:12
	v_lshlrev_b64 v[170:171], 8, v[170:171]
	s_waitcnt vmcnt(0)
	v_mov_b32_e32 v160, v242
	v_fmamk_f32 v160, v160, 0x3b800000, v216
	v_mfma_f32_32x32x16_bf16 v[16:31], v[186:189], v[174:177], v[16:31]
	v_mul_f32_e32 v174, 0x4b800000, v160
	v_cmp_gt_f32_e32 vcc, s38, v160
	s_nop 1
	v_cndmask_b32_e32 v160, v160, v174, vcc
	v_rsq_f32_e32 v160, v160
	v_mfma_f32_32x32x16_bf16 v[96:111], v[182:185], v[178:181], v[96:111]
	v_mul_f32_e32 v174, 0x45800000, v160
	v_cndmask_b32_e32 v160, v160, v174, vcc
	v_mul_f32_e32 v160, 0x3dd53b94, v160
	v_mfma_f32_32x32x16_bf16 v[112:127], v[182:185], v[194:197], v[112:127]
	s_nop 7
	v_mov_b32_e32 v175, v96
	v_mfma_f32_32x32x16_bf16 v[32:47], v[190:193], v[178:181], v[32:47]
	v_and_b32_e32 v178, 31, v218
	s_nop 0
	v_mov_b32_e32 v174, v112
	v_mul_f32_e64 v176, v174, v160
	v_mul_f32_e64 v177, v175, v160
	v_lshlrev_b32_e32 v160, 3, v178
	v_mfma_f32_32x32x16_bf16 v[48:63], v[190:193], v[194:197], v[48:63]
	v_mfma_f32_32x32x16_bf16 v[64:79], v[182:185], v[198:201], v[64:79]
	v_mfma_f32_32x32x16_bf16 v[0:15], v[190:193], v[198:201], v[0:15]
	v_mfma_f32_32x32x16_bf16 v[80:95], v[182:185], v[222:225], v[80:95]
	v_mfma_f32_32x32x16_bf16 v[16:31], v[190:193], v[222:225], v[16:31]
	s_cbranch_scc1 .LBB0_877
	s_load_dwordx2 s[2:3], s[0:1], 0x148
	s_waitcnt lgkmcnt(0)
	v_lshl_add_u64 v[174:175], s[2:3], 0, v[170:171]
	v_lshl_add_u64 v[174:175], v[174:175], 0, v[160:161]
	global_load_dwordx2 v[246:247], v[174:175], off
	global_load_dwordx2 v[248:249], v[174:175], off offset:256
	global_load_dwordx2 v[250:251], v[174:175], off offset:512
	global_load_dwordx2 v[252:253], v[174:175], off offset:768
	s_waitcnt vmcnt(0)
	v_mov_b32_e32 v174, v246
	v_mov_b32_e32 v175, v247
	v_pk_mul_f32 v[180:181], v[176:177], v[174:175] op_sel_hi:[0,1]
	v_pk_mul_f32 v[182:183], v[176:177], v[174:175] op_sel:[1,1] op_sel_hi:[1,0]
	v_pk_fma_f32 v[176:177], v[176:177], v[174:175], v[180:181] op_sel:[1,1,0] op_sel_hi:[1,0,1] neg_lo:[0,0,1] neg_hi:[0,0,1]
	s_nop 0
	v_add_f32_e32 v176, v182, v180
.LBB0_877:
	v_or_b32_e32 v96, 1, v204
	v_min_i32_e32 v180, 0x7fff, v96
	v_ashrrev_i32_e32 v181, 31, v180
	v_lshl_add_u64 v[174:175], v[180:181], 2, s[18:19]
	v_mov_b32_e32 v112, v243
	v_mov_b32_e32 v96, v113
	v_cndmask_b32_e64 v113, 0, 1, s[6:7]
	v_cmp_ne_u32_e64 s[2:3], 1, v113
	v_mul_lo_u32 v179, v220, s29
	v_or_b32_e32 v178, v179, v178
	v_cvt_pk_bf16_f32 v177, v177, s0
	v_lshl_add_u32 v217, v178, 1, s31
	s_andn2_b64 vcc, exec, s[6:7]
	v_cvt_pk_bf16_f32 v176, v176, s0
	ds_write_b16 v217, v177
	ds_write_b16 v217, v176 offset:64
	s_waitcnt vmcnt(0)
	v_fmamk_f32 v112, v112, 0x3b800000, v216
	v_mul_f32_e32 v113, 0x4b800000, v112
	v_cmp_gt_f32_e64 s[4:5], s38, v112
	s_nop 1
	v_cndmask_b32_e64 v112, v112, v113, s[4:5]
	v_rsq_f32_e32 v112, v112
	s_nop 0
	v_mul_f32_e32 v113, 0x45800000, v112
	v_cndmask_b32_e64 v112, v112, v113, s[4:5]
	v_mul_f32_e32 v112, 0x3dd53b94, v112
	v_pk_mul_f32 v[96:97], v[96:97], v[112:113] op_sel_hi:[1,0]
	v_lshlrev_b64 v[112:113], 8, v[180:181]
	s_cbranch_vccnz .LBB0_879
	s_load_dwordx2 s[4:5], s[0:1], 0x148
	s_waitcnt lgkmcnt(0)
	v_lshl_add_u64 v[176:177], s[4:5], 0, v[112:113]
	v_lshl_add_u64 v[176:177], v[176:177], 0, v[160:161]
	v_mov_b32_e32 v176, v248
	v_mov_b32_e32 v177, v249
	s_waitcnt vmcnt(0)
	v_pk_mul_f32 v[178:179], v[96:97], v[176:177] op_sel_hi:[0,1]
	v_pk_mul_f32 v[180:181], v[96:97], v[176:177] op_sel:[1,1] op_sel_hi:[1,0]
	v_pk_fma_f32 v[96:97], v[96:97], v[176:177], v[178:179] op_sel:[1,1,0] op_sel_hi:[1,0,1] neg_lo:[0,0,1] neg_hi:[0,0,1]
	s_nop 0
	v_add_f32_e32 v96, v180, v178
.LBB0_879:
	v_or_b32_e32 v176, 2, v204
	v_min_i32_e32 v176, 0x7fff, v176
	v_ashrrev_i32_e32 v177, 31, v176
	v_lshl_add_u64 v[178:179], v[176:177], 2, s[18:19]
	v_mov_b32_e32 v180, v244
	v_cvt_pk_bf16_f32 v181, v97, s0
	v_mov_b32_e32 v97, v98
	v_cvt_pk_bf16_f32 v182, v96, s0
	v_mov_b32_e32 v96, v114
	s_and_b64 vcc, exec, s[2:3]
	v_lshlrev_b64 v[176:177], 8, v[176:177]
	ds_write_b16 v217, v181 offset:144
	ds_write_b16 v217, v182 offset:208
	s_waitcnt vmcnt(0)
	v_fmamk_f32 v98, v180, 0x3b800000, v216
	v_mul_f32_e32 v114, 0x4b800000, v98
	v_cmp_gt_f32_e64 s[4:5], s38, v98
	s_nop 1
	v_cndmask_b32_e64 v98, v98, v114, s[4:5]
	v_rsq_f32_e32 v98, v98
	s_nop 0
	v_mul_f32_e32 v114, 0x45800000, v98
	v_cndmask_b32_e64 v98, v98, v114, s[4:5]
	v_mul_f32_e32 v98, 0x3dd53b94, v98
	v_pk_mul_f32 v[96:97], v[96:97], v[98:99] op_sel_hi:[1,0]
	s_cbranch_vccnz .LBB0_881
	s_load_dwordx2 s[4:5], s[0:1], 0x148
	s_waitcnt lgkmcnt(0)
	v_lshl_add_u64 v[180:181], s[4:5], 0, v[176:177]
	v_lshl_add_u64 v[180:181], v[180:181], 0, v[160:161]
	v_mov_b32_e32 v180, v250
	v_mov_b32_e32 v181, v251
	s_waitcnt vmcnt(0)
	v_pk_mul_f32 v[182:183], v[96:97], v[180:181] op_sel_hi:[0,1]
	v_pk_mul_f32 v[184:185], v[96:97], v[180:181] op_sel:[1,1] op_sel_hi:[1,0]
	v_pk_fma_f32 v[96:97], v[96:97], v[180:181], v[182:183] op_sel:[1,1,0] op_sel_hi:[1,0,1] neg_lo:[0,0,1] neg_hi:[0,0,1]
	s_nop 0
	v_add_f32_e32 v96, v184, v182
.LBB0_881:
	v_or_b32_e32 v98, 3, v204
	v_min_i32_e32 v182, 0x7fff, v98
	v_ashrrev_i32_e32 v183, 31, v182
	v_lshl_add_u64 v[180:181], v[182:183], 2, s[18:19]
	v_mov_b32_e32 v114, v245
	v_mov_b32_e32 v98, v115
	v_cvt_pk_bf16_f32 v97, v97, s0
	v_cvt_pk_bf16_f32 v96, v96, s0
	ds_write_b16 v217, v97 offset:288
	ds_write_b16 v217, v96 offset:352
	s_and_b64 vcc, exec, s[2:3]
	s_waitcnt vmcnt(0)
	v_fmamk_f32 v114, v114, 0x3b800000, v216
	v_mul_f32_e32 v115, 0x4b800000, v114
	v_cmp_gt_f32_e64 s[4:5], s38, v114
	s_nop 1
	v_cndmask_b32_e64 v114, v114, v115, s[4:5]
	v_rsq_f32_e32 v114, v114
	s_nop 0
	v_mul_f32_e32 v96, 0x45800000, v114
	v_cndmask_b32_e64 v96, v114, v96, s[4:5]
	v_mul_f32_e32 v96, 0x3dd53b94, v96
	v_pk_mul_f32 v[96:97], v[98:99], v[96:97] op_sel_hi:[1,0]
	v_lshlrev_b64 v[98:99], 8, v[182:183]
	s_cbranch_vccnz .LBB0_883
	s_load_dwordx2 s[4:5], s[0:1], 0x148
	s_waitcnt lgkmcnt(0)
	v_lshl_add_u64 v[114:115], s[4:5], 0, v[98:99]
	v_lshl_add_u64 v[114:115], v[114:115], 0, v[160:161]
	v_mov_b32_e32 v114, v252
	v_mov_b32_e32 v115, v253
	s_waitcnt vmcnt(0)
	v_pk_mul_f32 v[182:183], v[96:97], v[114:115] op_sel_hi:[0,1]
	v_pk_mul_f32 v[184:185], v[96:97], v[114:115] op_sel:[1,1] op_sel_hi:[1,0]
	v_pk_fma_f32 v[96:97], v[96:97], v[114:115], v[182:183] op_sel:[1,1,0] op_sel_hi:[1,0,1] neg_lo:[0,0,1] neg_hi:[0,0,1]
	s_nop 0
	v_add_f32_e32 v96, v184, v182
.LBB0_883:
	v_add_u32_e32 v114, 8, v204
	v_min_i32_e32 v114, 0x7fff, v114
	v_ashrrev_i32_e32 v115, 31, v114
	v_lshl_add_u64 v[182:183], v[114:115], 2, s[18:19]
	global_load_dword v242, v[182:183], off
	global_load_dword v243, v[182:183], off offset:4
	global_load_dword v244, v[182:183], off offset:8
	global_load_dword v245, v[182:183], off offset:12
	v_cvt_pk_bf16_f32 v185, v97, s0
	v_mov_b32_e32 v97, v100
	v_cvt_pk_bf16_f32 v186, v96, s0
	v_mov_b32_e32 v96, v116
	s_and_b64 vcc, exec, s[2:3]
	v_lshlrev_b64 v[114:115], 8, v[114:115]
	ds_write_b16 v217, v185 offset:432
	ds_write_b16 v217, v186 offset:496
	s_waitcnt vmcnt(0)
	v_mov_b32_e32 v184, v242
	v_fmamk_f32 v100, v184, 0x3b800000, v216
	v_mul_f32_e32 v116, 0x4b800000, v100
	v_cmp_gt_f32_e64 s[4:5], s38, v100
	s_nop 1
	v_cndmask_b32_e64 v100, v100, v116, s[4:5]
	v_rsq_f32_e32 v100, v100
	s_nop 0
	v_mul_f32_e32 v116, 0x45800000, v100
	v_cndmask_b32_e64 v100, v100, v116, s[4:5]
	v_mul_f32_e32 v100, 0x3dd53b94, v100
	v_pk_mul_f32 v[96:97], v[96:97], v[100:101] op_sel_hi:[1,0]
	s_cbranch_vccnz .LBB0_885
	s_load_dwordx2 s[4:5], s[0:1], 0x148
	s_waitcnt lgkmcnt(0)
	v_lshl_add_u64 v[184:185], s[4:5], 0, v[114:115]
	v_lshl_add_u64 v[184:185], v[184:185], 0, v[160:161]
	global_load_dwordx2 v[246:247], v[184:185], off
	global_load_dwordx2 v[248:249], v[184:185], off offset:256
	global_load_dwordx2 v[250:251], v[184:185], off offset:512
	global_load_dwordx2 v[252:253], v[184:185], off offset:768
	s_waitcnt vmcnt(0)
	v_mov_b32_e32 v184, v246
	v_mov_b32_e32 v185, v247
	v_pk_mul_f32 v[186:187], v[96:97], v[184:185] op_sel_hi:[0,1]
	v_pk_mul_f32 v[188:189], v[96:97], v[184:185] op_sel:[1,1] op_sel_hi:[1,0]
	v_pk_fma_f32 v[96:97], v[96:97], v[184:185], v[186:187] op_sel:[1,1,0] op_sel_hi:[1,0,1] neg_lo:[0,0,1] neg_hi:[0,0,1]
	s_nop 0
	v_add_f32_e32 v96, v188, v186
.LBB0_885:
	v_add_u32_e32 v100, 9, v204
	v_min_i32_e32 v186, 0x7fff, v100
	v_ashrrev_i32_e32 v187, 31, v186
	v_lshl_add_u64 v[184:185], v[186:187], 2, s[18:19]
	v_mov_b32_e32 v116, v243
	v_mov_b32_e32 v100, v117
	v_cvt_pk_bf16_f32 v97, v97, s0
	v_cvt_pk_bf16_f32 v96, v96, s0
	ds_write_b16 v217, v97 offset:1152
	ds_write_b16 v217, v96 offset:1216
	s_and_b64 vcc, exec, s[2:3]
	s_waitcnt vmcnt(0)
	v_fmamk_f32 v116, v116, 0x3b800000, v216
	v_mul_f32_e32 v117, 0x4b800000, v116
	v_cmp_gt_f32_e64 s[4:5], s38, v116
	s_nop 1
	v_cndmask_b32_e64 v116, v116, v117, s[4:5]
	v_rsq_f32_e32 v116, v116
	s_nop 0
	v_mul_f32_e32 v96, 0x45800000, v116
	v_cndmask_b32_e64 v96, v116, v96, s[4:5]
	v_mul_f32_e32 v96, 0x3dd53b94, v96
	v_pk_mul_f32 v[96:97], v[100:101], v[96:97] op_sel_hi:[1,0]
	v_lshlrev_b64 v[100:101], 8, v[186:187]
	s_cbranch_vccnz .LBB0_887
	s_load_dwordx2 s[4:5], s[0:1], 0x148
	s_waitcnt lgkmcnt(0)
	v_lshl_add_u64 v[116:117], s[4:5], 0, v[100:101]
	v_lshl_add_u64 v[116:117], v[116:117], 0, v[160:161]
	v_mov_b32_e32 v116, v248
	v_mov_b32_e32 v117, v249
	s_waitcnt vmcnt(0)
	v_pk_mul_f32 v[186:187], v[96:97], v[116:117] op_sel_hi:[0,1]
	v_pk_mul_f32 v[188:189], v[96:97], v[116:117] op_sel:[1,1] op_sel_hi:[1,0]
	v_pk_fma_f32 v[96:97], v[96:97], v[116:117], v[186:187] op_sel:[1,1,0] op_sel_hi:[1,0,1] neg_lo:[0,0,1] neg_hi:[0,0,1]
	s_nop 0
	v_add_f32_e32 v96, v188, v186
.LBB0_887:
	v_add_u32_e32 v116, 10, v204
	v_min_i32_e32 v116, 0x7fff, v116
	v_ashrrev_i32_e32 v117, 31, v116
	v_lshl_add_u64 v[186:187], v[116:117], 2, s[18:19]
	v_mov_b32_e32 v188, v244
	v_cvt_pk_bf16_f32 v189, v97, s0
	v_mov_b32_e32 v97, v102
	v_cvt_pk_bf16_f32 v190, v96, s0
	v_mov_b32_e32 v96, v118
	s_and_b64 vcc, exec, s[2:3]
	v_lshlrev_b64 v[116:117], 8, v[116:117]
	ds_write_b16 v217, v189 offset:1296
	ds_write_b16 v217, v190 offset:1360
	s_waitcnt vmcnt(0)
	v_fmamk_f32 v102, v188, 0x3b800000, v216
	v_mul_f32_e32 v118, 0x4b800000, v102
	v_cmp_gt_f32_e64 s[4:5], s38, v102
	s_nop 1
	v_cndmask_b32_e64 v102, v102, v118, s[4:5]
	v_rsq_f32_e32 v102, v102
	s_nop 0
	v_mul_f32_e32 v118, 0x45800000, v102
	v_cndmask_b32_e64 v102, v102, v118, s[4:5]
	v_mul_f32_e32 v102, 0x3dd53b94, v102
	v_pk_mul_f32 v[96:97], v[96:97], v[102:103] op_sel_hi:[1,0]
	s_cbranch_vccnz .LBB0_889
	s_load_dwordx2 s[4:5], s[0:1], 0x148
	s_waitcnt lgkmcnt(0)
	v_lshl_add_u64 v[188:189], s[4:5], 0, v[116:117]
	v_lshl_add_u64 v[188:189], v[188:189], 0, v[160:161]
	v_mov_b32_e32 v188, v250
	v_mov_b32_e32 v189, v251
	s_waitcnt vmcnt(0)
	v_pk_mul_f32 v[190:191], v[96:97], v[188:189] op_sel_hi:[0,1]
	v_pk_mul_f32 v[192:193], v[96:97], v[188:189] op_sel:[1,1] op_sel_hi:[1,0]
	v_pk_fma_f32 v[96:97], v[96:97], v[188:189], v[190:191] op_sel:[1,1,0] op_sel_hi:[1,0,1] neg_lo:[0,0,1] neg_hi:[0,0,1]
	s_nop 0
	v_add_f32_e32 v96, v192, v190
.LBB0_889:
	v_add_u32_e32 v102, 11, v204
	v_min_i32_e32 v190, 0x7fff, v102
	v_ashrrev_i32_e32 v191, 31, v190
	v_lshl_add_u64 v[188:189], v[190:191], 2, s[18:19]
	v_mov_b32_e32 v118, v245
	v_mov_b32_e32 v102, v119
	v_cvt_pk_bf16_f32 v97, v97, s0
	v_cvt_pk_bf16_f32 v96, v96, s0
	ds_write_b16 v217, v97 offset:1440
	ds_write_b16 v217, v96 offset:1504
	s_and_b64 vcc, exec, s[2:3]
	s_waitcnt vmcnt(0)
	v_fmamk_f32 v118, v118, 0x3b800000, v216
	v_mul_f32_e32 v119, 0x4b800000, v118
	v_cmp_gt_f32_e64 s[4:5], s38, v118
	s_nop 1
	v_cndmask_b32_e64 v118, v118, v119, s[4:5]
	v_rsq_f32_e32 v118, v118
	s_nop 0
	v_mul_f32_e32 v96, 0x45800000, v118
	v_cndmask_b32_e64 v96, v118, v96, s[4:5]
	v_mul_f32_e32 v96, 0x3dd53b94, v96
	v_pk_mul_f32 v[96:97], v[102:103], v[96:97] op_sel_hi:[1,0]
	v_lshlrev_b64 v[102:103], 8, v[190:191]
	s_cbranch_vccnz .LBB0_891
	s_load_dwordx2 s[4:5], s[0:1], 0x148
	s_waitcnt lgkmcnt(0)
	v_lshl_add_u64 v[118:119], s[4:5], 0, v[102:103]
	v_lshl_add_u64 v[118:119], v[118:119], 0, v[160:161]
	v_mov_b32_e32 v118, v252
	v_mov_b32_e32 v119, v253
	s_waitcnt vmcnt(0)
	v_pk_mul_f32 v[190:191], v[96:97], v[118:119] op_sel_hi:[0,1]
	v_pk_mul_f32 v[192:193], v[96:97], v[118:119] op_sel:[1,1] op_sel_hi:[1,0]
	v_pk_fma_f32 v[96:97], v[96:97], v[118:119], v[190:191] op_sel:[1,1,0] op_sel_hi:[1,0,1] neg_lo:[0,0,1] neg_hi:[0,0,1]
	s_nop 0
	v_add_f32_e32 v96, v192, v190
.LBB0_891:
	v_add_u32_e32 v118, 16, v204
	v_min_i32_e32 v118, 0x7fff, v118
	v_ashrrev_i32_e32 v119, 31, v118
	v_lshl_add_u64 v[190:191], v[118:119], 2, s[18:19]
	global_load_dword v242, v[190:191], off
	global_load_dword v243, v[190:191], off offset:4
	global_load_dword v244, v[190:191], off offset:8
	global_load_dword v245, v[190:191], off offset:12
	v_cvt_pk_bf16_f32 v193, v97, s0
	v_mov_b32_e32 v97, v104
	v_cvt_pk_bf16_f32 v194, v96, s0
	v_mov_b32_e32 v96, v120
	s_and_b64 vcc, exec, s[2:3]
	v_lshlrev_b64 v[118:119], 8, v[118:119]
	ds_write_b16 v217, v193 offset:1584
	ds_write_b16 v217, v194 offset:1648
	s_waitcnt vmcnt(0)
	v_mov_b32_e32 v192, v242
	v_fmamk_f32 v104, v192, 0x3b800000, v216
	v_mul_f32_e32 v120, 0x4b800000, v104
	v_cmp_gt_f32_e64 s[4:5], s38, v104
	s_nop 1
	v_cndmask_b32_e64 v104, v104, v120, s[4:5]
	v_rsq_f32_e32 v104, v104
	s_nop 0
	v_mul_f32_e32 v120, 0x45800000, v104
	v_cndmask_b32_e64 v104, v104, v120, s[4:5]
	v_mul_f32_e32 v104, 0x3dd53b94, v104
	v_pk_mul_f32 v[96:97], v[96:97], v[104:105] op_sel_hi:[1,0]
	s_cbranch_vccnz .LBB0_893
	s_load_dwordx2 s[4:5], s[0:1], 0x148
	s_waitcnt lgkmcnt(0)
	v_lshl_add_u64 v[192:193], s[4:5], 0, v[118:119]
	v_lshl_add_u64 v[192:193], v[192:193], 0, v[160:161]
	global_load_dwordx2 v[246:247], v[192:193], off
	global_load_dwordx2 v[248:249], v[192:193], off offset:256
	global_load_dwordx2 v[250:251], v[192:193], off offset:512
	global_load_dwordx2 v[252:253], v[192:193], off offset:768
	s_waitcnt vmcnt(0)
	v_mov_b32_e32 v192, v246
	v_mov_b32_e32 v193, v247
	v_pk_mul_f32 v[194:195], v[96:97], v[192:193] op_sel_hi:[0,1]
	v_pk_mul_f32 v[196:197], v[96:97], v[192:193] op_sel:[1,1] op_sel_hi:[1,0]
	v_pk_fma_f32 v[96:97], v[96:97], v[192:193], v[194:195] op_sel:[1,1,0] op_sel_hi:[1,0,1] neg_lo:[0,0,1] neg_hi:[0,0,1]
	s_nop 0
	v_add_f32_e32 v96, v196, v194
.LBB0_893:
	v_add_u32_e32 v104, 17, v204
	v_min_i32_e32 v194, 0x7fff, v104
	v_ashrrev_i32_e32 v195, 31, v194
	v_lshl_add_u64 v[192:193], v[194:195], 2, s[18:19]
	v_mov_b32_e32 v120, v243
	v_mov_b32_e32 v104, v121
	v_cvt_pk_bf16_f32 v97, v97, s0
	v_cvt_pk_bf16_f32 v96, v96, s0
	ds_write_b16 v217, v97 offset:2304
	ds_write_b16 v217, v96 offset:2368
	s_and_b64 vcc, exec, s[2:3]
	s_waitcnt vmcnt(0)
	v_fmamk_f32 v120, v120, 0x3b800000, v216
	v_mul_f32_e32 v121, 0x4b800000, v120
	v_cmp_gt_f32_e64 s[4:5], s38, v120
	s_nop 1
	v_cndmask_b32_e64 v120, v120, v121, s[4:5]
	v_rsq_f32_e32 v120, v120
	s_nop 0
	v_mul_f32_e32 v96, 0x45800000, v120
	v_cndmask_b32_e64 v96, v120, v96, s[4:5]
	v_mul_f32_e32 v96, 0x3dd53b94, v96
	v_pk_mul_f32 v[96:97], v[104:105], v[96:97] op_sel_hi:[1,0]
	v_lshlrev_b64 v[104:105], 8, v[194:195]
	s_cbranch_vccnz .LBB0_895
	s_load_dwordx2 s[4:5], s[0:1], 0x148
	s_waitcnt lgkmcnt(0)
	v_lshl_add_u64 v[120:121], s[4:5], 0, v[104:105]
	v_lshl_add_u64 v[120:121], v[120:121], 0, v[160:161]
	v_mov_b32_e32 v120, v248
	v_mov_b32_e32 v121, v249
	s_waitcnt vmcnt(0)
	v_pk_mul_f32 v[194:195], v[96:97], v[120:121] op_sel_hi:[0,1]
	v_pk_mul_f32 v[196:197], v[96:97], v[120:121] op_sel:[1,1] op_sel_hi:[1,0]
	v_pk_fma_f32 v[96:97], v[96:97], v[120:121], v[194:195] op_sel:[1,1,0] op_sel_hi:[1,0,1] neg_lo:[0,0,1] neg_hi:[0,0,1]
	s_nop 0
	v_add_f32_e32 v96, v196, v194
.LBB0_895:
	v_add_u32_e32 v120, 18, v204
	v_min_i32_e32 v120, 0x7fff, v120
	v_ashrrev_i32_e32 v121, 31, v120
	v_lshl_add_u64 v[194:195], v[120:121], 2, s[18:19]
	v_mov_b32_e32 v196, v244
	v_cvt_pk_bf16_f32 v197, v97, s0
	v_mov_b32_e32 v97, v106
	v_cvt_pk_bf16_f32 v198, v96, s0
	v_mov_b32_e32 v96, v122
	s_and_b64 vcc, exec, s[2:3]
	v_lshlrev_b64 v[120:121], 8, v[120:121]
	ds_write_b16 v217, v197 offset:2448
	ds_write_b16 v217, v198 offset:2512
	s_waitcnt vmcnt(0)
	v_fmamk_f32 v106, v196, 0x3b800000, v216
	v_mul_f32_e32 v122, 0x4b800000, v106
	v_cmp_gt_f32_e64 s[4:5], s38, v106
	s_nop 1
	v_cndmask_b32_e64 v106, v106, v122, s[4:5]
	v_rsq_f32_e32 v106, v106
	s_nop 0
	v_mul_f32_e32 v122, 0x45800000, v106
	v_cndmask_b32_e64 v106, v106, v122, s[4:5]
	v_mul_f32_e32 v106, 0x3dd53b94, v106
	v_pk_mul_f32 v[96:97], v[96:97], v[106:107] op_sel_hi:[1,0]
	s_cbranch_vccnz .LBB0_897
	s_load_dwordx2 s[4:5], s[0:1], 0x148
	s_waitcnt lgkmcnt(0)
	v_lshl_add_u64 v[196:197], s[4:5], 0, v[120:121]
	v_lshl_add_u64 v[196:197], v[196:197], 0, v[160:161]
	v_mov_b32_e32 v196, v250
	v_mov_b32_e32 v197, v251
	s_waitcnt vmcnt(0)
	v_pk_mul_f32 v[198:199], v[96:97], v[196:197] op_sel_hi:[0,1]
	v_pk_mul_f32 v[200:201], v[96:97], v[196:197] op_sel:[1,1] op_sel_hi:[1,0]
	v_pk_fma_f32 v[96:97], v[96:97], v[196:197], v[198:199] op_sel:[1,1,0] op_sel_hi:[1,0,1] neg_lo:[0,0,1] neg_hi:[0,0,1]
	s_nop 0
	v_add_f32_e32 v96, v200, v198
.LBB0_897:
	v_add_u32_e32 v106, 19, v204
	v_min_i32_e32 v198, 0x7fff, v106
	v_ashrrev_i32_e32 v199, 31, v198
	v_lshl_add_u64 v[196:197], v[198:199], 2, s[18:19]
	v_mov_b32_e32 v122, v245
	v_mov_b32_e32 v106, v123
	v_cvt_pk_bf16_f32 v97, v97, s0
	v_cvt_pk_bf16_f32 v96, v96, s0
	ds_write_b16 v217, v97 offset:2592
	ds_write_b16 v217, v96 offset:2656
	s_and_b64 vcc, exec, s[2:3]
	s_waitcnt vmcnt(0)
	v_fmamk_f32 v122, v122, 0x3b800000, v216
	v_mul_f32_e32 v123, 0x4b800000, v122
	v_cmp_gt_f32_e64 s[4:5], s38, v122
	s_nop 1
	v_cndmask_b32_e64 v122, v122, v123, s[4:5]
	v_rsq_f32_e32 v122, v122
	s_nop 0
	v_mul_f32_e32 v96, 0x45800000, v122
	v_cndmask_b32_e64 v96, v122, v96, s[4:5]
	v_mul_f32_e32 v96, 0x3dd53b94, v96
	v_pk_mul_f32 v[96:97], v[106:107], v[96:97] op_sel_hi:[1,0]
	v_lshlrev_b64 v[106:107], 8, v[198:199]
	s_cbranch_vccnz .LBB0_899
	s_load_dwordx2 s[4:5], s[0:1], 0x148
	s_waitcnt lgkmcnt(0)
	v_lshl_add_u64 v[122:123], s[4:5], 0, v[106:107]
	v_lshl_add_u64 v[122:123], v[122:123], 0, v[160:161]
	v_mov_b32_e32 v122, v252
	v_mov_b32_e32 v123, v253
	s_waitcnt vmcnt(0)
	v_pk_mul_f32 v[198:199], v[96:97], v[122:123] op_sel_hi:[0,1]
	v_pk_mul_f32 v[200:201], v[96:97], v[122:123] op_sel:[1,1] op_sel_hi:[1,0]
	v_pk_fma_f32 v[96:97], v[96:97], v[122:123], v[198:199] op_sel:[1,1,0] op_sel_hi:[1,0,1] neg_lo:[0,0,1] neg_hi:[0,0,1]
	s_nop 0
	v_add_f32_e32 v96, v200, v198
.LBB0_899:
	v_add_u32_e32 v122, 24, v204
	v_min_i32_e32 v122, 0x7fff, v122
	v_ashrrev_i32_e32 v123, 31, v122
	v_lshl_add_u64 v[198:199], v[122:123], 2, s[18:19]
	global_load_dword v242, v[198:199], off
	global_load_dword v243, v[198:199], off offset:4
	global_load_dword v244, v[198:199], off offset:8
	global_load_dword v245, v[198:199], off offset:12
	v_cvt_pk_bf16_f32 v201, v97, s0
	v_mov_b32_e32 v97, v108
	v_cvt_pk_bf16_f32 v202, v96, s0
	v_mov_b32_e32 v96, v124
	s_and_b64 vcc, exec, s[2:3]
	v_lshlrev_b64 v[122:123], 8, v[122:123]
	ds_write_b16 v217, v201 offset:2736
	ds_write_b16 v217, v202 offset:2800
	s_waitcnt vmcnt(0)
	v_mov_b32_e32 v200, v242
	v_fmamk_f32 v108, v200, 0x3b800000, v216
	v_mul_f32_e32 v124, 0x4b800000, v108
	v_cmp_gt_f32_e64 s[4:5], s38, v108
	s_nop 1
	v_cndmask_b32_e64 v108, v108, v124, s[4:5]
	v_rsq_f32_e32 v108, v108
	s_nop 0
	v_mul_f32_e32 v124, 0x45800000, v108
	v_cndmask_b32_e64 v108, v108, v124, s[4:5]
	v_mul_f32_e32 v108, 0x3dd53b94, v108
	v_pk_mul_f32 v[96:97], v[96:97], v[108:109] op_sel_hi:[1,0]
	s_cbranch_vccnz .LBB0_901
	s_load_dwordx2 s[4:5], s[0:1], 0x148
	s_waitcnt lgkmcnt(0)
	v_lshl_add_u64 v[200:201], s[4:5], 0, v[122:123]
	v_lshl_add_u64 v[200:201], v[200:201], 0, v[160:161]
	global_load_dwordx2 v[246:247], v[200:201], off
	global_load_dwordx2 v[248:249], v[200:201], off offset:256
	global_load_dwordx2 v[250:251], v[200:201], off offset:512
	global_load_dwordx2 v[252:253], v[200:201], off offset:768
	s_waitcnt vmcnt(0)
	v_mov_b32_e32 v200, v246
	v_mov_b32_e32 v201, v247
	v_pk_mul_f32 v[202:203], v[96:97], v[200:201] op_sel_hi:[0,1]
	v_pk_mul_f32 v[222:223], v[96:97], v[200:201] op_sel:[1,1] op_sel_hi:[1,0]
	v_pk_fma_f32 v[96:97], v[96:97], v[200:201], v[202:203] op_sel:[1,1,0] op_sel_hi:[1,0,1] neg_lo:[0,0,1] neg_hi:[0,0,1]
	s_nop 0
	v_add_f32_e32 v96, v222, v202
.LBB0_901:
	v_add_u32_e32 v108, 25, v204
	v_min_i32_e32 v202, 0x7fff, v108
	v_ashrrev_i32_e32 v203, 31, v202
	v_lshl_add_u64 v[200:201], v[202:203], 2, s[18:19]
	v_mov_b32_e32 v124, v243
	v_mov_b32_e32 v108, v125
	v_cvt_pk_bf16_f32 v97, v97, s0
	v_cvt_pk_bf16_f32 v96, v96, s0
	ds_write_b16 v217, v97 offset:3456
	ds_write_b16 v217, v96 offset:3520
	s_and_b64 vcc, exec, s[2:3]
	s_waitcnt vmcnt(0)
	v_fmamk_f32 v124, v124, 0x3b800000, v216
	v_mul_f32_e32 v125, 0x4b800000, v124
	v_cmp_gt_f32_e64 s[4:5], s38, v124
	s_nop 1
	v_cndmask_b32_e64 v124, v124, v125, s[4:5]
	v_rsq_f32_e32 v124, v124
	s_nop 0
	v_mul_f32_e32 v96, 0x45800000, v124
	v_cndmask_b32_e64 v96, v124, v96, s[4:5]
	v_mul_f32_e32 v96, 0x3dd53b94, v96
	v_pk_mul_f32 v[96:97], v[108:109], v[96:97] op_sel_hi:[1,0]
	v_lshlrev_b64 v[108:109], 8, v[202:203]
	s_cbranch_vccnz .LBB0_903
	s_load_dwordx2 s[4:5], s[0:1], 0x148
	s_waitcnt lgkmcnt(0)
	v_lshl_add_u64 v[124:125], s[4:5], 0, v[108:109]
	v_lshl_add_u64 v[124:125], v[124:125], 0, v[160:161]
	v_mov_b32_e32 v124, v248
	v_mov_b32_e32 v125, v249
	s_waitcnt vmcnt(0)
	v_pk_mul_f32 v[202:203], v[96:97], v[124:125] op_sel_hi:[0,1]
	v_pk_mul_f32 v[222:223], v[96:97], v[124:125] op_sel:[1,1] op_sel_hi:[1,0]
	v_pk_fma_f32 v[96:97], v[96:97], v[124:125], v[202:203] op_sel:[1,1,0] op_sel_hi:[1,0,1] neg_lo:[0,0,1] neg_hi:[0,0,1]
	s_nop 0
	v_add_f32_e32 v96, v222, v202
.LBB0_903:
	v_add_u32_e32 v124, 26, v204
	v_min_i32_e32 v124, 0x7fff, v124
	v_ashrrev_i32_e32 v125, 31, v124
	v_lshl_add_u64 v[202:203], v[124:125], 2, s[18:19]
	v_mov_b32_e32 v205, v244
	v_cvt_pk_bf16_f32 v221, v97, s0
	v_mov_b32_e32 v97, v110
	v_cvt_pk_bf16_f32 v222, v96, s0
	v_mov_b32_e32 v96, v126
	s_and_b64 vcc, exec, s[2:3]
	v_lshlrev_b64 v[124:125], 8, v[124:125]
	ds_write_b16 v217, v221 offset:3600
	ds_write_b16 v217, v222 offset:3664
	s_waitcnt vmcnt(0)
	v_fmamk_f32 v110, v205, 0x3b800000, v216
	v_mul_f32_e32 v126, 0x4b800000, v110
	v_cmp_gt_f32_e64 s[4:5], s38, v110
	s_nop 1
	v_cndmask_b32_e64 v110, v110, v126, s[4:5]
	v_rsq_f32_e32 v110, v110
	s_nop 0
	v_mul_f32_e32 v126, 0x45800000, v110
	v_cndmask_b32_e64 v110, v110, v126, s[4:5]
	v_mul_f32_e32 v110, 0x3dd53b94, v110
	v_pk_mul_f32 v[96:97], v[96:97], v[110:111] op_sel_hi:[1,0]
	s_cbranch_vccnz .LBB0_905
	s_load_dwordx2 s[4:5], s[0:1], 0x148
	s_waitcnt lgkmcnt(0)
	v_lshl_add_u64 v[222:223], s[4:5], 0, v[124:125]
	v_lshl_add_u64 v[222:223], v[222:223], 0, v[160:161]
	v_mov_b32_e32 v222, v250
	v_mov_b32_e32 v223, v251
	s_waitcnt vmcnt(0)
	v_pk_mul_f32 v[224:225], v[96:97], v[222:223] op_sel_hi:[0,1]
	v_pk_mul_f32 v[226:227], v[96:97], v[222:223] op_sel:[1,1] op_sel_hi:[1,0]
	v_pk_fma_f32 v[96:97], v[96:97], v[222:223], v[224:225] op_sel:[1,1,0] op_sel_hi:[1,0,1] neg_lo:[0,0,1] neg_hi:[0,0,1]
	s_nop 0
	v_add_f32_e32 v96, v226, v224
.LBB0_905:
	v_add_u32_e32 v110, 27, v204
	v_min_i32_e32 v222, 0x7fff, v110
	v_ashrrev_i32_e32 v223, 31, v222
	v_lshl_add_u64 v[204:205], v[222:223], 2, s[18:19]
	v_mov_b32_e32 v126, v245
	v_mov_b32_e32 v110, v127
	v_cvt_pk_bf16_f32 v97, v97, s0
	v_cvt_pk_bf16_f32 v96, v96, s0
	ds_write_b16 v217, v97 offset:3744
	ds_write_b16 v217, v96 offset:3808
	s_and_b64 vcc, exec, s[2:3]
	s_waitcnt vmcnt(0)
	v_fmamk_f32 v126, v126, 0x3b800000, v216
	v_mul_f32_e32 v127, 0x4b800000, v126
	v_cmp_gt_f32_e64 s[4:5], s38, v126
	s_nop 1
	v_cndmask_b32_e64 v126, v126, v127, s[4:5]
	v_rsq_f32_e32 v126, v126
	s_nop 0
	v_mul_f32_e32 v96, 0x45800000, v126
	v_cndmask_b32_e64 v96, v126, v96, s[4:5]
	v_mul_f32_e32 v96, 0x3dd53b94, v96
	v_pk_mul_f32 v[96:97], v[110:111], v[96:97] op_sel_hi:[1,0]
	v_lshlrev_b64 v[110:111], 8, v[222:223]
	s_cbranch_vccnz .LBB0_907
	s_load_dwordx2 s[4:5], s[0:1], 0x148
	s_waitcnt lgkmcnt(0)
	v_lshl_add_u64 v[126:127], s[4:5], 0, v[110:111]
	v_lshl_add_u64 v[126:127], v[126:127], 0, v[160:161]
	v_mov_b32_e32 v126, v252
	v_mov_b32_e32 v127, v253
	s_waitcnt vmcnt(0)
	v_pk_mul_f32 v[222:223], v[96:97], v[126:127] op_sel_hi:[0,1]
	v_pk_mul_f32 v[224:225], v[96:97], v[126:127] op_sel:[1,1] op_sel_hi:[1,0]
	v_pk_fma_f32 v[96:97], v[96:97], v[126:127], v[222:223] op_sel:[1,1,0] op_sel_hi:[1,0,1] neg_lo:[0,0,1] neg_hi:[0,0,1]
	s_nop 0
	v_add_f32_e32 v96, v224, v222

.LBB0_915:
	s_or_b64 exec, exec, s[4:5]
	global_load_dword v242, v[172:173], off
	global_load_dword v243, v[172:173], off offset:4
	global_load_dword v244, v[172:173], off offset:8
	global_load_dword v245, v[172:173], off offset:12
	v_mov_b32_e32 v126, v80
	s_or_b32 s26, s24, 1
	s_mul_hi_i32 s54, s26, 0x55555556
	s_lshr_b32 s4, s54, 31
	s_add_i32 s54, s54, s4
	s_mul_i32 s4, s54, 3
	s_sub_i32 s4, s26, s4
	s_cmp_eq_u32 s4, 2
	v_mov_b32_e32 v127, v64
	s_cselect_b64 s[24:25], -1, 0
	s_cmp_lg_u32 s4, 2
	s_waitcnt vmcnt(0)
	v_mov_b32_e32 v97, v242
	v_fmamk_f32 v80, v97, 0x3b800000, v216
	v_mul_f32_e32 v97, 0x4b800000, v80
	v_cmp_gt_f32_e32 vcc, s38, v80
	s_nop 1
	v_cndmask_b32_e32 v80, v80, v97, vcc
	v_rsq_f32_e32 v80, v80
	s_nop 0
	v_mul_f32_e32 v97, 0x45800000, v80
	v_cndmask_b32_e32 v80, v80, v97, vcc
	v_mul_f32_e32 v80, 0x3dd53b94, v80
	v_pk_mul_f32 v[126:127], v[126:127], v[80:81] op_sel_hi:[1,0]
	s_cbranch_scc1 .LBB0_917
	s_load_dwordx2 s[4:5], s[0:1], 0x148
	s_waitcnt lgkmcnt(0)
	v_lshl_add_u64 v[170:171], s[4:5], 0, v[170:171]
	v_lshl_add_u64 v[170:171], v[170:171], 0, v[160:161]
	global_load_dwordx2 v[246:247], v[170:171], off
	global_load_dwordx2 v[248:249], v[170:171], off offset:256
	global_load_dwordx2 v[250:251], v[170:171], off offset:512
	global_load_dwordx2 v[252:253], v[170:171], off offset:768
	s_waitcnt vmcnt(0)
	v_mov_b32_e32 v170, v246
	v_mov_b32_e32 v171, v247
	v_pk_mul_f32 v[172:173], v[126:127], v[170:171] op_sel_hi:[0,1]
	v_pk_mul_f32 v[230:231], v[126:127], v[170:171] op_sel:[1,1] op_sel_hi:[1,0]
	v_pk_fma_f32 v[126:127], v[126:127], v[170:171], v[172:173] op_sel:[1,1,0] op_sel_hi:[1,0,1] neg_lo:[0,0,1] neg_hi:[0,0,1]
	s_nop 0
	v_add_f32_e32 v126, v230, v172
.LBB0_917:
	v_mov_b32_e32 v80, v243
	v_cvt_pk_bf16_f32 v97, v127, s0
	v_mov_b32_e32 v64, v81
	v_cndmask_b32_e64 v81, 0, 1, s[24:25]
	v_cmp_ne_u32_e64 s[4:5], 1, v81
	v_cvt_pk_bf16_f32 v126, v126, s0
	ds_write_b16 v217, v97
	ds_write_b16 v217, v126 offset:64
	s_waitcnt vmcnt(0)
	v_fmamk_f32 v80, v80, 0x3b800000, v216
	v_mul_f32_e32 v127, 0x4b800000, v80
	v_cmp_gt_f32_e32 vcc, s38, v80
	s_nop 1
	v_cndmask_b32_e32 v80, v80, v127, vcc
	v_rsq_f32_e32 v80, v80
	s_nop 0
	v_mul_f32_e32 v81, 0x45800000, v80
	v_cndmask_b32_e32 v80, v80, v81, vcc
	v_mul_f32_e32 v80, 0x3dd53b94, v80
	s_andn2_b64 vcc, exec, s[24:25]
	v_pk_mul_f32 v[64:65], v[64:65], v[80:81] op_sel_hi:[1,0]
	s_cbranch_vccnz .LBB0_919
	s_load_dwordx2 s[24:25], s[0:1], 0x148
	s_waitcnt lgkmcnt(0)
	v_lshl_add_u64 v[80:81], s[24:25], 0, v[112:113]
	v_lshl_add_u64 v[80:81], v[80:81], 0, v[160:161]
	v_mov_b32_e32 v80, v248
	v_mov_b32_e32 v81, v249
	s_waitcnt vmcnt(0)
	v_pk_mul_f32 v[112:113], v[64:65], v[80:81] op_sel_hi:[0,1]
	v_pk_mul_f32 v[126:127], v[64:65], v[80:81] op_sel:[1,1] op_sel_hi:[1,0]
	v_pk_fma_f32 v[64:65], v[64:65], v[80:81], v[112:113] op_sel:[1,1,0] op_sel_hi:[1,0,1] neg_lo:[0,0,1] neg_hi:[0,0,1]
	s_nop 0
	v_add_f32_e32 v64, v126, v112
.LBB0_919:
	v_mov_b32_e32 v80, v244
	v_cvt_pk_bf16_f32 v81, v65, s0
	v_cvt_pk_bf16_f32 v97, v64, s0
	v_mov_b32_e32 v64, v82
	ds_write_b16 v217, v81 offset:144
	ds_write_b16 v217, v97 offset:208
	s_waitcnt vmcnt(0)
	v_fmamk_f32 v65, v80, 0x3b800000, v216
	v_mul_f32_e32 v80, 0x4b800000, v65
	v_cmp_gt_f32_e32 vcc, s38, v65
	s_nop 1
	v_cndmask_b32_e32 v65, v65, v80, vcc
	v_rsq_f32_e32 v80, v65
	v_mov_b32_e32 v65, v66
	v_mul_f32_e32 v66, 0x45800000, v80
	v_cndmask_b32_e32 v66, v80, v66, vcc
	v_mul_f32_e32 v66, 0x3dd53b94, v66
	s_and_b64 vcc, exec, s[4:5]
	v_pk_mul_f32 v[64:65], v[64:65], v[66:67] op_sel_hi:[1,0]
	s_cbranch_vccnz .LBB0_921
	s_load_dwordx2 s[24:25], s[0:1], 0x148
	s_waitcnt lgkmcnt(0)
	v_lshl_add_u64 v[80:81], s[24:25], 0, v[176:177]
	v_lshl_add_u64 v[80:81], v[80:81], 0, v[160:161]
	v_mov_b32_e32 v80, v250
	v_mov_b32_e32 v81, v251
	s_waitcnt vmcnt(0)
	v_pk_mul_f32 v[112:113], v[64:65], v[80:81] op_sel_hi:[0,1]
	v_pk_mul_f32 v[126:127], v[64:65], v[80:81] op_sel:[1,1] op_sel_hi:[1,0]
	v_pk_fma_f32 v[64:65], v[64:65], v[80:81], v[112:113] op_sel:[1,1,0] op_sel_hi:[1,0,1] neg_lo:[0,0,1] neg_hi:[0,0,1]
	s_nop 0
	v_add_f32_e32 v64, v126, v112
.LBB0_921:
	v_mov_b32_e32 v66, v245
	v_cvt_pk_bf16_f32 v65, v65, s0
	v_cvt_pk_bf16_f32 v64, v64, s0
	ds_write_b16 v217, v65 offset:288
	ds_write_b16 v217, v64 offset:352
	s_waitcnt vmcnt(0)
	v_fmamk_f32 v66, v66, 0x3b800000, v216
	v_mul_f32_e32 v80, 0x4b800000, v66
	v_cmp_gt_f32_e32 vcc, s38, v66
	s_nop 1
	v_cndmask_b32_e32 v66, v66, v80, vcc
	v_rsq_f32_e32 v80, v66
	v_mov_b32_e32 v66, v83
	v_mul_f32_e32 v64, 0x45800000, v80
	v_cndmask_b32_e32 v64, v80, v64, vcc
	v_mul_f32_e32 v64, 0x3dd53b94, v64
	s_and_b64 vcc, exec, s[4:5]
	v_pk_mul_f32 v[64:65], v[66:67], v[64:65] op_sel_hi:[1,0]
	s_cbranch_vccnz .LBB0_923
	s_load_dwordx2 s[24:25], s[0:1], 0x148
	s_waitcnt lgkmcnt(0)
	v_lshl_add_u64 v[66:67], s[24:25], 0, v[98:99]
	v_lshl_add_u64 v[66:67], v[66:67], 0, v[160:161]
	v_mov_b32_e32 v66, v252
	v_mov_b32_e32 v67, v253
	s_waitcnt vmcnt(0)
	v_pk_mul_f32 v[80:81], v[64:65], v[66:67] op_sel_hi:[0,1]
	v_pk_mul_f32 v[82:83], v[64:65], v[66:67] op_sel:[1,1] op_sel_hi:[1,0]
	v_pk_fma_f32 v[64:65], v[64:65], v[66:67], v[80:81] op_sel:[1,1,0] op_sel_hi:[1,0,1] neg_lo:[0,0,1] neg_hi:[0,0,1]
	s_nop 0
	v_add_f32_e32 v64, v82, v80
.LBB0_923:
	global_load_dword v242, v[182:183], off
	global_load_dword v243, v[182:183], off offset:4
	global_load_dword v244, v[182:183], off offset:8
	global_load_dword v245, v[182:183], off offset:12
	v_cvt_pk_bf16_f32 v67, v65, s0
	v_cvt_pk_bf16_f32 v80, v64, s0
	ds_write_b16 v217, v67 offset:432
	ds_write_b16 v217, v80 offset:496
	v_mov_b32_e32 v64, v84
	s_waitcnt vmcnt(0)
	v_mov_b32_e32 v66, v242
	v_fmamk_f32 v65, v66, 0x3b800000, v216
	v_mul_f32_e32 v66, 0x4b800000, v65
	v_cmp_gt_f32_e32 vcc, s38, v65
	s_nop 1
	v_cndmask_b32_e32 v65, v65, v66, vcc
	v_rsq_f32_e32 v66, v65
	v_mov_b32_e32 v65, v68
	v_mul_f32_e32 v67, 0x45800000, v66
	v_cndmask_b32_e32 v66, v66, v67, vcc
	v_mul_f32_e32 v66, 0x3dd53b94, v66
	s_and_b64 vcc, exec, s[4:5]
	v_pk_mul_f32 v[64:65], v[64:65], v[66:67] op_sel_hi:[1,0]
	s_cbranch_vccnz .LBB0_925
	s_load_dwordx2 s[24:25], s[0:1], 0x148
	s_waitcnt lgkmcnt(0)
	v_lshl_add_u64 v[66:67], s[24:25], 0, v[114:115]
	v_lshl_add_u64 v[66:67], v[66:67], 0, v[160:161]
	global_load_dwordx2 v[246:247], v[66:67], off
	global_load_dwordx2 v[248:249], v[66:67], off offset:256
	global_load_dwordx2 v[250:251], v[66:67], off offset:512
	global_load_dwordx2 v[252:253], v[66:67], off offset:768
	s_waitcnt vmcnt(0)
	v_mov_b32_e32 v66, v246
	v_mov_b32_e32 v67, v247
	v_pk_mul_f32 v[80:81], v[64:65], v[66:67] op_sel_hi:[0,1]
	v_pk_mul_f32 v[82:83], v[64:65], v[66:67] op_sel:[1,1] op_sel_hi:[1,0]
	v_pk_fma_f32 v[64:65], v[64:65], v[66:67], v[80:81] op_sel:[1,1,0] op_sel_hi:[1,0,1] neg_lo:[0,0,1] neg_hi:[0,0,1]
	s_nop 0
	v_add_f32_e32 v64, v82, v80
.LBB0_925:
	v_mov_b32_e32 v66, v243
	v_cvt_pk_bf16_f32 v65, v65, s0
	v_cvt_pk_bf16_f32 v64, v64, s0
	ds_write_b16 v217, v65 offset:1152
	ds_write_b16 v217, v64 offset:1216
	v_mov_b32_e32 v68, v85
	s_waitcnt vmcnt(0)
	v_fmamk_f32 v66, v66, 0x3b800000, v216
	v_mul_f32_e32 v67, 0x4b800000, v66
	v_cmp_gt_f32_e32 vcc, s38, v66
	s_nop 1
	v_cndmask_b32_e32 v66, v66, v67, vcc
	v_rsq_f32_e32 v66, v66
	s_nop 0
	v_mul_f32_e32 v64, 0x45800000, v66
	v_cndmask_b32_e32 v64, v66, v64, vcc
	v_mul_f32_e32 v64, 0x3dd53b94, v64
	s_and_b64 vcc, exec, s[4:5]
	v_pk_mul_f32 v[64:65], v[68:69], v[64:65] op_sel_hi:[1,0]
	s_cbranch_vccnz .LBB0_927
	s_load_dwordx2 s[24:25], s[0:1], 0x148
	s_waitcnt lgkmcnt(0)
	v_lshl_add_u64 v[66:67], s[24:25], 0, v[100:101]
	v_lshl_add_u64 v[66:67], v[66:67], 0, v[160:161]
	v_mov_b32_e32 v66, v248
	v_mov_b32_e32 v67, v249
	s_waitcnt vmcnt(0)
	v_pk_mul_f32 v[68:69], v[64:65], v[66:67] op_sel_hi:[0,1]
	v_pk_mul_f32 v[80:81], v[64:65], v[66:67] op_sel:[1,1] op_sel_hi:[1,0]
	v_pk_fma_f32 v[64:65], v[64:65], v[66:67], v[68:69] op_sel:[1,1,0] op_sel_hi:[1,0,1] neg_lo:[0,0,1] neg_hi:[0,0,1]
	s_nop 0
	v_add_f32_e32 v64, v80, v68
.LBB0_927:
	v_mov_b32_e32 v66, v244
	v_cvt_pk_bf16_f32 v67, v65, s0
	v_cvt_pk_bf16_f32 v68, v64, s0
	ds_write_b16 v217, v67 offset:1296
	ds_write_b16 v217, v68 offset:1360
	v_mov_b32_e32 v64, v86
	s_waitcnt vmcnt(0)
	v_fmamk_f32 v65, v66, 0x3b800000, v216
	v_mul_f32_e32 v66, 0x4b800000, v65
	v_cmp_gt_f32_e32 vcc, s38, v65
	s_nop 1
	v_cndmask_b32_e32 v65, v65, v66, vcc
	v_rsq_f32_e32 v66, v65
	v_mov_b32_e32 v65, v70
	v_mul_f32_e32 v67, 0x45800000, v66
	v_cndmask_b32_e32 v66, v66, v67, vcc
	v_mul_f32_e32 v66, 0x3dd53b94, v66
	s_and_b64 vcc, exec, s[4:5]
	v_pk_mul_f32 v[64:65], v[64:65], v[66:67] op_sel_hi:[1,0]
	s_cbranch_vccnz .LBB0_929
	s_load_dwordx2 s[24:25], s[0:1], 0x148
	s_waitcnt lgkmcnt(0)
	v_lshl_add_u64 v[66:67], s[24:25], 0, v[116:117]
	v_lshl_add_u64 v[66:67], v[66:67], 0, v[160:161]
	v_mov_b32_e32 v66, v250
	v_mov_b32_e32 v67, v251
	s_waitcnt vmcnt(0)
	v_pk_mul_f32 v[68:69], v[64:65], v[66:67] op_sel_hi:[0,1]
	v_pk_mul_f32 v[80:81], v[64:65], v[66:67] op_sel:[1,1] op_sel_hi:[1,0]
	v_pk_fma_f32 v[64:65], v[64:65], v[66:67], v[68:69] op_sel:[1,1,0] op_sel_hi:[1,0,1] neg_lo:[0,0,1] neg_hi:[0,0,1]
	s_nop 0
	v_add_f32_e32 v64, v80, v68
.LBB0_929:
	v_mov_b32_e32 v66, v245
	v_cvt_pk_bf16_f32 v65, v65, s0
	v_cvt_pk_bf16_f32 v64, v64, s0
	ds_write_b16 v217, v65 offset:1440
	ds_write_b16 v217, v64 offset:1504
	v_mov_b32_e32 v70, v87
	s_waitcnt vmcnt(0)
	v_fmamk_f32 v66, v66, 0x3b800000, v216
	v_mul_f32_e32 v67, 0x4b800000, v66
	v_cmp_gt_f32_e32 vcc, s38, v66
	s_nop 1
	v_cndmask_b32_e32 v66, v66, v67, vcc
	v_rsq_f32_e32 v66, v66
	s_nop 0
	v_mul_f32_e32 v64, 0x45800000, v66
	v_cndmask_b32_e32 v64, v66, v64, vcc
	v_mul_f32_e32 v64, 0x3dd53b94, v64
	s_and_b64 vcc, exec, s[4:5]
	v_pk_mul_f32 v[64:65], v[70:71], v[64:65] op_sel_hi:[1,0]
	s_cbranch_vccnz .LBB0_931
	s_load_dwordx2 s[24:25], s[0:1], 0x148
	s_waitcnt lgkmcnt(0)
	v_lshl_add_u64 v[66:67], s[24:25], 0, v[102:103]
	v_lshl_add_u64 v[66:67], v[66:67], 0, v[160:161]
	v_mov_b32_e32 v66, v252
	v_mov_b32_e32 v67, v253
	s_waitcnt vmcnt(0)
	v_pk_mul_f32 v[68:69], v[64:65], v[66:67] op_sel_hi:[0,1]
	v_pk_mul_f32 v[70:71], v[64:65], v[66:67] op_sel:[1,1] op_sel_hi:[1,0]
	v_pk_fma_f32 v[64:65], v[64:65], v[66:67], v[68:69] op_sel:[1,1,0] op_sel_hi:[1,0,1] neg_lo:[0,0,1] neg_hi:[0,0,1]
	s_nop 0
	v_add_f32_e32 v64, v70, v68
.LBB0_931:
	global_load_dword v242, v[190:191], off
	global_load_dword v243, v[190:191], off offset:4
	global_load_dword v244, v[190:191], off offset:8
	global_load_dword v245, v[190:191], off offset:12
	v_cvt_pk_bf16_f32 v67, v65, s0
	v_cvt_pk_bf16_f32 v68, v64, s0
	ds_write_b16 v217, v67 offset:1584
	ds_write_b16 v217, v68 offset:1648
	v_mov_b32_e32 v64, v88
	s_waitcnt vmcnt(0)
	v_mov_b32_e32 v66, v242
	v_fmamk_f32 v65, v66, 0x3b800000, v216
	v_mul_f32_e32 v66, 0x4b800000, v65
	v_cmp_gt_f32_e32 vcc, s38, v65
	s_nop 1
	v_cndmask_b32_e32 v65, v65, v66, vcc
	v_rsq_f32_e32 v66, v65
	v_mov_b32_e32 v65, v72
	v_mul_f32_e32 v67, 0x45800000, v66
	v_cndmask_b32_e32 v66, v66, v67, vcc
	v_mul_f32_e32 v66, 0x3dd53b94, v66
	s_and_b64 vcc, exec, s[4:5]
	v_pk_mul_f32 v[64:65], v[64:65], v[66:67] op_sel_hi:[1,0]
	s_cbranch_vccnz .LBB0_933
	s_load_dwordx2 s[24:25], s[0:1], 0x148
	s_waitcnt lgkmcnt(0)
	v_lshl_add_u64 v[66:67], s[24:25], 0, v[118:119]
	v_lshl_add_u64 v[66:67], v[66:67], 0, v[160:161]
	global_load_dwordx2 v[246:247], v[66:67], off
	global_load_dwordx2 v[248:249], v[66:67], off offset:256
	global_load_dwordx2 v[250:251], v[66:67], off offset:512
	global_load_dwordx2 v[252:253], v[66:67], off offset:768
	s_waitcnt vmcnt(0)
	v_mov_b32_e32 v66, v246
	v_mov_b32_e32 v67, v247
	v_pk_mul_f32 v[68:69], v[64:65], v[66:67] op_sel_hi:[0,1]
	v_pk_mul_f32 v[70:71], v[64:65], v[66:67] op_sel:[1,1] op_sel_hi:[1,0]
	v_pk_fma_f32 v[64:65], v[64:65], v[66:67], v[68:69] op_sel:[1,1,0] op_sel_hi:[1,0,1] neg_lo:[0,0,1] neg_hi:[0,0,1]
	s_nop 0
	v_add_f32_e32 v64, v70, v68
.LBB0_933:
	v_mov_b32_e32 v66, v243
	v_cvt_pk_bf16_f32 v65, v65, s0
	v_cvt_pk_bf16_f32 v64, v64, s0
	ds_write_b16 v217, v65 offset:2304
	ds_write_b16 v217, v64 offset:2368
	v_mov_b32_e32 v72, v89
	s_waitcnt vmcnt(0)
	v_fmamk_f32 v66, v66, 0x3b800000, v216
	v_mul_f32_e32 v67, 0x4b800000, v66
	v_cmp_gt_f32_e32 vcc, s38, v66
	s_nop 1
	v_cndmask_b32_e32 v66, v66, v67, vcc
	v_rsq_f32_e32 v66, v66
	s_nop 0
	v_mul_f32_e32 v64, 0x45800000, v66
	v_cndmask_b32_e32 v64, v66, v64, vcc
	v_mul_f32_e32 v64, 0x3dd53b94, v64
	s_and_b64 vcc, exec, s[4:5]
	v_pk_mul_f32 v[64:65], v[72:73], v[64:65] op_sel_hi:[1,0]
	s_cbranch_vccnz .LBB0_935
	s_load_dwordx2 s[24:25], s[0:1], 0x148
	s_waitcnt lgkmcnt(0)
	v_lshl_add_u64 v[66:67], s[24:25], 0, v[104:105]
	v_lshl_add_u64 v[66:67], v[66:67], 0, v[160:161]
	v_mov_b32_e32 v66, v248
	v_mov_b32_e32 v67, v249
	s_waitcnt vmcnt(0)
	v_pk_mul_f32 v[68:69], v[64:65], v[66:67] op_sel_hi:[0,1]
	v_pk_mul_f32 v[70:71], v[64:65], v[66:67] op_sel:[1,1] op_sel_hi:[1,0]
	v_pk_fma_f32 v[64:65], v[64:65], v[66:67], v[68:69] op_sel:[1,1,0] op_sel_hi:[1,0,1] neg_lo:[0,0,1] neg_hi:[0,0,1]
	s_nop 0
	v_add_f32_e32 v64, v70, v68
.LBB0_935:
	v_mov_b32_e32 v66, v244
	v_cvt_pk_bf16_f32 v67, v65, s0
	v_cvt_pk_bf16_f32 v68, v64, s0
	ds_write_b16 v217, v67 offset:2448
	ds_write_b16 v217, v68 offset:2512
	v_mov_b32_e32 v64, v90
	s_waitcnt vmcnt(0)
	v_fmamk_f32 v65, v66, 0x3b800000, v216
	v_mul_f32_e32 v66, 0x4b800000, v65
	v_cmp_gt_f32_e32 vcc, s38, v65
	s_nop 1
	v_cndmask_b32_e32 v65, v65, v66, vcc
	v_rsq_f32_e32 v66, v65
	v_mov_b32_e32 v65, v74
	v_mul_f32_e32 v67, 0x45800000, v66
	v_cndmask_b32_e32 v66, v66, v67, vcc
	v_mul_f32_e32 v66, 0x3dd53b94, v66
	s_and_b64 vcc, exec, s[4:5]
	v_pk_mul_f32 v[64:65], v[64:65], v[66:67] op_sel_hi:[1,0]
	s_cbranch_vccnz .LBB0_937
	s_load_dwordx2 s[24:25], s[0:1], 0x148
	s_waitcnt lgkmcnt(0)
	v_lshl_add_u64 v[66:67], s[24:25], 0, v[120:121]
	v_lshl_add_u64 v[66:67], v[66:67], 0, v[160:161]
	v_mov_b32_e32 v66, v250
	v_mov_b32_e32 v67, v251
	s_waitcnt vmcnt(0)
	v_pk_mul_f32 v[68:69], v[64:65], v[66:67] op_sel_hi:[0,1]
	v_pk_mul_f32 v[70:71], v[64:65], v[66:67] op_sel:[1,1] op_sel_hi:[1,0]
	v_pk_fma_f32 v[64:65], v[64:65], v[66:67], v[68:69] op_sel:[1,1,0] op_sel_hi:[1,0,1] neg_lo:[0,0,1] neg_hi:[0,0,1]
	s_nop 0
	v_add_f32_e32 v64, v70, v68
.LBB0_937:
	v_mov_b32_e32 v66, v245
	v_cvt_pk_bf16_f32 v65, v65, s0
	v_cvt_pk_bf16_f32 v64, v64, s0
	ds_write_b16 v217, v65 offset:2592
	ds_write_b16 v217, v64 offset:2656
	v_mov_b32_e32 v74, v91
	s_waitcnt vmcnt(0)
	v_fmamk_f32 v66, v66, 0x3b800000, v216
	v_mul_f32_e32 v67, 0x4b800000, v66
	v_cmp_gt_f32_e32 vcc, s38, v66
	s_nop 1
	v_cndmask_b32_e32 v66, v66, v67, vcc
	v_rsq_f32_e32 v66, v66
	s_nop 0
	v_mul_f32_e32 v64, 0x45800000, v66
	v_cndmask_b32_e32 v64, v66, v64, vcc
	v_mul_f32_e32 v64, 0x3dd53b94, v64
	s_and_b64 vcc, exec, s[4:5]
	v_pk_mul_f32 v[64:65], v[74:75], v[64:65] op_sel_hi:[1,0]
	s_cbranch_vccnz .LBB0_939
	s_load_dwordx2 s[24:25], s[0:1], 0x148
	s_waitcnt lgkmcnt(0)
	v_lshl_add_u64 v[66:67], s[24:25], 0, v[106:107]
	v_lshl_add_u64 v[66:67], v[66:67], 0, v[160:161]
	v_mov_b32_e32 v66, v252
	v_mov_b32_e32 v67, v253
	s_waitcnt vmcnt(0)
	v_pk_mul_f32 v[68:69], v[64:65], v[66:67] op_sel_hi:[0,1]
	v_pk_mul_f32 v[70:71], v[64:65], v[66:67] op_sel:[1,1] op_sel_hi:[1,0]
	v_pk_fma_f32 v[64:65], v[64:65], v[66:67], v[68:69] op_sel:[1,1,0] op_sel_hi:[1,0,1] neg_lo:[0,0,1] neg_hi:[0,0,1]
	s_nop 0
	v_add_f32_e32 v64, v70, v68
.LBB0_939:
	global_load_dword v242, v[198:199], off
	global_load_dword v243, v[198:199], off offset:4
	global_load_dword v244, v[198:199], off offset:8
	global_load_dword v245, v[198:199], off offset:12
	v_cvt_pk_bf16_f32 v67, v65, s0
	v_cvt_pk_bf16_f32 v68, v64, s0
	ds_write_b16 v217, v67 offset:2736
	ds_write_b16 v217, v68 offset:2800
	v_mov_b32_e32 v64, v92
	s_waitcnt vmcnt(0)
	v_mov_b32_e32 v66, v242
	v_fmamk_f32 v65, v66, 0x3b800000, v216
	v_mul_f32_e32 v66, 0x4b800000, v65
	v_cmp_gt_f32_e32 vcc, s38, v65
	s_nop 1
	v_cndmask_b32_e32 v65, v65, v66, vcc
	v_rsq_f32_e32 v66, v65
	v_mov_b32_e32 v65, v76
	v_mul_f32_e32 v67, 0x45800000, v66
	v_cndmask_b32_e32 v66, v66, v67, vcc
	v_mul_f32_e32 v66, 0x3dd53b94, v66
	s_and_b64 vcc, exec, s[4:5]
	v_pk_mul_f32 v[64:65], v[64:65], v[66:67] op_sel_hi:[1,0]
	s_cbranch_vccnz .LBB0_941
	s_load_dwordx2 s[24:25], s[0:1], 0x148
	s_waitcnt lgkmcnt(0)
	v_lshl_add_u64 v[66:67], s[24:25], 0, v[122:123]
	v_lshl_add_u64 v[66:67], v[66:67], 0, v[160:161]
	global_load_dwordx2 v[246:247], v[66:67], off
	global_load_dwordx2 v[248:249], v[66:67], off offset:256
	global_load_dwordx2 v[250:251], v[66:67], off offset:512
	global_load_dwordx2 v[252:253], v[66:67], off offset:768
	s_waitcnt vmcnt(0)
	v_mov_b32_e32 v66, v246
	v_mov_b32_e32 v67, v247
	v_pk_mul_f32 v[68:69], v[64:65], v[66:67] op_sel_hi:[0,1]
	v_pk_mul_f32 v[70:71], v[64:65], v[66:67] op_sel:[1,1] op_sel_hi:[1,0]
	v_pk_fma_f32 v[64:65], v[64:65], v[66:67], v[68:69] op_sel:[1,1,0] op_sel_hi:[1,0,1] neg_lo:[0,0,1] neg_hi:[0,0,1]
	s_nop 0
	v_add_f32_e32 v64, v70, v68
.LBB0_941:
	v_mov_b32_e32 v66, v243
	v_cvt_pk_bf16_f32 v65, v65, s0
	v_cvt_pk_bf16_f32 v64, v64, s0
	ds_write_b16 v217, v65 offset:3456
	ds_write_b16 v217, v64 offset:3520
	v_mov_b32_e32 v76, v93
	s_waitcnt vmcnt(0)
	v_fmamk_f32 v66, v66, 0x3b800000, v216
	v_mul_f32_e32 v67, 0x4b800000, v66
	v_cmp_gt_f32_e32 vcc, s38, v66
	s_nop 1
	v_cndmask_b32_e32 v66, v66, v67, vcc
	v_rsq_f32_e32 v66, v66
	s_nop 0
	v_mul_f32_e32 v64, 0x45800000, v66
	v_cndmask_b32_e32 v64, v66, v64, vcc
	v_mul_f32_e32 v64, 0x3dd53b94, v64
	s_and_b64 vcc, exec, s[4:5]
	v_pk_mul_f32 v[64:65], v[76:77], v[64:65] op_sel_hi:[1,0]
	s_cbranch_vccnz .LBB0_943
	s_load_dwordx2 s[24:25], s[0:1], 0x148
	s_waitcnt lgkmcnt(0)
	v_lshl_add_u64 v[66:67], s[24:25], 0, v[108:109]
	v_lshl_add_u64 v[66:67], v[66:67], 0, v[160:161]
	v_mov_b32_e32 v66, v248
	v_mov_b32_e32 v67, v249
	s_waitcnt vmcnt(0)
	v_pk_mul_f32 v[68:69], v[64:65], v[66:67] op_sel_hi:[0,1]
	v_pk_mul_f32 v[70:71], v[64:65], v[66:67] op_sel:[1,1] op_sel_hi:[1,0]
	v_pk_fma_f32 v[64:65], v[64:65], v[66:67], v[68:69] op_sel:[1,1,0] op_sel_hi:[1,0,1] neg_lo:[0,0,1] neg_hi:[0,0,1]
	s_nop 0
	v_add_f32_e32 v64, v70, v68
.LBB0_943:
	v_mov_b32_e32 v66, v244
	v_cvt_pk_bf16_f32 v67, v65, s0
	v_cvt_pk_bf16_f32 v68, v64, s0
	ds_write_b16 v217, v67 offset:3600
	ds_write_b16 v217, v68 offset:3664
	v_mov_b32_e32 v64, v94
	s_waitcnt vmcnt(0)
	v_fmamk_f32 v65, v66, 0x3b800000, v216
	v_mul_f32_e32 v66, 0x4b800000, v65
	v_cmp_gt_f32_e32 vcc, s38, v65
	s_nop 1
	v_cndmask_b32_e32 v65, v65, v66, vcc
	v_rsq_f32_e32 v66, v65
	v_mov_b32_e32 v65, v78
	v_mul_f32_e32 v67, 0x45800000, v66
	v_cndmask_b32_e32 v66, v66, v67, vcc
	v_mul_f32_e32 v66, 0x3dd53b94, v66
	s_and_b64 vcc, exec, s[4:5]
	v_pk_mul_f32 v[64:65], v[64:65], v[66:67] op_sel_hi:[1,0]
	s_cbranch_vccnz .LBB0_945
	s_load_dwordx2 s[24:25], s[0:1], 0x148
	s_waitcnt lgkmcnt(0)
	v_lshl_add_u64 v[66:67], s[24:25], 0, v[124:125]
	v_lshl_add_u64 v[66:67], v[66:67], 0, v[160:161]
	v_mov_b32_e32 v66, v250
	v_mov_b32_e32 v67, v251
	s_waitcnt vmcnt(0)
	v_pk_mul_f32 v[68:69], v[64:65], v[66:67] op_sel_hi:[0,1]
	v_pk_mul_f32 v[70:71], v[64:65], v[66:67] op_sel:[1,1] op_sel_hi:[1,0]
	v_pk_fma_f32 v[64:65], v[64:65], v[66:67], v[68:69] op_sel:[1,1,0] op_sel_hi:[1,0,1] neg_lo:[0,0,1] neg_hi:[0,0,1]
	s_nop 0
	v_add_f32_e32 v64, v70, v68
.LBB0_945:
	v_mov_b32_e32 v66, v245
	v_cvt_pk_bf16_f32 v65, v65, s0
	v_cvt_pk_bf16_f32 v64, v64, s0
	ds_write_b16 v217, v65 offset:3744
	ds_write_b16 v217, v64 offset:3808
	v_mov_b32_e32 v78, v95
	s_waitcnt vmcnt(0)
	v_fmamk_f32 v66, v66, 0x3b800000, v216
	v_mul_f32_e32 v67, 0x4b800000, v66
	v_cmp_gt_f32_e32 vcc, s38, v66
	s_nop 1
	v_cndmask_b32_e32 v66, v66, v67, vcc
	v_rsq_f32_e32 v66, v66
	s_nop 0
	v_mul_f32_e32 v64, 0x45800000, v66
	v_cndmask_b32_e32 v64, v66, v64, vcc
	v_mul_f32_e32 v64, 0x3dd53b94, v64
	s_and_b64 vcc, exec, s[4:5]
	v_pk_mul_f32 v[64:65], v[78:79], v[64:65] op_sel_hi:[1,0]
	s_cbranch_vccnz .LBB0_947
	s_load_dwordx2 s[24:25], s[0:1], 0x148
	s_waitcnt lgkmcnt(0)
	v_lshl_add_u64 v[66:67], s[24:25], 0, v[110:111]
	v_lshl_add_u64 v[66:67], v[66:67], 0, v[160:161]
	v_mov_b32_e32 v66, v252
	v_mov_b32_e32 v67, v253
	s_waitcnt vmcnt(0)
	v_pk_mul_f32 v[68:69], v[64:65], v[66:67] op_sel_hi:[0,1]
	v_pk_mul_f32 v[70:71], v[64:65], v[66:67] op_sel:[1,1] op_sel_hi:[1,0]
	v_pk_fma_f32 v[64:65], v[64:65], v[66:67], v[68:69] op_sel:[1,1,0] op_sel_hi:[1,0,1] neg_lo:[0,0,1] neg_hi:[0,0,1]
	s_nop 0
	v_add_f32_e32 v64, v70, v68

.LBB0_955:
	s_or_b64 exec, exec, s[6:7]
	s_or_b32 s8, s55, 32
	v_add_u32_e32 v97, s8, v220
	v_min_i32_e32 v64, 0x7fff, v97
	v_ashrrev_i32_e32 v65, 31, v64
	v_lshl_add_u64 v[66:67], v[64:65], 2, s[18:19]
	global_load_dword v242, v[66:67], off
	global_load_dword v243, v[66:67], off offset:4
	global_load_dword v244, v[66:67], off offset:8
	global_load_dword v245, v[66:67], off offset:12
	s_and_b64 vcc, exec, s[2:3]
	v_lshlrev_b64 v[64:65], 8, v[64:65]
	s_waitcnt vmcnt(0)
	v_mov_b32_e32 v68, v242
	v_fmamk_f32 v68, v68, 0x3b800000, v216
	v_mul_f32_e32 v69, 0x4b800000, v68
	v_cmp_gt_f32_e64 s[6:7], s38, v68
	s_nop 1
	v_cndmask_b32_e64 v68, v68, v69, s[6:7]
	v_rsq_f32_e32 v70, v68
	v_mov_b32_e32 v69, v32
	v_mov_b32_e32 v68, v48
	v_mul_f32_e32 v32, 0x45800000, v70
	v_cndmask_b32_e64 v32, v70, v32, s[6:7]
	v_mul_f32_e32 v32, 0x3dd53b94, v32
	v_pk_mul_f32 v[70:71], v[68:69], v[32:33] op_sel_hi:[1,0]
	s_cbranch_vccnz .LBB0_957
	s_load_dwordx2 s[6:7], s[0:1], 0x148
	s_waitcnt lgkmcnt(0)
	v_lshl_add_u64 v[68:69], s[6:7], 0, v[64:65]
	v_lshl_add_u64 v[68:69], v[68:69], 0, v[160:161]
	global_load_dwordx2 v[246:247], v[68:69], off
	global_load_dwordx2 v[248:249], v[68:69], off offset:256
	global_load_dwordx2 v[250:251], v[68:69], off offset:512
	global_load_dwordx2 v[252:253], v[68:69], off offset:768
	s_waitcnt vmcnt(0)
	v_mov_b32_e32 v68, v246
	v_mov_b32_e32 v69, v247
	v_pk_mul_f32 v[72:73], v[70:71], v[68:69] op_sel_hi:[0,1]
	v_pk_mul_f32 v[74:75], v[70:71], v[68:69] op_sel:[1,1] op_sel_hi:[1,0]
	v_pk_fma_f32 v[70:71], v[70:71], v[68:69], v[72:73] op_sel:[1,1,0] op_sel_hi:[1,0,1] neg_lo:[0,0,1] neg_hi:[0,0,1]
	s_nop 0
	v_add_f32_e32 v70, v74, v72
.LBB0_957:
	v_or_b32_e32 v32, 1, v97
	v_min_i32_e32 v72, 0x7fff, v32
	v_ashrrev_i32_e32 v73, 31, v72
	v_lshl_add_u64 v[68:69], v[72:73], 2, s[18:19]
	v_mov_b32_e32 v48, v243
	v_mov_b32_e32 v32, v49
	v_cvt_pk_bf16_f32 v71, v71, s0
	s_and_b64 vcc, exec, s[2:3]
	v_cvt_pk_bf16_f32 v70, v70, s0
	ds_write_b16 v217, v71
	ds_write_b16 v217, v70 offset:64
	s_waitcnt vmcnt(0)
	v_fmamk_f32 v48, v48, 0x3b800000, v216
	v_mul_f32_e32 v49, 0x4b800000, v48
	v_cmp_gt_f32_e64 s[6:7], s38, v48
	s_nop 1
	v_cndmask_b32_e64 v48, v48, v49, s[6:7]
	v_rsq_f32_e32 v48, v48
	s_nop 0
	v_mul_f32_e32 v49, 0x45800000, v48
	v_cndmask_b32_e64 v48, v48, v49, s[6:7]
	v_mul_f32_e32 v48, 0x3dd53b94, v48
	v_pk_mul_f32 v[48:49], v[32:33], v[48:49] op_sel_hi:[1,0]
	v_lshlrev_b64 v[32:33], 8, v[72:73]
	s_cbranch_vccnz .LBB0_959
	s_load_dwordx2 s[6:7], s[0:1], 0x148
	s_waitcnt lgkmcnt(0)
	v_lshl_add_u64 v[70:71], s[6:7], 0, v[32:33]
	v_lshl_add_u64 v[70:71], v[70:71], 0, v[160:161]
	v_mov_b32_e32 v70, v248
	v_mov_b32_e32 v71, v249
	s_waitcnt vmcnt(0)
	v_pk_mul_f32 v[72:73], v[48:49], v[70:71] op_sel_hi:[0,1]
	v_pk_mul_f32 v[74:75], v[48:49], v[70:71] op_sel:[1,1] op_sel_hi:[1,0]
	v_pk_fma_f32 v[48:49], v[48:49], v[70:71], v[72:73] op_sel:[1,1,0] op_sel_hi:[1,0,1] neg_lo:[0,0,1] neg_hi:[0,0,1]
	s_nop 0
	v_add_f32_e32 v48, v74, v72
.LBB0_959:
	v_or_b32_e32 v70, 2, v97
	v_min_i32_e32 v72, 0x7fff, v70
	v_ashrrev_i32_e32 v73, 31, v72
	v_lshl_add_u64 v[70:71], v[72:73], 2, s[18:19]
	v_mov_b32_e32 v74, v244
	v_cvt_pk_bf16_f32 v75, v49, s0
	v_mov_b32_e32 v49, v34
	v_cvt_pk_bf16_f32 v76, v48, s0
	v_mov_b32_e32 v48, v50
	s_and_b64 vcc, exec, s[2:3]
	ds_write_b16 v217, v75 offset:144
	ds_write_b16 v217, v76 offset:208
	s_waitcnt vmcnt(0)
	v_fmamk_f32 v34, v74, 0x3b800000, v216
	v_mul_f32_e32 v50, 0x4b800000, v34
	v_cmp_gt_f32_e64 s[6:7], s38, v34
	s_nop 1
	v_cndmask_b32_e64 v34, v34, v50, s[6:7]
	v_rsq_f32_e32 v34, v34
	s_nop 0
	v_mul_f32_e32 v50, 0x45800000, v34
	v_cndmask_b32_e64 v34, v34, v50, s[6:7]
	v_mul_f32_e32 v34, 0x3dd53b94, v34
	v_pk_mul_f32 v[74:75], v[48:49], v[34:35] op_sel_hi:[1,0]
	v_lshlrev_b64 v[48:49], 8, v[72:73]
	s_cbranch_vccnz .LBB0_961
	s_load_dwordx2 s[6:7], s[0:1], 0x148
	s_waitcnt lgkmcnt(0)
	v_lshl_add_u64 v[72:73], s[6:7], 0, v[48:49]
	v_lshl_add_u64 v[72:73], v[72:73], 0, v[160:161]
	v_mov_b32_e32 v72, v250
	v_mov_b32_e32 v73, v251
	s_waitcnt vmcnt(0)
	v_pk_mul_f32 v[76:77], v[74:75], v[72:73] op_sel_hi:[0,1]
	v_pk_mul_f32 v[78:79], v[74:75], v[72:73] op_sel:[1,1] op_sel_hi:[1,0]
	v_pk_fma_f32 v[74:75], v[74:75], v[72:73], v[76:77] op_sel:[1,1,0] op_sel_hi:[1,0,1] neg_lo:[0,0,1] neg_hi:[0,0,1]
	s_nop 0
	v_add_f32_e32 v74, v78, v76
.LBB0_961:
	v_or_b32_e32 v34, 3, v97
	v_min_i32_e32 v76, 0x7fff, v34
	v_ashrrev_i32_e32 v77, 31, v76
	v_lshl_add_u64 v[72:73], v[76:77], 2, s[18:19]
	v_mov_b32_e32 v50, v245
	v_mov_b32_e32 v34, v51
	v_cvt_pk_bf16_f32 v75, v75, s0
	s_and_b64 vcc, exec, s[2:3]
	v_cvt_pk_bf16_f32 v74, v74, s0
	ds_write_b16 v217, v75 offset:288
	ds_write_b16 v217, v74 offset:352
	s_waitcnt vmcnt(0)
	v_fmamk_f32 v50, v50, 0x3b800000, v216
	v_mul_f32_e32 v51, 0x4b800000, v50
	v_cmp_gt_f32_e64 s[6:7], s38, v50
	s_nop 1
	v_cndmask_b32_e64 v50, v50, v51, s[6:7]
	v_rsq_f32_e32 v50, v50
	s_nop 0
	v_mul_f32_e32 v51, 0x45800000, v50
	v_cndmask_b32_e64 v50, v50, v51, s[6:7]
	v_mul_f32_e32 v50, 0x3dd53b94, v50
	v_pk_mul_f32 v[50:51], v[34:35], v[50:51] op_sel_hi:[1,0]
	v_lshlrev_b64 v[34:35], 8, v[76:77]
	s_cbranch_vccnz .LBB0_963
	s_load_dwordx2 s[6:7], s[0:1], 0x148
	s_waitcnt lgkmcnt(0)
	v_lshl_add_u64 v[74:75], s[6:7], 0, v[34:35]
	v_lshl_add_u64 v[74:75], v[74:75], 0, v[160:161]
	v_mov_b32_e32 v74, v252
	v_mov_b32_e32 v75, v253
	s_waitcnt vmcnt(0)
	v_pk_mul_f32 v[76:77], v[50:51], v[74:75] op_sel_hi:[0,1]
	v_pk_mul_f32 v[78:79], v[50:51], v[74:75] op_sel:[1,1] op_sel_hi:[1,0]
	v_pk_fma_f32 v[50:51], v[50:51], v[74:75], v[76:77] op_sel:[1,1,0] op_sel_hi:[1,0,1] neg_lo:[0,0,1] neg_hi:[0,0,1]
	s_nop 0
	v_add_f32_e32 v50, v78, v76
.LBB0_963:
	v_add_u32_e32 v74, 8, v97
	v_min_i32_e32 v76, 0x7fff, v74
	v_ashrrev_i32_e32 v77, 31, v76
	v_lshl_add_u64 v[74:75], v[76:77], 2, s[18:19]
	global_load_dword v242, v[74:75], off
	global_load_dword v243, v[74:75], off offset:4
	global_load_dword v244, v[74:75], off offset:8
	global_load_dword v245, v[74:75], off offset:12
	v_cvt_pk_bf16_f32 v79, v51, s0
	v_mov_b32_e32 v51, v36
	v_cvt_pk_bf16_f32 v80, v50, s0
	v_mov_b32_e32 v50, v52
	s_and_b64 vcc, exec, s[2:3]
	ds_write_b16 v217, v79 offset:432
	ds_write_b16 v217, v80 offset:496
	s_waitcnt vmcnt(0)
	v_mov_b32_e32 v78, v242
	v_fmamk_f32 v36, v78, 0x3b800000, v216
	v_mul_f32_e32 v52, 0x4b800000, v36
	v_cmp_gt_f32_e64 s[6:7], s38, v36
	s_nop 1
	v_cndmask_b32_e64 v36, v36, v52, s[6:7]
	v_rsq_f32_e32 v36, v36
	s_nop 0
	v_mul_f32_e32 v52, 0x45800000, v36
	v_cndmask_b32_e64 v36, v36, v52, s[6:7]
	v_mul_f32_e32 v36, 0x3dd53b94, v36
	v_pk_mul_f32 v[78:79], v[50:51], v[36:37] op_sel_hi:[1,0]
	v_lshlrev_b64 v[50:51], 8, v[76:77]
	s_cbranch_vccnz .LBB0_965
	s_load_dwordx2 s[6:7], s[0:1], 0x148
	s_waitcnt lgkmcnt(0)
	v_lshl_add_u64 v[76:77], s[6:7], 0, v[50:51]
	v_lshl_add_u64 v[76:77], v[76:77], 0, v[160:161]
	global_load_dwordx2 v[246:247], v[76:77], off
	global_load_dwordx2 v[248:249], v[76:77], off offset:256
	global_load_dwordx2 v[250:251], v[76:77], off offset:512
	global_load_dwordx2 v[252:253], v[76:77], off offset:768
	s_waitcnt vmcnt(0)
	v_mov_b32_e32 v76, v246
	v_mov_b32_e32 v77, v247
	v_pk_mul_f32 v[80:81], v[78:79], v[76:77] op_sel_hi:[0,1]
	v_pk_mul_f32 v[82:83], v[78:79], v[76:77] op_sel:[1,1] op_sel_hi:[1,0]
	v_pk_fma_f32 v[78:79], v[78:79], v[76:77], v[80:81] op_sel:[1,1,0] op_sel_hi:[1,0,1] neg_lo:[0,0,1] neg_hi:[0,0,1]
	s_nop 0
	v_add_f32_e32 v78, v82, v80
.LBB0_965:
	v_add_u32_e32 v36, 9, v97
	v_min_i32_e32 v80, 0x7fff, v36
	v_ashrrev_i32_e32 v81, 31, v80
	v_lshl_add_u64 v[76:77], v[80:81], 2, s[18:19]
	v_mov_b32_e32 v52, v243
	v_mov_b32_e32 v36, v53
	v_cvt_pk_bf16_f32 v79, v79, s0
	s_and_b64 vcc, exec, s[2:3]
	v_cvt_pk_bf16_f32 v78, v78, s0
	ds_write_b16 v217, v79 offset:1152
	ds_write_b16 v217, v78 offset:1216
	s_waitcnt vmcnt(0)
	v_fmamk_f32 v52, v52, 0x3b800000, v216
	v_mul_f32_e32 v53, 0x4b800000, v52
	v_cmp_gt_f32_e64 s[6:7], s38, v52
	s_nop 1
	v_cndmask_b32_e64 v52, v52, v53, s[6:7]
	v_rsq_f32_e32 v52, v52
	s_nop 0
	v_mul_f32_e32 v53, 0x45800000, v52
	v_cndmask_b32_e64 v52, v52, v53, s[6:7]
	v_mul_f32_e32 v52, 0x3dd53b94, v52
	v_pk_mul_f32 v[52:53], v[36:37], v[52:53] op_sel_hi:[1,0]
	v_lshlrev_b64 v[36:37], 8, v[80:81]
	s_cbranch_vccnz .LBB0_967
	s_load_dwordx2 s[6:7], s[0:1], 0x148
	s_waitcnt lgkmcnt(0)
	v_lshl_add_u64 v[78:79], s[6:7], 0, v[36:37]
	v_lshl_add_u64 v[78:79], v[78:79], 0, v[160:161]
	v_mov_b32_e32 v78, v248
	v_mov_b32_e32 v79, v249
	s_waitcnt vmcnt(0)
	v_pk_mul_f32 v[80:81], v[52:53], v[78:79] op_sel_hi:[0,1]
	v_pk_mul_f32 v[82:83], v[52:53], v[78:79] op_sel:[1,1] op_sel_hi:[1,0]
	v_pk_fma_f32 v[52:53], v[52:53], v[78:79], v[80:81] op_sel:[1,1,0] op_sel_hi:[1,0,1] neg_lo:[0,0,1] neg_hi:[0,0,1]
	s_nop 0
	v_add_f32_e32 v52, v82, v80
.LBB0_967:
	v_add_u32_e32 v78, 10, v97
	v_min_i32_e32 v80, 0x7fff, v78
	v_ashrrev_i32_e32 v81, 31, v80
	v_lshl_add_u64 v[78:79], v[80:81], 2, s[18:19]
	v_mov_b32_e32 v82, v244
	v_cvt_pk_bf16_f32 v83, v53, s0
	v_mov_b32_e32 v53, v38
	v_cvt_pk_bf16_f32 v84, v52, s0
	v_mov_b32_e32 v52, v54
	s_and_b64 vcc, exec, s[2:3]
	ds_write_b16 v217, v83 offset:1296
	ds_write_b16 v217, v84 offset:1360
	s_waitcnt vmcnt(0)
	v_fmamk_f32 v38, v82, 0x3b800000, v216
	v_mul_f32_e32 v54, 0x4b800000, v38
	v_cmp_gt_f32_e64 s[6:7], s38, v38
	s_nop 1
	v_cndmask_b32_e64 v38, v38, v54, s[6:7]
	v_rsq_f32_e32 v38, v38
	s_nop 0
	v_mul_f32_e32 v54, 0x45800000, v38
	v_cndmask_b32_e64 v38, v38, v54, s[6:7]
	v_mul_f32_e32 v38, 0x3dd53b94, v38
	v_pk_mul_f32 v[82:83], v[52:53], v[38:39] op_sel_hi:[1,0]
	v_lshlrev_b64 v[52:53], 8, v[80:81]
	s_cbranch_vccnz .LBB0_969
	s_load_dwordx2 s[6:7], s[0:1], 0x148
	s_waitcnt lgkmcnt(0)
	v_lshl_add_u64 v[80:81], s[6:7], 0, v[52:53]
	v_lshl_add_u64 v[80:81], v[80:81], 0, v[160:161]
	v_mov_b32_e32 v80, v250
	v_mov_b32_e32 v81, v251
	s_waitcnt vmcnt(0)
	v_pk_mul_f32 v[84:85], v[82:83], v[80:81] op_sel_hi:[0,1]
	v_pk_mul_f32 v[86:87], v[82:83], v[80:81] op_sel:[1,1] op_sel_hi:[1,0]
	v_pk_fma_f32 v[82:83], v[82:83], v[80:81], v[84:85] op_sel:[1,1,0] op_sel_hi:[1,0,1] neg_lo:[0,0,1] neg_hi:[0,0,1]
	s_nop 0
	v_add_f32_e32 v82, v86, v84
.LBB0_969:
	v_add_u32_e32 v38, 11, v97
	v_min_i32_e32 v84, 0x7fff, v38
	v_ashrrev_i32_e32 v85, 31, v84
	v_lshl_add_u64 v[80:81], v[84:85], 2, s[18:19]
	v_mov_b32_e32 v54, v245
	v_mov_b32_e32 v38, v55
	v_cvt_pk_bf16_f32 v83, v83, s0
	s_and_b64 vcc, exec, s[2:3]
	v_cvt_pk_bf16_f32 v82, v82, s0
	ds_write_b16 v217, v83 offset:1440
	ds_write_b16 v217, v82 offset:1504
	s_waitcnt vmcnt(0)
	v_fmamk_f32 v54, v54, 0x3b800000, v216
	v_mul_f32_e32 v55, 0x4b800000, v54
	v_cmp_gt_f32_e64 s[6:7], s38, v54
	s_nop 1
	v_cndmask_b32_e64 v54, v54, v55, s[6:7]
	v_rsq_f32_e32 v54, v54
	s_nop 0
	v_mul_f32_e32 v55, 0x45800000, v54
	v_cndmask_b32_e64 v54, v54, v55, s[6:7]
	v_mul_f32_e32 v54, 0x3dd53b94, v54
	v_pk_mul_f32 v[54:55], v[38:39], v[54:55] op_sel_hi:[1,0]
	v_lshlrev_b64 v[38:39], 8, v[84:85]
	s_cbranch_vccnz .LBB0_971
	s_load_dwordx2 s[6:7], s[0:1], 0x148
	s_waitcnt lgkmcnt(0)
	v_lshl_add_u64 v[82:83], s[6:7], 0, v[38:39]
	v_lshl_add_u64 v[82:83], v[82:83], 0, v[160:161]
	v_mov_b32_e32 v82, v252
	v_mov_b32_e32 v83, v253
	s_waitcnt vmcnt(0)
	v_pk_mul_f32 v[84:85], v[54:55], v[82:83] op_sel_hi:[0,1]
	v_pk_mul_f32 v[86:87], v[54:55], v[82:83] op_sel:[1,1] op_sel_hi:[1,0]
	v_pk_fma_f32 v[54:55], v[54:55], v[82:83], v[84:85] op_sel:[1,1,0] op_sel_hi:[1,0,1] neg_lo:[0,0,1] neg_hi:[0,0,1]
	s_nop 0
	v_add_f32_e32 v54, v86, v84
.LBB0_971:
	v_add_u32_e32 v82, 16, v97
	v_min_i32_e32 v84, 0x7fff, v82
	v_ashrrev_i32_e32 v85, 31, v84
	v_lshl_add_u64 v[82:83], v[84:85], 2, s[18:19]
	global_load_dword v242, v[82:83], off
	global_load_dword v243, v[82:83], off offset:4
	global_load_dword v244, v[82:83], off offset:8
	global_load_dword v245, v[82:83], off offset:12
	v_cvt_pk_bf16_f32 v87, v55, s0
	v_mov_b32_e32 v55, v40
	v_cvt_pk_bf16_f32 v88, v54, s0
	v_mov_b32_e32 v54, v56
	s_and_b64 vcc, exec, s[2:3]
	ds_write_b16 v217, v87 offset:1584
	ds_write_b16 v217, v88 offset:1648
	s_waitcnt vmcnt(0)
	v_mov_b32_e32 v86, v242
	v_fmamk_f32 v40, v86, 0x3b800000, v216
	v_mul_f32_e32 v56, 0x4b800000, v40
	v_cmp_gt_f32_e64 s[6:7], s38, v40
	s_nop 1
	v_cndmask_b32_e64 v40, v40, v56, s[6:7]
	v_rsq_f32_e32 v40, v40
	s_nop 0
	v_mul_f32_e32 v56, 0x45800000, v40
	v_cndmask_b32_e64 v40, v40, v56, s[6:7]
	v_mul_f32_e32 v40, 0x3dd53b94, v40
	v_pk_mul_f32 v[86:87], v[54:55], v[40:41] op_sel_hi:[1,0]
	v_lshlrev_b64 v[54:55], 8, v[84:85]
	s_cbranch_vccnz .LBB0_973
	s_load_dwordx2 s[6:7], s[0:1], 0x148
	s_waitcnt lgkmcnt(0)
	v_lshl_add_u64 v[84:85], s[6:7], 0, v[54:55]
	v_lshl_add_u64 v[84:85], v[84:85], 0, v[160:161]
	global_load_dwordx2 v[246:247], v[84:85], off
	global_load_dwordx2 v[248:249], v[84:85], off offset:256
	global_load_dwordx2 v[250:251], v[84:85], off offset:512
	global_load_dwordx2 v[252:253], v[84:85], off offset:768
	s_waitcnt vmcnt(0)
	v_mov_b32_e32 v84, v246
	v_mov_b32_e32 v85, v247
	v_pk_mul_f32 v[88:89], v[86:87], v[84:85] op_sel_hi:[0,1]
	v_pk_mul_f32 v[90:91], v[86:87], v[84:85] op_sel:[1,1] op_sel_hi:[1,0]
	v_pk_fma_f32 v[86:87], v[86:87], v[84:85], v[88:89] op_sel:[1,1,0] op_sel_hi:[1,0,1] neg_lo:[0,0,1] neg_hi:[0,0,1]
	s_nop 0
	v_add_f32_e32 v86, v90, v88
.LBB0_973:
	v_add_u32_e32 v40, 17, v97
	v_min_i32_e32 v88, 0x7fff, v40
	v_ashrrev_i32_e32 v89, 31, v88
	v_lshl_add_u64 v[84:85], v[88:89], 2, s[18:19]
	v_mov_b32_e32 v56, v243
	v_mov_b32_e32 v40, v57
	v_cvt_pk_bf16_f32 v87, v87, s0
	s_and_b64 vcc, exec, s[2:3]
	v_cvt_pk_bf16_f32 v86, v86, s0
	ds_write_b16 v217, v87 offset:2304
	ds_write_b16 v217, v86 offset:2368
	s_waitcnt vmcnt(0)
	v_fmamk_f32 v56, v56, 0x3b800000, v216
	v_mul_f32_e32 v57, 0x4b800000, v56
	v_cmp_gt_f32_e64 s[6:7], s38, v56
	s_nop 1
	v_cndmask_b32_e64 v56, v56, v57, s[6:7]
	v_rsq_f32_e32 v56, v56
	s_nop 0
	v_mul_f32_e32 v57, 0x45800000, v56
	v_cndmask_b32_e64 v56, v56, v57, s[6:7]
	v_mul_f32_e32 v56, 0x3dd53b94, v56
	v_pk_mul_f32 v[56:57], v[40:41], v[56:57] op_sel_hi:[1,0]
	v_lshlrev_b64 v[40:41], 8, v[88:89]
	s_cbranch_vccnz .LBB0_975
	s_load_dwordx2 s[6:7], s[0:1], 0x148
	s_waitcnt lgkmcnt(0)
	v_lshl_add_u64 v[86:87], s[6:7], 0, v[40:41]
	v_lshl_add_u64 v[86:87], v[86:87], 0, v[160:161]
	v_mov_b32_e32 v86, v248
	v_mov_b32_e32 v87, v249
	s_waitcnt vmcnt(0)
	v_pk_mul_f32 v[88:89], v[56:57], v[86:87] op_sel_hi:[0,1]
	v_pk_mul_f32 v[90:91], v[56:57], v[86:87] op_sel:[1,1] op_sel_hi:[1,0]
	v_pk_fma_f32 v[56:57], v[56:57], v[86:87], v[88:89] op_sel:[1,1,0] op_sel_hi:[1,0,1] neg_lo:[0,0,1] neg_hi:[0,0,1]
	s_nop 0
	v_add_f32_e32 v56, v90, v88
.LBB0_975:
	v_add_u32_e32 v86, 18, v97
	v_min_i32_e32 v88, 0x7fff, v86
	v_ashrrev_i32_e32 v89, 31, v88
	v_lshl_add_u64 v[86:87], v[88:89], 2, s[18:19]
	v_mov_b32_e32 v90, v244
	v_cvt_pk_bf16_f32 v91, v57, s0
	v_mov_b32_e32 v57, v42
	v_cvt_pk_bf16_f32 v92, v56, s0
	v_mov_b32_e32 v56, v58
	s_and_b64 vcc, exec, s[2:3]
	ds_write_b16 v217, v91 offset:2448
	ds_write_b16 v217, v92 offset:2512
	s_waitcnt vmcnt(0)
	v_fmamk_f32 v42, v90, 0x3b800000, v216
	v_mul_f32_e32 v58, 0x4b800000, v42
	v_cmp_gt_f32_e64 s[6:7], s38, v42
	s_nop 1
	v_cndmask_b32_e64 v42, v42, v58, s[6:7]
	v_rsq_f32_e32 v42, v42
	s_nop 0
	v_mul_f32_e32 v58, 0x45800000, v42
	v_cndmask_b32_e64 v42, v42, v58, s[6:7]
	v_mul_f32_e32 v42, 0x3dd53b94, v42
	v_pk_mul_f32 v[90:91], v[56:57], v[42:43] op_sel_hi:[1,0]
	v_lshlrev_b64 v[56:57], 8, v[88:89]
	s_cbranch_vccnz .LBB0_977
	s_load_dwordx2 s[6:7], s[0:1], 0x148
	s_waitcnt lgkmcnt(0)
	v_lshl_add_u64 v[88:89], s[6:7], 0, v[56:57]
	v_lshl_add_u64 v[88:89], v[88:89], 0, v[160:161]
	v_mov_b32_e32 v88, v250
	v_mov_b32_e32 v89, v251
	s_waitcnt vmcnt(0)
	v_pk_mul_f32 v[92:93], v[90:91], v[88:89] op_sel_hi:[0,1]
	v_pk_mul_f32 v[94:95], v[90:91], v[88:89] op_sel:[1,1] op_sel_hi:[1,0]
	v_pk_fma_f32 v[90:91], v[90:91], v[88:89], v[92:93] op_sel:[1,1,0] op_sel_hi:[1,0,1] neg_lo:[0,0,1] neg_hi:[0,0,1]
	s_nop 0
	v_add_f32_e32 v90, v94, v92
.LBB0_977:
	v_add_u32_e32 v42, 19, v97
	v_min_i32_e32 v92, 0x7fff, v42
	v_ashrrev_i32_e32 v93, 31, v92
	v_lshl_add_u64 v[88:89], v[92:93], 2, s[18:19]
	v_mov_b32_e32 v58, v245
	v_mov_b32_e32 v42, v59
	v_cvt_pk_bf16_f32 v91, v91, s0
	s_and_b64 vcc, exec, s[2:3]
	v_cvt_pk_bf16_f32 v90, v90, s0
	ds_write_b16 v217, v91 offset:2592
	ds_write_b16 v217, v90 offset:2656
	s_waitcnt vmcnt(0)
	v_fmamk_f32 v58, v58, 0x3b800000, v216
	v_mul_f32_e32 v59, 0x4b800000, v58
	v_cmp_gt_f32_e64 s[6:7], s38, v58
	s_nop 1
	v_cndmask_b32_e64 v58, v58, v59, s[6:7]
	v_rsq_f32_e32 v58, v58
	s_nop 0
	v_mul_f32_e32 v59, 0x45800000, v58
	v_cndmask_b32_e64 v58, v58, v59, s[6:7]
	v_mul_f32_e32 v58, 0x3dd53b94, v58
	v_pk_mul_f32 v[58:59], v[42:43], v[58:59] op_sel_hi:[1,0]
	v_lshlrev_b64 v[42:43], 8, v[92:93]
	s_cbranch_vccnz .LBB0_979
	s_load_dwordx2 s[6:7], s[0:1], 0x148
	s_waitcnt lgkmcnt(0)
	v_lshl_add_u64 v[90:91], s[6:7], 0, v[42:43]
	v_lshl_add_u64 v[90:91], v[90:91], 0, v[160:161]
	v_mov_b32_e32 v90, v252
	v_mov_b32_e32 v91, v253
	s_waitcnt vmcnt(0)
	v_pk_mul_f32 v[92:93], v[58:59], v[90:91] op_sel_hi:[0,1]
	v_pk_mul_f32 v[94:95], v[58:59], v[90:91] op_sel:[1,1] op_sel_hi:[1,0]
	v_pk_fma_f32 v[58:59], v[58:59], v[90:91], v[92:93] op_sel:[1,1,0] op_sel_hi:[1,0,1] neg_lo:[0,0,1] neg_hi:[0,0,1]
	s_nop 0
	v_add_f32_e32 v58, v94, v92
.LBB0_979:
	v_add_u32_e32 v90, 24, v97
	v_min_i32_e32 v92, 0x7fff, v90
	v_ashrrev_i32_e32 v93, 31, v92
	v_lshl_add_u64 v[90:91], v[92:93], 2, s[18:19]
	global_load_dword v242, v[90:91], off
	global_load_dword v243, v[90:91], off offset:4
	global_load_dword v244, v[90:91], off offset:8
	global_load_dword v245, v[90:91], off offset:12
	v_cvt_pk_bf16_f32 v95, v59, s0
	v_mov_b32_e32 v59, v44
	v_cvt_pk_bf16_f32 v98, v58, s0
	v_mov_b32_e32 v58, v60
	s_and_b64 vcc, exec, s[2:3]
	ds_write_b16 v217, v95 offset:2736
	ds_write_b16 v217, v98 offset:2800
	s_waitcnt vmcnt(0)
	v_mov_b32_e32 v94, v242
	v_fmamk_f32 v44, v94, 0x3b800000, v216
	v_mul_f32_e32 v60, 0x4b800000, v44
	v_cmp_gt_f32_e64 s[6:7], s38, v44
	s_nop 1
	v_cndmask_b32_e64 v44, v44, v60, s[6:7]
	v_rsq_f32_e32 v44, v44
	s_nop 0
	v_mul_f32_e32 v60, 0x45800000, v44
	v_cndmask_b32_e64 v44, v44, v60, s[6:7]
	v_mul_f32_e32 v44, 0x3dd53b94, v44
	v_pk_mul_f32 v[94:95], v[58:59], v[44:45] op_sel_hi:[1,0]
	v_lshlrev_b64 v[58:59], 8, v[92:93]
	s_cbranch_vccnz .LBB0_981
	s_load_dwordx2 s[6:7], s[0:1], 0x148
	s_waitcnt lgkmcnt(0)
	v_lshl_add_u64 v[92:93], s[6:7], 0, v[58:59]
	v_lshl_add_u64 v[92:93], v[92:93], 0, v[160:161]
	global_load_dwordx2 v[246:247], v[92:93], off
	global_load_dwordx2 v[248:249], v[92:93], off offset:256
	global_load_dwordx2 v[250:251], v[92:93], off offset:512
	global_load_dwordx2 v[252:253], v[92:93], off offset:768
	s_waitcnt vmcnt(0)
	v_mov_b32_e32 v92, v246
	v_mov_b32_e32 v93, v247
	v_pk_mul_f32 v[98:99], v[94:95], v[92:93] op_sel_hi:[0,1]
	v_pk_mul_f32 v[100:101], v[94:95], v[92:93] op_sel:[1,1] op_sel_hi:[1,0]
	v_pk_fma_f32 v[94:95], v[94:95], v[92:93], v[98:99] op_sel:[1,1,0] op_sel_hi:[1,0,1] neg_lo:[0,0,1] neg_hi:[0,0,1]
	s_nop 0
	v_add_f32_e32 v94, v100, v98
.LBB0_981:
	v_add_u32_e32 v44, 25, v97
	v_min_i32_e32 v98, 0x7fff, v44
	v_ashrrev_i32_e32 v99, 31, v98
	v_lshl_add_u64 v[92:93], v[98:99], 2, s[18:19]
	v_mov_b32_e32 v60, v243
	v_mov_b32_e32 v44, v61
	v_cvt_pk_bf16_f32 v95, v95, s0
	s_and_b64 vcc, exec, s[2:3]
	v_cvt_pk_bf16_f32 v94, v94, s0
	ds_write_b16 v217, v95 offset:3456
	ds_write_b16 v217, v94 offset:3520
	s_waitcnt vmcnt(0)
	v_fmamk_f32 v60, v60, 0x3b800000, v216
	v_mul_f32_e32 v61, 0x4b800000, v60
	v_cmp_gt_f32_e64 s[6:7], s38, v60
	s_nop 1
	v_cndmask_b32_e64 v60, v60, v61, s[6:7]
	v_rsq_f32_e32 v60, v60
	s_nop 0
	v_mul_f32_e32 v61, 0x45800000, v60
	v_cndmask_b32_e64 v60, v60, v61, s[6:7]
	v_mul_f32_e32 v60, 0x3dd53b94, v60
	v_pk_mul_f32 v[60:61], v[44:45], v[60:61] op_sel_hi:[1,0]
	v_lshlrev_b64 v[44:45], 8, v[98:99]
	s_cbranch_vccnz .LBB0_983
	s_load_dwordx2 s[6:7], s[0:1], 0x148
	s_waitcnt lgkmcnt(0)
	v_lshl_add_u64 v[94:95], s[6:7], 0, v[44:45]
	v_lshl_add_u64 v[94:95], v[94:95], 0, v[160:161]
	v_mov_b32_e32 v94, v248
	v_mov_b32_e32 v95, v249
	s_waitcnt vmcnt(0)
	v_pk_mul_f32 v[98:99], v[60:61], v[94:95] op_sel_hi:[0,1]
	v_pk_mul_f32 v[100:101], v[60:61], v[94:95] op_sel:[1,1] op_sel_hi:[1,0]
	v_pk_fma_f32 v[60:61], v[60:61], v[94:95], v[98:99] op_sel:[1,1,0] op_sel_hi:[1,0,1] neg_lo:[0,0,1] neg_hi:[0,0,1]
	s_nop 0
	v_add_f32_e32 v60, v100, v98
.LBB0_983:
	v_add_u32_e32 v94, 26, v97
	v_min_i32_e32 v98, 0x7fff, v94
	v_ashrrev_i32_e32 v99, 31, v98
	v_lshl_add_u64 v[94:95], v[98:99], 2, s[18:19]
	v_mov_b32_e32 v100, v244
	v_cvt_pk_bf16_f32 v101, v61, s0
	v_mov_b32_e32 v61, v46
	v_cvt_pk_bf16_f32 v102, v60, s0
	v_mov_b32_e32 v60, v62
	s_and_b64 vcc, exec, s[2:3]
	ds_write_b16 v217, v101 offset:3600
	ds_write_b16 v217, v102 offset:3664
	s_waitcnt vmcnt(0)
	v_fmamk_f32 v46, v100, 0x3b800000, v216
	v_mul_f32_e32 v62, 0x4b800000, v46
	v_cmp_gt_f32_e64 s[6:7], s38, v46
	s_nop 1
	v_cndmask_b32_e64 v46, v46, v62, s[6:7]
	v_rsq_f32_e32 v46, v46
	s_nop 0
	v_mul_f32_e32 v62, 0x45800000, v46
	v_cndmask_b32_e64 v46, v46, v62, s[6:7]
	v_mul_f32_e32 v46, 0x3dd53b94, v46
	v_pk_mul_f32 v[100:101], v[60:61], v[46:47] op_sel_hi:[1,0]
	v_lshlrev_b64 v[60:61], 8, v[98:99]
	s_cbranch_vccnz .LBB0_985
	s_load_dwordx2 s[6:7], s[0:1], 0x148
	s_waitcnt lgkmcnt(0)
	v_lshl_add_u64 v[98:99], s[6:7], 0, v[60:61]
	v_lshl_add_u64 v[98:99], v[98:99], 0, v[160:161]
	v_mov_b32_e32 v98, v250
	v_mov_b32_e32 v99, v251
	s_waitcnt vmcnt(0)
	v_pk_mul_f32 v[102:103], v[100:101], v[98:99] op_sel_hi:[0,1]
	v_pk_mul_f32 v[104:105], v[100:101], v[98:99] op_sel:[1,1] op_sel_hi:[1,0]
	v_pk_fma_f32 v[100:101], v[100:101], v[98:99], v[102:103] op_sel:[1,1,0] op_sel_hi:[1,0,1] neg_lo:[0,0,1] neg_hi:[0,0,1]
	s_nop 0
	v_add_f32_e32 v100, v104, v102
.LBB0_985:
	v_add_u32_e32 v46, 27, v97
	v_min_i32_e32 v102, 0x7fff, v46
	v_ashrrev_i32_e32 v103, 31, v102
	v_lshl_add_u64 v[98:99], v[102:103], 2, s[18:19]
	v_mov_b32_e32 v62, v245
	v_mov_b32_e32 v46, v63
	v_cvt_pk_bf16_f32 v97, v101, s0
	s_and_b64 vcc, exec, s[2:3]
	v_cvt_pk_bf16_f32 v100, v100, s0
	ds_write_b16 v217, v97 offset:3744
	ds_write_b16 v217, v100 offset:3808
	s_waitcnt vmcnt(0)
	v_fmamk_f32 v62, v62, 0x3b800000, v216
	v_mul_f32_e32 v63, 0x4b800000, v62
	v_cmp_gt_f32_e64 s[6:7], s38, v62
	s_nop 1
	v_cndmask_b32_e64 v62, v62, v63, s[6:7]
	v_rsq_f32_e32 v62, v62
	s_nop 0
	v_mul_f32_e32 v63, 0x45800000, v62
	v_cndmask_b32_e64 v62, v62, v63, s[6:7]
	v_mul_f32_e32 v62, 0x3dd53b94, v62
	v_pk_mul_f32 v[62:63], v[46:47], v[62:63] op_sel_hi:[1,0]
	v_lshlrev_b64 v[46:47], 8, v[102:103]
	s_cbranch_vccnz .LBB0_987
	s_load_dwordx2 s[2:3], s[0:1], 0x148
	s_waitcnt lgkmcnt(0)
	v_lshl_add_u64 v[100:101], s[2:3], 0, v[46:47]
	v_lshl_add_u64 v[100:101], v[100:101], 0, v[160:161]
	v_mov_b32_e32 v100, v252
	v_mov_b32_e32 v101, v253
	s_waitcnt vmcnt(0)
	v_pk_mul_f32 v[102:103], v[62:63], v[100:101] op_sel_hi:[0,1]
	v_pk_mul_f32 v[104:105], v[62:63], v[100:101] op_sel:[1,1] op_sel_hi:[1,0]
	v_pk_fma_f32 v[62:63], v[62:63], v[100:101], v[102:103] op_sel:[1,1,0] op_sel_hi:[1,0,1] neg_lo:[0,0,1] neg_hi:[0,0,1]
	s_nop 0
	v_add_f32_e32 v62, v104, v102

.LBB0_995:
	s_or_b64 exec, exec, s[12:13]
	global_load_dword v242, v[66:67], off
	global_load_dword v243, v[66:67], off offset:4
	global_load_dword v244, v[66:67], off offset:8
	global_load_dword v245, v[66:67], off offset:12
	s_waitcnt vmcnt(0)
	v_mov_b32_e32 v62, v242
	v_fmamk_f32 v62, v62, 0x3b800000, v216
	v_mul_f32_e32 v63, 0x4b800000, v62
	v_cmp_gt_f32_e32 vcc, s38, v62
	s_nop 1
	v_cndmask_b32_e32 v62, v62, v63, vcc
	v_rsq_f32_e32 v66, v62
	v_mov_b32_e32 v63, v0
	v_mov_b32_e32 v62, v16
	v_mul_f32_e32 v0, 0x45800000, v66
	v_cndmask_b32_e32 v0, v66, v0, vcc
	v_mul_f32_e32 v0, 0x3dd53b94, v0
	s_and_b64 vcc, exec, s[4:5]
	v_pk_mul_f32 v[62:63], v[62:63], v[0:1] op_sel_hi:[1,0]
	s_cbranch_vccnz .LBB0_997
	s_load_dwordx2 s[12:13], s[0:1], 0x148
	s_waitcnt lgkmcnt(0)
	v_lshl_add_u64 v[64:65], s[12:13], 0, v[64:65]
	v_lshl_add_u64 v[64:65], v[64:65], 0, v[160:161]
	global_load_dwordx2 v[246:247], v[64:65], off
	global_load_dwordx2 v[248:249], v[64:65], off offset:256
	global_load_dwordx2 v[250:251], v[64:65], off offset:512
	global_load_dwordx2 v[252:253], v[64:65], off offset:768
	s_waitcnt vmcnt(0)
	v_mov_b32_e32 v64, v246
	v_mov_b32_e32 v65, v247
	v_pk_mul_f32 v[66:67], v[62:63], v[64:65] op_sel_hi:[0,1]
	v_pk_mul_f32 v[108:109], v[62:63], v[64:65] op_sel:[1,1] op_sel_hi:[1,0]
	v_pk_fma_f32 v[62:63], v[62:63], v[64:65], v[66:67] op_sel:[1,1,0] op_sel_hi:[1,0,1] neg_lo:[0,0,1] neg_hi:[0,0,1]
	s_nop 0
	v_add_f32_e32 v62, v108, v66
.LBB0_997:
	v_mov_b32_e32 v0, v243
	v_cvt_pk_bf16_f32 v16, v63, s0
	v_cvt_pk_bf16_f32 v62, v62, s0
	ds_write_b16 v217, v16
	ds_write_b16 v217, v62 offset:64
	s_waitcnt vmcnt(0)
	v_fmamk_f32 v0, v0, 0x3b800000, v216
	v_mul_f32_e32 v63, 0x4b800000, v0
	v_cmp_gt_f32_e32 vcc, s38, v0
	s_nop 1
	v_cndmask_b32_e32 v0, v0, v63, vcc
	v_rsq_f32_e32 v63, v0
	v_mov_b32_e32 v0, v17
	v_mul_f32_e32 v16, 0x45800000, v63
	v_cndmask_b32_e32 v16, v63, v16, vcc
	v_mul_f32_e32 v16, 0x3dd53b94, v16
	s_and_b64 vcc, exec, s[4:5]
	v_pk_mul_f32 v[0:1], v[0:1], v[16:17] op_sel_hi:[1,0]
	s_cbranch_vccnz .LBB0_999
	s_load_dwordx2 s[12:13], s[0:1], 0x148
	s_waitcnt lgkmcnt(0)
	v_lshl_add_u64 v[16:17], s[12:13], 0, v[32:33]
	v_lshl_add_u64 v[16:17], v[16:17], 0, v[160:161]
	v_mov_b32_e32 v16, v248
	v_mov_b32_e32 v17, v249
	s_waitcnt vmcnt(0)
	v_pk_mul_f32 v[32:33], v[0:1], v[16:17] op_sel_hi:[0,1]
	v_pk_mul_f32 v[62:63], v[0:1], v[16:17] op_sel:[1,1] op_sel_hi:[1,0]
	v_pk_fma_f32 v[0:1], v[0:1], v[16:17], v[32:33] op_sel:[1,1,0] op_sel_hi:[1,0,1] neg_lo:[0,0,1] neg_hi:[0,0,1]
	s_nop 0
	v_add_f32_e32 v0, v62, v32
.LBB0_999:
	v_mov_b32_e32 v16, v244
	v_cvt_pk_bf16_f32 v17, v1, s0
	v_cvt_pk_bf16_f32 v32, v0, s0
	v_mov_b32_e32 v0, v18
	ds_write_b16 v217, v17 offset:144
	ds_write_b16 v217, v32 offset:208
	s_waitcnt vmcnt(0)
	v_fmamk_f32 v1, v16, 0x3b800000, v216
	v_mul_f32_e32 v16, 0x4b800000, v1
	v_cmp_gt_f32_e32 vcc, s38, v1
	s_nop 1
	v_cndmask_b32_e32 v1, v1, v16, vcc
	v_rsq_f32_e32 v16, v1
	v_mov_b32_e32 v1, v2
	v_mul_f32_e32 v2, 0x45800000, v16
	v_cndmask_b32_e32 v2, v16, v2, vcc
	v_mul_f32_e32 v2, 0x3dd53b94, v2
	s_and_b64 vcc, exec, s[4:5]
	v_pk_mul_f32 v[0:1], v[0:1], v[2:3] op_sel_hi:[1,0]
	s_cbranch_vccnz .LBB0_1001
	s_load_dwordx2 s[12:13], s[0:1], 0x148
	s_waitcnt lgkmcnt(0)
	v_lshl_add_u64 v[16:17], s[12:13], 0, v[48:49]
	v_lshl_add_u64 v[16:17], v[16:17], 0, v[160:161]
	v_mov_b32_e32 v16, v250
	v_mov_b32_e32 v17, v251
	s_waitcnt vmcnt(0)
	v_pk_mul_f32 v[32:33], v[0:1], v[16:17] op_sel_hi:[0,1]
	v_pk_mul_f32 v[48:49], v[0:1], v[16:17] op_sel:[1,1] op_sel_hi:[1,0]
	v_pk_fma_f32 v[0:1], v[0:1], v[16:17], v[32:33] op_sel:[1,1,0] op_sel_hi:[1,0,1] neg_lo:[0,0,1] neg_hi:[0,0,1]
	s_nop 0
	v_add_f32_e32 v0, v48, v32
.LBB0_1001:
	v_mov_b32_e32 v2, v245
	v_cvt_pk_bf16_f32 v1, v1, s0
	v_cvt_pk_bf16_f32 v0, v0, s0
	ds_write_b16 v217, v1 offset:288
	ds_write_b16 v217, v0 offset:352
	s_waitcnt vmcnt(0)
	v_fmamk_f32 v2, v2, 0x3b800000, v216
	v_mul_f32_e32 v16, 0x4b800000, v2
	v_cmp_gt_f32_e32 vcc, s38, v2
	s_nop 1
	v_cndmask_b32_e32 v2, v2, v16, vcc
	v_rsq_f32_e32 v16, v2
	v_mov_b32_e32 v2, v19
	v_mul_f32_e32 v0, 0x45800000, v16
	v_cndmask_b32_e32 v0, v16, v0, vcc
	v_mul_f32_e32 v0, 0x3dd53b94, v0
	s_and_b64 vcc, exec, s[4:5]
	v_pk_mul_f32 v[0:1], v[2:3], v[0:1] op_sel_hi:[1,0]
	s_cbranch_vccnz .LBB0_1003
	s_load_dwordx2 s[12:13], s[0:1], 0x148
	s_waitcnt lgkmcnt(0)
	v_lshl_add_u64 v[2:3], s[12:13], 0, v[34:35]
	v_lshl_add_u64 v[2:3], v[2:3], 0, v[160:161]
	v_mov_b32_e32 v2, v252
	v_mov_b32_e32 v3, v253
	s_waitcnt vmcnt(0)
	v_pk_mul_f32 v[16:17], v[0:1], v[2:3] op_sel_hi:[0,1]
	v_pk_mul_f32 v[18:19], v[0:1], v[2:3] op_sel:[1,1] op_sel_hi:[1,0]
	v_pk_fma_f32 v[0:1], v[0:1], v[2:3], v[16:17] op_sel:[1,1,0] op_sel_hi:[1,0,1] neg_lo:[0,0,1] neg_hi:[0,0,1]
	s_nop 0
	v_add_f32_e32 v0, v18, v16
.LBB0_1003:
	global_load_dword v242, v[74:75], off
	global_load_dword v243, v[74:75], off offset:4
	global_load_dword v244, v[74:75], off offset:8
	global_load_dword v245, v[74:75], off offset:12
	v_cvt_pk_bf16_f32 v3, v1, s0
	v_cvt_pk_bf16_f32 v16, v0, s0
	ds_write_b16 v217, v3 offset:432
	ds_write_b16 v217, v16 offset:496
	v_mov_b32_e32 v0, v20
	s_waitcnt vmcnt(0)
	v_mov_b32_e32 v2, v242
	v_fmamk_f32 v1, v2, 0x3b800000, v216
	v_mul_f32_e32 v2, 0x4b800000, v1
	v_cmp_gt_f32_e32 vcc, s38, v1
	s_nop 1
	v_cndmask_b32_e32 v1, v1, v2, vcc
	v_rsq_f32_e32 v2, v1
	v_mov_b32_e32 v1, v4
	v_mul_f32_e32 v3, 0x45800000, v2
	v_cndmask_b32_e32 v2, v2, v3, vcc
	v_mul_f32_e32 v2, 0x3dd53b94, v2
	s_and_b64 vcc, exec, s[4:5]
	v_pk_mul_f32 v[0:1], v[0:1], v[2:3] op_sel_hi:[1,0]
	s_cbranch_vccnz .LBB0_1005
	s_load_dwordx2 s[12:13], s[0:1], 0x148
	s_waitcnt lgkmcnt(0)
	v_lshl_add_u64 v[2:3], s[12:13], 0, v[50:51]
	v_lshl_add_u64 v[2:3], v[2:3], 0, v[160:161]
	global_load_dwordx2 v[246:247], v[2:3], off
	global_load_dwordx2 v[248:249], v[2:3], off offset:256
	global_load_dwordx2 v[250:251], v[2:3], off offset:512
	global_load_dwordx2 v[252:253], v[2:3], off offset:768
	s_waitcnt vmcnt(0)
	v_mov_b32_e32 v2, v246
	v_mov_b32_e32 v3, v247
	v_pk_mul_f32 v[16:17], v[0:1], v[2:3] op_sel_hi:[0,1]
	v_pk_mul_f32 v[18:19], v[0:1], v[2:3] op_sel:[1,1] op_sel_hi:[1,0]
	v_pk_fma_f32 v[0:1], v[0:1], v[2:3], v[16:17] op_sel:[1,1,0] op_sel_hi:[1,0,1] neg_lo:[0,0,1] neg_hi:[0,0,1]
	s_nop 0
	v_add_f32_e32 v0, v18, v16
.LBB0_1005:
	v_mov_b32_e32 v2, v243
	v_cvt_pk_bf16_f32 v1, v1, s0
	v_cvt_pk_bf16_f32 v0, v0, s0
	ds_write_b16 v217, v1 offset:1152
	ds_write_b16 v217, v0 offset:1216
	v_mov_b32_e32 v4, v21
	s_waitcnt vmcnt(0)
	v_fmamk_f32 v2, v2, 0x3b800000, v216
	v_mul_f32_e32 v3, 0x4b800000, v2
	v_cmp_gt_f32_e32 vcc, s38, v2
	s_nop 1
	v_cndmask_b32_e32 v2, v2, v3, vcc
	v_rsq_f32_e32 v2, v2
	s_nop 0
	v_mul_f32_e32 v0, 0x45800000, v2
	v_cndmask_b32_e32 v0, v2, v0, vcc
	v_mul_f32_e32 v0, 0x3dd53b94, v0
	s_and_b64 vcc, exec, s[4:5]
	v_pk_mul_f32 v[0:1], v[4:5], v[0:1] op_sel_hi:[1,0]
	s_cbranch_vccnz .LBB0_1007
	s_load_dwordx2 s[12:13], s[0:1], 0x148
	s_waitcnt lgkmcnt(0)
	v_lshl_add_u64 v[2:3], s[12:13], 0, v[36:37]
	v_lshl_add_u64 v[2:3], v[2:3], 0, v[160:161]
	v_mov_b32_e32 v2, v248
	v_mov_b32_e32 v3, v249
	s_waitcnt vmcnt(0)
	v_pk_mul_f32 v[4:5], v[0:1], v[2:3] op_sel_hi:[0,1]
	v_pk_mul_f32 v[16:17], v[0:1], v[2:3] op_sel:[1,1] op_sel_hi:[1,0]
	v_pk_fma_f32 v[0:1], v[0:1], v[2:3], v[4:5] op_sel:[1,1,0] op_sel_hi:[1,0,1] neg_lo:[0,0,1] neg_hi:[0,0,1]
	s_nop 0
	v_add_f32_e32 v0, v16, v4
.LBB0_1007:
	v_mov_b32_e32 v2, v244
	v_cvt_pk_bf16_f32 v3, v1, s0
	v_cvt_pk_bf16_f32 v4, v0, s0
	ds_write_b16 v217, v3 offset:1296
	ds_write_b16 v217, v4 offset:1360
	v_mov_b32_e32 v0, v22
	s_waitcnt vmcnt(0)
	v_fmamk_f32 v1, v2, 0x3b800000, v216
	v_mul_f32_e32 v2, 0x4b800000, v1
	v_cmp_gt_f32_e32 vcc, s38, v1
	s_nop 1
	v_cndmask_b32_e32 v1, v1, v2, vcc
	v_rsq_f32_e32 v2, v1
	v_mov_b32_e32 v1, v6
	v_mul_f32_e32 v3, 0x45800000, v2
	v_cndmask_b32_e32 v2, v2, v3, vcc
	v_mul_f32_e32 v2, 0x3dd53b94, v2
	s_and_b64 vcc, exec, s[4:5]
	v_pk_mul_f32 v[0:1], v[0:1], v[2:3] op_sel_hi:[1,0]
	s_cbranch_vccnz .LBB0_1009
	s_load_dwordx2 s[12:13], s[0:1], 0x148
	s_waitcnt lgkmcnt(0)
	v_lshl_add_u64 v[2:3], s[12:13], 0, v[52:53]
	v_lshl_add_u64 v[2:3], v[2:3], 0, v[160:161]
	v_mov_b32_e32 v2, v250
	v_mov_b32_e32 v3, v251
	s_waitcnt vmcnt(0)
	v_pk_mul_f32 v[4:5], v[0:1], v[2:3] op_sel_hi:[0,1]
	v_pk_mul_f32 v[16:17], v[0:1], v[2:3] op_sel:[1,1] op_sel_hi:[1,0]
	v_pk_fma_f32 v[0:1], v[0:1], v[2:3], v[4:5] op_sel:[1,1,0] op_sel_hi:[1,0,1] neg_lo:[0,0,1] neg_hi:[0,0,1]
	s_nop 0
	v_add_f32_e32 v0, v16, v4
.LBB0_1009:
	v_mov_b32_e32 v2, v245
	v_cvt_pk_bf16_f32 v1, v1, s0
	v_cvt_pk_bf16_f32 v0, v0, s0
	ds_write_b16 v217, v1 offset:1440
	ds_write_b16 v217, v0 offset:1504
	v_mov_b32_e32 v6, v23
	s_waitcnt vmcnt(0)
	v_fmamk_f32 v2, v2, 0x3b800000, v216
	v_mul_f32_e32 v3, 0x4b800000, v2
	v_cmp_gt_f32_e32 vcc, s38, v2
	s_nop 1
	v_cndmask_b32_e32 v2, v2, v3, vcc
	v_rsq_f32_e32 v2, v2
	s_nop 0
	v_mul_f32_e32 v0, 0x45800000, v2
	v_cndmask_b32_e32 v0, v2, v0, vcc
	v_mul_f32_e32 v0, 0x3dd53b94, v0
	s_and_b64 vcc, exec, s[4:5]
	v_pk_mul_f32 v[0:1], v[6:7], v[0:1] op_sel_hi:[1,0]
	s_cbranch_vccnz .LBB0_1011
	s_load_dwordx2 s[12:13], s[0:1], 0x148
	s_waitcnt lgkmcnt(0)
	v_lshl_add_u64 v[2:3], s[12:13], 0, v[38:39]
	v_lshl_add_u64 v[2:3], v[2:3], 0, v[160:161]
	v_mov_b32_e32 v2, v252
	v_mov_b32_e32 v3, v253
	s_waitcnt vmcnt(0)
	v_pk_mul_f32 v[4:5], v[0:1], v[2:3] op_sel_hi:[0,1]
	v_pk_mul_f32 v[6:7], v[0:1], v[2:3] op_sel:[1,1] op_sel_hi:[1,0]
	v_pk_fma_f32 v[0:1], v[0:1], v[2:3], v[4:5] op_sel:[1,1,0] op_sel_hi:[1,0,1] neg_lo:[0,0,1] neg_hi:[0,0,1]
	s_nop 0
	v_add_f32_e32 v0, v6, v4
.LBB0_1011:
	global_load_dword v242, v[82:83], off
	global_load_dword v243, v[82:83], off offset:4
	global_load_dword v244, v[82:83], off offset:8
	global_load_dword v245, v[82:83], off offset:12
	v_cvt_pk_bf16_f32 v3, v1, s0
	v_cvt_pk_bf16_f32 v4, v0, s0
	ds_write_b16 v217, v3 offset:1584
	ds_write_b16 v217, v4 offset:1648
	v_mov_b32_e32 v0, v24
	s_waitcnt vmcnt(0)
	v_mov_b32_e32 v2, v242
	v_fmamk_f32 v1, v2, 0x3b800000, v216
	v_mul_f32_e32 v2, 0x4b800000, v1
	v_cmp_gt_f32_e32 vcc, s38, v1
	s_nop 1
	v_cndmask_b32_e32 v1, v1, v2, vcc
	v_rsq_f32_e32 v2, v1
	v_mov_b32_e32 v1, v8
	v_mul_f32_e32 v3, 0x45800000, v2
	v_cndmask_b32_e32 v2, v2, v3, vcc
	v_mul_f32_e32 v2, 0x3dd53b94, v2
	s_and_b64 vcc, exec, s[4:5]
	v_pk_mul_f32 v[0:1], v[0:1], v[2:3] op_sel_hi:[1,0]
	s_cbranch_vccnz .LBB0_1013
	s_load_dwordx2 s[12:13], s[0:1], 0x148
	s_waitcnt lgkmcnt(0)
	v_lshl_add_u64 v[2:3], s[12:13], 0, v[54:55]
	v_lshl_add_u64 v[2:3], v[2:3], 0, v[160:161]
	global_load_dwordx2 v[246:247], v[2:3], off
	global_load_dwordx2 v[248:249], v[2:3], off offset:256
	global_load_dwordx2 v[250:251], v[2:3], off offset:512
	global_load_dwordx2 v[252:253], v[2:3], off offset:768
	s_waitcnt vmcnt(0)
	v_mov_b32_e32 v2, v246
	v_mov_b32_e32 v3, v247
	v_pk_mul_f32 v[4:5], v[0:1], v[2:3] op_sel_hi:[0,1]
	v_pk_mul_f32 v[6:7], v[0:1], v[2:3] op_sel:[1,1] op_sel_hi:[1,0]
	v_pk_fma_f32 v[0:1], v[0:1], v[2:3], v[4:5] op_sel:[1,1,0] op_sel_hi:[1,0,1] neg_lo:[0,0,1] neg_hi:[0,0,1]
	s_nop 0
	v_add_f32_e32 v0, v6, v4
.LBB0_1013:
	v_mov_b32_e32 v2, v243
	v_cvt_pk_bf16_f32 v1, v1, s0
	v_cvt_pk_bf16_f32 v0, v0, s0
	ds_write_b16 v217, v1 offset:2304
	ds_write_b16 v217, v0 offset:2368
	v_mov_b32_e32 v8, v25
	s_waitcnt vmcnt(0)
	v_fmamk_f32 v2, v2, 0x3b800000, v216
	v_mul_f32_e32 v3, 0x4b800000, v2
	v_cmp_gt_f32_e32 vcc, s38, v2
	s_nop 1
	v_cndmask_b32_e32 v2, v2, v3, vcc
	v_rsq_f32_e32 v2, v2
	s_nop 0
	v_mul_f32_e32 v0, 0x45800000, v2
	v_cndmask_b32_e32 v0, v2, v0, vcc
	v_mul_f32_e32 v0, 0x3dd53b94, v0
	s_and_b64 vcc, exec, s[4:5]
	v_pk_mul_f32 v[0:1], v[8:9], v[0:1] op_sel_hi:[1,0]
	s_cbranch_vccnz .LBB0_1015
	s_load_dwordx2 s[12:13], s[0:1], 0x148
	s_waitcnt lgkmcnt(0)
	v_lshl_add_u64 v[2:3], s[12:13], 0, v[40:41]
	v_lshl_add_u64 v[2:3], v[2:3], 0, v[160:161]
	v_mov_b32_e32 v2, v248
	v_mov_b32_e32 v3, v249
	s_waitcnt vmcnt(0)
	v_pk_mul_f32 v[4:5], v[0:1], v[2:3] op_sel_hi:[0,1]
	v_pk_mul_f32 v[6:7], v[0:1], v[2:3] op_sel:[1,1] op_sel_hi:[1,0]
	v_pk_fma_f32 v[0:1], v[0:1], v[2:3], v[4:5] op_sel:[1,1,0] op_sel_hi:[1,0,1] neg_lo:[0,0,1] neg_hi:[0,0,1]
	s_nop 0
	v_add_f32_e32 v0, v6, v4
.LBB0_1015:
	v_mov_b32_e32 v2, v244
	v_cvt_pk_bf16_f32 v3, v1, s0
	v_cvt_pk_bf16_f32 v4, v0, s0
	ds_write_b16 v217, v3 offset:2448
	ds_write_b16 v217, v4 offset:2512
	v_mov_b32_e32 v0, v26
	s_waitcnt vmcnt(0)
	v_fmamk_f32 v1, v2, 0x3b800000, v216
	v_mul_f32_e32 v2, 0x4b800000, v1
	v_cmp_gt_f32_e32 vcc, s38, v1
	s_nop 1
	v_cndmask_b32_e32 v1, v1, v2, vcc
	v_rsq_f32_e32 v2, v1
	v_mov_b32_e32 v1, v10
	v_mul_f32_e32 v3, 0x45800000, v2
	v_cndmask_b32_e32 v2, v2, v3, vcc
	v_mul_f32_e32 v2, 0x3dd53b94, v2
	s_and_b64 vcc, exec, s[4:5]
	v_pk_mul_f32 v[0:1], v[0:1], v[2:3] op_sel_hi:[1,0]
	s_cbranch_vccnz .LBB0_1017
	s_load_dwordx2 s[12:13], s[0:1], 0x148
	s_waitcnt lgkmcnt(0)
	v_lshl_add_u64 v[2:3], s[12:13], 0, v[56:57]
	v_lshl_add_u64 v[2:3], v[2:3], 0, v[160:161]
	v_mov_b32_e32 v2, v250
	v_mov_b32_e32 v3, v251
	s_waitcnt vmcnt(0)
	v_pk_mul_f32 v[4:5], v[0:1], v[2:3] op_sel_hi:[0,1]
	v_pk_mul_f32 v[6:7], v[0:1], v[2:3] op_sel:[1,1] op_sel_hi:[1,0]
	v_pk_fma_f32 v[0:1], v[0:1], v[2:3], v[4:5] op_sel:[1,1,0] op_sel_hi:[1,0,1] neg_lo:[0,0,1] neg_hi:[0,0,1]
	s_nop 0
	v_add_f32_e32 v0, v6, v4
.LBB0_1017:
	v_mov_b32_e32 v2, v245
	v_cvt_pk_bf16_f32 v1, v1, s0
	v_cvt_pk_bf16_f32 v0, v0, s0
	ds_write_b16 v217, v1 offset:2592
	ds_write_b16 v217, v0 offset:2656
	v_mov_b32_e32 v10, v27
	s_waitcnt vmcnt(0)
	v_fmamk_f32 v2, v2, 0x3b800000, v216
	v_mul_f32_e32 v3, 0x4b800000, v2
	v_cmp_gt_f32_e32 vcc, s38, v2
	s_nop 1
	v_cndmask_b32_e32 v2, v2, v3, vcc
	v_rsq_f32_e32 v2, v2
	s_nop 0
	v_mul_f32_e32 v0, 0x45800000, v2
	v_cndmask_b32_e32 v0, v2, v0, vcc
	v_mul_f32_e32 v0, 0x3dd53b94, v0
	s_and_b64 vcc, exec, s[4:5]
	v_pk_mul_f32 v[0:1], v[10:11], v[0:1] op_sel_hi:[1,0]
	s_cbranch_vccnz .LBB0_1019
	s_load_dwordx2 s[12:13], s[0:1], 0x148
	s_waitcnt lgkmcnt(0)
	v_lshl_add_u64 v[2:3], s[12:13], 0, v[42:43]
	v_lshl_add_u64 v[2:3], v[2:3], 0, v[160:161]
	v_mov_b32_e32 v2, v252
	v_mov_b32_e32 v3, v253
	s_waitcnt vmcnt(0)
	v_pk_mul_f32 v[4:5], v[0:1], v[2:3] op_sel_hi:[0,1]
	v_pk_mul_f32 v[6:7], v[0:1], v[2:3] op_sel:[1,1] op_sel_hi:[1,0]
	v_pk_fma_f32 v[0:1], v[0:1], v[2:3], v[4:5] op_sel:[1,1,0] op_sel_hi:[1,0,1] neg_lo:[0,0,1] neg_hi:[0,0,1]
	s_nop 0
	v_add_f32_e32 v0, v6, v4
.LBB0_1019:
	global_load_dword v242, v[90:91], off
	global_load_dword v243, v[90:91], off offset:4
	global_load_dword v244, v[90:91], off offset:8
	global_load_dword v245, v[90:91], off offset:12
	v_cvt_pk_bf16_f32 v3, v1, s0
	v_cvt_pk_bf16_f32 v4, v0, s0
	ds_write_b16 v217, v3 offset:2736
	ds_write_b16 v217, v4 offset:2800
	v_mov_b32_e32 v0, v28
	s_waitcnt vmcnt(0)
	v_mov_b32_e32 v2, v242
	v_fmamk_f32 v1, v2, 0x3b800000, v216
	v_mul_f32_e32 v2, 0x4b800000, v1
	v_cmp_gt_f32_e32 vcc, s38, v1
	s_nop 1
	v_cndmask_b32_e32 v1, v1, v2, vcc
	v_rsq_f32_e32 v2, v1
	v_mov_b32_e32 v1, v12
	v_mul_f32_e32 v3, 0x45800000, v2
	v_cndmask_b32_e32 v2, v2, v3, vcc
	v_mul_f32_e32 v2, 0x3dd53b94, v2
	s_and_b64 vcc, exec, s[4:5]
	v_pk_mul_f32 v[0:1], v[0:1], v[2:3] op_sel_hi:[1,0]
	s_cbranch_vccnz .LBB0_1021
	s_load_dwordx2 s[12:13], s[0:1], 0x148
	s_waitcnt lgkmcnt(0)
	v_lshl_add_u64 v[2:3], s[12:13], 0, v[58:59]
	v_lshl_add_u64 v[2:3], v[2:3], 0, v[160:161]
	global_load_dwordx2 v[246:247], v[2:3], off
	global_load_dwordx2 v[248:249], v[2:3], off offset:256
	global_load_dwordx2 v[250:251], v[2:3], off offset:512
	global_load_dwordx2 v[252:253], v[2:3], off offset:768
	s_waitcnt vmcnt(0)
	v_mov_b32_e32 v2, v246
	v_mov_b32_e32 v3, v247
	v_pk_mul_f32 v[4:5], v[0:1], v[2:3] op_sel_hi:[0,1]
	v_pk_mul_f32 v[6:7], v[0:1], v[2:3] op_sel:[1,1] op_sel_hi:[1,0]
	v_pk_fma_f32 v[0:1], v[0:1], v[2:3], v[4:5] op_sel:[1,1,0] op_sel_hi:[1,0,1] neg_lo:[0,0,1] neg_hi:[0,0,1]
	s_nop 0
	v_add_f32_e32 v0, v6, v4
.LBB0_1021:
	v_mov_b32_e32 v2, v243
	v_cvt_pk_bf16_f32 v1, v1, s0
	v_cvt_pk_bf16_f32 v0, v0, s0
	ds_write_b16 v217, v1 offset:3456
	ds_write_b16 v217, v0 offset:3520
	v_mov_b32_e32 v12, v29
	s_waitcnt vmcnt(0)
	v_fmamk_f32 v2, v2, 0x3b800000, v216
	v_mul_f32_e32 v3, 0x4b800000, v2
	v_cmp_gt_f32_e32 vcc, s38, v2
	s_nop 1
	v_cndmask_b32_e32 v2, v2, v3, vcc
	v_rsq_f32_e32 v2, v2
	s_nop 0
	v_mul_f32_e32 v0, 0x45800000, v2
	v_cndmask_b32_e32 v0, v2, v0, vcc
	v_mul_f32_e32 v0, 0x3dd53b94, v0
	s_and_b64 vcc, exec, s[4:5]
	v_pk_mul_f32 v[0:1], v[12:13], v[0:1] op_sel_hi:[1,0]
	s_cbranch_vccnz .LBB0_1023
	s_load_dwordx2 s[12:13], s[0:1], 0x148
	s_waitcnt lgkmcnt(0)
	v_lshl_add_u64 v[2:3], s[12:13], 0, v[44:45]
	v_lshl_add_u64 v[2:3], v[2:3], 0, v[160:161]
	v_mov_b32_e32 v2, v248
	v_mov_b32_e32 v3, v249
	s_waitcnt vmcnt(0)
	v_pk_mul_f32 v[4:5], v[0:1], v[2:3] op_sel_hi:[0,1]
	v_pk_mul_f32 v[6:7], v[0:1], v[2:3] op_sel:[1,1] op_sel_hi:[1,0]
	v_pk_fma_f32 v[0:1], v[0:1], v[2:3], v[4:5] op_sel:[1,1,0] op_sel_hi:[1,0,1] neg_lo:[0,0,1] neg_hi:[0,0,1]
	s_nop 0
	v_add_f32_e32 v0, v6, v4
.LBB0_1023:
	v_mov_b32_e32 v2, v244
	v_cvt_pk_bf16_f32 v3, v1, s0
	v_cvt_pk_bf16_f32 v4, v0, s0
	ds_write_b16 v217, v3 offset:3600
	ds_write_b16 v217, v4 offset:3664
	v_mov_b32_e32 v0, v30
	s_waitcnt vmcnt(0)
	v_fmamk_f32 v1, v2, 0x3b800000, v216
	v_mul_f32_e32 v2, 0x4b800000, v1
	v_cmp_gt_f32_e32 vcc, s38, v1
	s_nop 1
	v_cndmask_b32_e32 v1, v1, v2, vcc
	v_rsq_f32_e32 v2, v1
	v_mov_b32_e32 v1, v14
	v_mul_f32_e32 v3, 0x45800000, v2
	v_cndmask_b32_e32 v2, v2, v3, vcc
	v_mul_f32_e32 v2, 0x3dd53b94, v2
	s_and_b64 vcc, exec, s[4:5]
	v_pk_mul_f32 v[0:1], v[0:1], v[2:3] op_sel_hi:[1,0]
	s_cbranch_vccnz .LBB0_1025
	s_load_dwordx2 s[12:13], s[0:1], 0x148
	s_waitcnt lgkmcnt(0)
	v_lshl_add_u64 v[2:3], s[12:13], 0, v[60:61]
	v_lshl_add_u64 v[2:3], v[2:3], 0, v[160:161]
	v_mov_b32_e32 v2, v250
	v_mov_b32_e32 v3, v251
	s_waitcnt vmcnt(0)
	v_pk_mul_f32 v[4:5], v[0:1], v[2:3] op_sel_hi:[0,1]
	v_pk_mul_f32 v[6:7], v[0:1], v[2:3] op_sel:[1,1] op_sel_hi:[1,0]
	v_pk_fma_f32 v[0:1], v[0:1], v[2:3], v[4:5] op_sel:[1,1,0] op_sel_hi:[1,0,1] neg_lo:[0,0,1] neg_hi:[0,0,1]
	s_nop 0
	v_add_f32_e32 v0, v6, v4
.LBB0_1025:
	v_mov_b32_e32 v2, v245
	v_cvt_pk_bf16_f32 v1, v1, s0
	v_cvt_pk_bf16_f32 v0, v0, s0
	ds_write_b16 v217, v1 offset:3744
	ds_write_b16 v217, v0 offset:3808
	v_mov_b32_e32 v14, v31
	s_waitcnt vmcnt(0)
	v_fmamk_f32 v2, v2, 0x3b800000, v216
	v_mul_f32_e32 v3, 0x4b800000, v2
	v_cmp_gt_f32_e32 vcc, s38, v2
	s_nop 1
	v_cndmask_b32_e32 v2, v2, v3, vcc
	v_rsq_f32_e32 v2, v2
	s_nop 0
	v_mul_f32_e32 v0, 0x45800000, v2
	v_cndmask_b32_e32 v0, v2, v0, vcc
	v_mul_f32_e32 v0, 0x3dd53b94, v0
	s_and_b64 vcc, exec, s[4:5]
	v_pk_mul_f32 v[0:1], v[14:15], v[0:1] op_sel_hi:[1,0]
	s_cbranch_vccnz .LBB0_1027
	s_load_dwordx2 s[4:5], s[0:1], 0x148
	s_waitcnt lgkmcnt(0)
	v_lshl_add_u64 v[2:3], s[4:5], 0, v[46:47]
	v_lshl_add_u64 v[2:3], v[2:3], 0, v[160:161]
	v_mov_b32_e32 v2, v252
	v_mov_b32_e32 v3, v253
	s_waitcnt vmcnt(0)
	v_pk_mul_f32 v[4:5], v[0:1], v[2:3] op_sel_hi:[0,1]
	v_pk_mul_f32 v[6:7], v[0:1], v[2:3] op_sel:[1,1] op_sel_hi:[1,0]
	v_pk_fma_f32 v[0:1], v[0:1], v[2:3], v[4:5] op_sel:[1,1,0] op_sel_hi:[1,0,1] neg_lo:[0,0,1] neg_hi:[0,0,1]
	s_nop 0
	v_add_f32_e32 v0, v6, v4

.LBB0_1194:
	s_cmp_gt_i32 s44, 4
	s_waitcnt lgkmcnt(0)
	s_cselect_b64 s[2:3], -1, 0
	s_cmp_lt_i32 s45, 5
	s_cselect_b64 s[4:5], -1, 0
	s_or_b64 s[2:3], s[2:3], s[4:5]
	s_and_b64 vcc, exec, s[2:3]
	s_cbranch_vccnz .LBB0_1267
	s_cmp_lt_u32 s70, 256
	s_cbranch_scc1 .Lprio_skip_4
	s_setprio 3
.Lprio_skip_4:
	v_mbcnt_hi_u32_b32 v178, -1, v210
	v_mov_b32_e32 v0, v178
	s_mov_b32 s3, 0
	v_add_u32_e32 v1, s70, v0
	s_cmpk_gt_i32 s22, 0x3ff
	v_readfirstlane_b32 s2, v1
	s_cbranch_scc1 .LBB0_1213
	s_abs_i32 s29, s42
	v_cvt_f32_u32_e32 v1, s29
	s_ashr_i32 s26, s42, 31
	s_lshr_b32 s4, s26, 26
	s_add_i32 s4, s42, s4
	v_rcp_iflag_f32_e32 v1, v1
	s_ashr_i32 s27, s4, 6
	s_load_dwordx4 s[4:7], s[0:1], 0x178
	s_load_dwordx2 s[12:13], s[0:1], 0x188
	s_ashr_i32 s28, s2, 1
	v_mul_f32_e32 v1, 0x4f7ffffe, v1
	v_cvt_u32_f32_e32 v1, v1
	s_sub_i32 s2, 0, s29
	s_andn2_b32 s28, s28, 31
	v_and_b32_e32 v4, 64, v178
	v_readfirstlane_b32 s8, v1
	s_mul_i32 s2, s2, s8
	s_mul_hi_u32 s2, s8, s2
	s_add_i32 s30, s8, s2
	v_xor_b32_e32 v3, 32, v178
	v_add_u32_e32 v4, 64, v4
	s_waitcnt lgkmcnt(0)
	s_add_u32 s16, s12, 0x4000
	v_and_b32_e32 v179, 31, v0
	v_lshrrev_b32_e32 v0, 2, v0
	v_cmp_lt_i32_e32 vcc, v3, v4
	s_addc_u32 s17, s13, 0
	v_and_b32_e32 v2, 8, v0
	v_mov_b32_e32 v0, 0
	v_cndmask_b32_e32 v3, v178, v3, vcc
	s_add_u32 s20, s6, 0x6000
	v_lshlrev_b32_e32 v180, 2, v3
	s_mov_b64 s[14:15], 0x4000
	s_mov_b64 s[18:19], 0x6000
	s_addc_u32 s21, s7, 0
	s_movk_i32 s31, 0x180
	v_lshlrev_b32_e32 v166, 1, v2
	v_mov_b32_e32 v167, v0
	s_movk_i32 s34, 0x2000
	s_movk_i32 s35, 0x4000
	s_mov_b32 s36, 0x2aaaaaab
	s_movk_i32 s37, 0xffe8
	s_movk_i32 s38, 0x190
	s_movk_i32 s39, 0x140
	s_mov_b32 s48, 0xff800000
	s_movk_i32 s49, 0x90
	s_mov_b32 s50, 0x5040100
	v_mov_b32_e32 v181, 0x180000
	v_mov_b32_e32 v182, 0xff800000
	s_mov_b32 s51, s22
	s_branch .LBB0_1198

.LBB0_1213:
	s_setprio 0
	s_cmp_lt_i32 s45, 6
	s_cbranch_scc1 .LBB0_1267
	s_waitcnt vmcnt(0)
	v_cmp_eq_u32_e32 vcc, 0, v178
	s_and_b64 s[4:5], s[46:47], vcc
	s_waitcnt vmcnt(63) expcnt(7) lgkmcnt(15)
	s_barrier
	s_and_saveexec_b64 s[2:3], s[4:5]
	s_cbranch_execz .LBB0_1266
	v_mov_b32_e32 v0, 0x24400
	s_waitcnt vmcnt(0) expcnt(0) lgkmcnt(0)
	ds_read_b32 v2, v0
	v_mov_b32_e32 v0, 0x24404
	ds_read_b32 v0, v0
	s_waitcnt lgkmcnt(1)
	v_cmp_ne_u32_e32 vcc, 0, v2
	s_cbranch_vccnz .LBB0_1230
	s_add_u32 s4, s40, 0x1000
	s_addc_u32 s5, s41, 0
	s_add_u32 s6, s40, 0x1100
	s_addc_u32 s7, s41, 0
	s_add_u32 s8, s40, 0x1200
	s_addc_u32 s9, s41, 0
	s_mul_i32 s18, s43, s33
	s_add_u32 s10, s40, 0x1300
	s_mul_i32 s18, s18, s42
	s_addc_u32 s11, s41, 0
	s_mov_b32 s19, 1
	v_mov_b32_e32 v16, 0
	s_branch .LBB0_1218

.LBB0_1474:
	v_ashrrev_i32_e32 v207, 3, v160
	v_and_b32_e32 v208, -4, v207
	s_add_i32 s77, s77, s65
	v_add_u32_e32 v209, s77, v208
	v_and_b32_e32 v175, 31, v160
	v_min_i32_e32 v176, 0x7fff, v209
	v_cndmask_b32_e64 v174, 1.0, v206, s[4:5]
	s_andn2_b64 vcc, exec, s[6:7]
	v_ashrrev_i32_e32 v177, 31, v176
	v_lshlrev_b32_e32 v172, 3, v175
	s_cbranch_vccnz .LBB0_1476
	s_load_dwordx2 s[4:5], s[0:1], 0x148
	v_lshlrev_b64 v[178:179], 8, v[176:177]
	v_mov_b32_e32 v173, v161
	s_waitcnt lgkmcnt(0)
	v_lshl_add_u64 v[178:179], s[4:5], 0, v[178:179]
	v_lshl_add_u64 v[178:179], v[178:179], 0, v[172:173]
	global_load_dwordx2 v[128:129], v[178:179], off
	global_load_dwordx2 v[130:131], v[178:179], off offset:256
	global_load_dwordx2 v[132:133], v[178:179], off offset:512
	global_load_dwordx2 v[134:135], v[178:179], off offset:768
	global_load_dwordx2 v[136:137], v[178:179], off offset:2048
	global_load_dwordx2 v[138:139], v[178:179], off offset:2304
	global_load_dwordx2 v[140:141], v[178:179], off offset:2560
	global_load_dwordx2 v[142:143], v[178:179], off offset:2816
	s_mov_b64 s[98:99], 0x1000
	v_lshl_add_u64 v[158:159], v[178:179], 0, s[98:99]
	global_load_dwordx2 v[144:145], v[158:159], off offset:0
	global_load_dwordx2 v[146:147], v[158:159], off offset:256
	global_load_dwordx2 v[148:149], v[158:159], off offset:512
	global_load_dwordx2 v[150:151], v[158:159], off offset:768
	global_load_dwordx2 v[152:153], v[158:159], off offset:2048
	global_load_dwordx2 v[154:155], v[158:159], off offset:2304
	global_load_dwordx2 v[156:157], v[158:159], off offset:2560
	global_load_dwordx2 v[158:159], v[158:159], off offset:2816
	s_waitcnt vmcnt(0)
	v_mov_b32_e32 v178, v128
	v_mov_b32_e32 v179, v129
	v_pk_mul_f32 v[180:181], v[96:97], v[178:179] op_sel:[0,1] op_sel_hi:[0,0]
	v_pk_fma_f32 v[182:183], v[112:113], v[178:179], v[180:181] neg_lo:[0,0,1] neg_hi:[0,0,1]
	v_pk_fma_f32 v[178:179], v[112:113], v[178:179], v[180:181] op_sel_hi:[0,1,1]
	v_mov_b32_e32 v183, v179
	v_pk_mul_f32 v[178:179], v[174:175], v[182:183] op_sel_hi:[0,1]

.LBB0_1480:
	v_or_b32_e32 v173, 1, v209
	s_andn2_b64 vcc, exec, s[4:5]
	v_min_i32_e32 v178, 0x7fff, v173
	s_cbranch_vccnz .LBB0_1482
	s_load_dwordx2 s[4:5], s[0:1], 0x148
	v_ashrrev_i32_e32 v179, 31, v178
	v_lshlrev_b64 v[180:181], 8, v[178:179]
	v_mov_b32_e32 v173, v161
	s_waitcnt lgkmcnt(0)
	v_lshl_add_u64 v[180:181], s[4:5], 0, v[180:181]
	v_lshl_add_u64 v[180:181], v[180:181], 0, v[172:173]
	v_mov_b32_e32 v180, v130
	v_mov_b32_e32 v181, v131
	s_waitcnt vmcnt(0)
	v_pk_mul_f32 v[96:97], v[96:97], v[180:181] op_sel:[1,1] op_sel_hi:[1,0]
	s_nop 0
	v_pk_fma_f32 v[182:183], v[112:113], v[180:181], v[96:97] op_sel:[1,0,0] neg_lo:[0,0,1] neg_hi:[0,0,1]
	v_pk_fma_f32 v[96:97], v[112:113], v[180:181], v[96:97] op_sel:[1,0,0]
	s_nop 0
	v_mov_b32_e32 v183, v97
	v_pk_mul_f32 v[180:181], v[174:175], v[182:183] op_sel_hi:[0,1]

.LBB0_1486:
	v_or_b32_e32 v112, 2, v209
	s_andn2_b64 vcc, exec, s[4:5]
	v_min_i32_e32 v112, 0x7fff, v112
	s_cbranch_vccnz .LBB0_1488
	s_load_dwordx2 s[4:5], s[0:1], 0x148
	v_ashrrev_i32_e32 v113, 31, v112
	v_lshlrev_b64 v[96:97], 8, v[112:113]
	v_mov_b32_e32 v173, v161
	s_waitcnt lgkmcnt(0)
	v_lshl_add_u64 v[96:97], s[4:5], 0, v[96:97]
	v_lshl_add_u64 v[96:97], v[96:97], 0, v[172:173]
	v_mov_b32_e32 v96, v132
	v_mov_b32_e32 v97, v133
	s_waitcnt vmcnt(0)
	v_pk_mul_f32 v[180:181], v[98:99], v[96:97] op_sel:[0,1] op_sel_hi:[0,0]
	v_pk_fma_f32 v[182:183], v[114:115], v[96:97], v[180:181] neg_lo:[0,0,1] neg_hi:[0,0,1]
	v_pk_fma_f32 v[96:97], v[114:115], v[96:97], v[180:181] op_sel_hi:[0,1,1]
	v_mov_b32_e32 v183, v97
	v_pk_mul_f32 v[96:97], v[174:175], v[182:183] op_sel_hi:[0,1]

.LBB0_1492:
	v_or_b32_e32 v98, 3, v209
	s_andn2_b64 vcc, exec, s[4:5]
	v_min_i32_e32 v180, 0x7fff, v98
	s_cbranch_vccnz .LBB0_1494
	s_load_dwordx2 s[4:5], s[0:1], 0x148
	v_ashrrev_i32_e32 v181, 31, v180
	v_lshlrev_b64 v[96:97], 8, v[180:181]
	v_mov_b32_e32 v173, v161
	v_mov_b32_e32 v98, v99
	s_waitcnt lgkmcnt(0)
	v_lshl_add_u64 v[96:97], s[4:5], 0, v[96:97]
	v_lshl_add_u64 v[96:97], v[96:97], 0, v[172:173]
	v_mov_b32_e32 v96, v134
	v_mov_b32_e32 v97, v135
	v_mov_b32_e32 v114, v115
	s_waitcnt vmcnt(0)
	v_pk_mul_f32 v[98:99], v[98:99], v[96:97] op_sel:[0,1] op_sel_hi:[0,0]
	v_pk_fma_f32 v[182:183], v[114:115], v[96:97], v[98:99] op_sel_hi:[0,1,1] neg_lo:[0,0,1] neg_hi:[0,0,1]
	v_pk_fma_f32 v[96:97], v[114:115], v[96:97], v[98:99] op_sel_hi:[0,1,1]
	v_mov_b32_e32 v183, v97
	v_pk_mul_f32 v[96:97], v[174:175], v[182:183] op_sel_hi:[0,1]

.LBB0_1498:
	v_add_u32_e32 v98, 8, v209
	s_andn2_b64 vcc, exec, s[4:5]
	v_min_i32_e32 v114, 0x7fff, v98
	s_cbranch_vccnz .LBB0_1500
	s_load_dwordx2 s[4:5], s[0:1], 0x148
	v_ashrrev_i32_e32 v115, 31, v114
	v_lshlrev_b64 v[96:97], 8, v[114:115]
	v_mov_b32_e32 v173, v161
	s_waitcnt lgkmcnt(0)
	v_lshl_add_u64 v[96:97], s[4:5], 0, v[96:97]
	v_lshl_add_u64 v[96:97], v[96:97], 0, v[172:173]
	v_mov_b32_e32 v96, v136
	v_mov_b32_e32 v97, v137
	s_waitcnt vmcnt(0)
	v_pk_mul_f32 v[98:99], v[100:101], v[96:97] op_sel:[0,1] op_sel_hi:[0,0]
	v_pk_fma_f32 v[182:183], v[116:117], v[96:97], v[98:99] neg_lo:[0,0,1] neg_hi:[0,0,1]
	v_pk_fma_f32 v[96:97], v[116:117], v[96:97], v[98:99] op_sel_hi:[0,1,1]
	v_mov_b32_e32 v183, v97
	v_pk_mul_f32 v[96:97], v[174:175], v[182:183] op_sel_hi:[0,1]

.LBB0_1504:
	v_add_u32_e32 v98, 9, v209
	s_andn2_b64 vcc, exec, s[4:5]
	v_min_i32_e32 v182, 0x7fff, v98
	s_cbranch_vccnz .LBB0_1506
	s_load_dwordx2 s[4:5], s[0:1], 0x148
	v_ashrrev_i32_e32 v183, 31, v182
	v_lshlrev_b64 v[96:97], 8, v[182:183]
	v_mov_b32_e32 v173, v161
	v_mov_b32_e32 v98, v101
	s_waitcnt lgkmcnt(0)
	v_lshl_add_u64 v[96:97], s[4:5], 0, v[96:97]
	v_lshl_add_u64 v[96:97], v[96:97], 0, v[172:173]
	v_mov_b32_e32 v96, v138
	v_mov_b32_e32 v97, v139
	v_mov_b32_e32 v100, v117
	s_waitcnt vmcnt(0)
	v_pk_mul_f32 v[98:99], v[98:99], v[96:97] op_sel:[0,1] op_sel_hi:[0,0]
	v_pk_fma_f32 v[116:117], v[100:101], v[96:97], v[98:99] op_sel_hi:[0,1,1] neg_lo:[0,0,1] neg_hi:[0,0,1]
	v_pk_fma_f32 v[96:97], v[100:101], v[96:97], v[98:99] op_sel_hi:[0,1,1]
	v_mov_b32_e32 v117, v97
	v_pk_mul_f32 v[96:97], v[174:175], v[116:117] op_sel_hi:[0,1]

.LBB0_1510:
	v_add_u32_e32 v98, 10, v209
	s_andn2_b64 vcc, exec, s[4:5]
	v_min_i32_e32 v116, 0x7fff, v98
	s_cbranch_vccnz .LBB0_1512
	s_load_dwordx2 s[4:5], s[0:1], 0x148
	v_ashrrev_i32_e32 v117, 31, v116
	v_lshlrev_b64 v[96:97], 8, v[116:117]
	v_mov_b32_e32 v173, v161
	s_waitcnt lgkmcnt(0)
	v_lshl_add_u64 v[96:97], s[4:5], 0, v[96:97]
	v_lshl_add_u64 v[96:97], v[96:97], 0, v[172:173]
	v_mov_b32_e32 v96, v140
	v_mov_b32_e32 v97, v141
	s_waitcnt vmcnt(0)
	v_pk_mul_f32 v[98:99], v[102:103], v[96:97] op_sel:[0,1] op_sel_hi:[0,0]
	v_pk_fma_f32 v[100:101], v[118:119], v[96:97], v[98:99] neg_lo:[0,0,1] neg_hi:[0,0,1]
	v_pk_fma_f32 v[96:97], v[118:119], v[96:97], v[98:99] op_sel_hi:[0,1,1]
	v_mov_b32_e32 v101, v97
	v_pk_mul_f32 v[96:97], v[174:175], v[100:101] op_sel_hi:[0,1]

.LBB0_1516:
	v_add_u32_e32 v98, 11, v209
	s_andn2_b64 vcc, exec, s[4:5]
	v_min_i32_e32 v184, 0x7fff, v98
	s_cbranch_vccnz .LBB0_1518
	s_load_dwordx2 s[4:5], s[0:1], 0x148
	v_ashrrev_i32_e32 v185, 31, v184
	v_lshlrev_b64 v[96:97], 8, v[184:185]
	v_mov_b32_e32 v173, v161
	v_mov_b32_e32 v98, v103
	s_waitcnt lgkmcnt(0)
	v_lshl_add_u64 v[96:97], s[4:5], 0, v[96:97]
	v_lshl_add_u64 v[96:97], v[96:97], 0, v[172:173]
	v_mov_b32_e32 v96, v142
	v_mov_b32_e32 v97, v143
	v_mov_b32_e32 v100, v119
	s_waitcnt vmcnt(0)
	v_pk_mul_f32 v[98:99], v[98:99], v[96:97] op_sel:[0,1] op_sel_hi:[0,0]
	v_pk_fma_f32 v[102:103], v[100:101], v[96:97], v[98:99] op_sel_hi:[0,1,1] neg_lo:[0,0,1] neg_hi:[0,0,1]
	v_pk_fma_f32 v[96:97], v[100:101], v[96:97], v[98:99] op_sel_hi:[0,1,1]
	v_mov_b32_e32 v103, v97
	v_pk_mul_f32 v[96:97], v[174:175], v[102:103] op_sel_hi:[0,1]

.LBB0_1522:
	v_add_u32_e32 v98, 16, v209
	s_andn2_b64 vcc, exec, s[4:5]
	v_min_i32_e32 v118, 0x7fff, v98
	s_cbranch_vccnz .LBB0_1524
	s_load_dwordx2 s[4:5], s[0:1], 0x148
	v_ashrrev_i32_e32 v119, 31, v118
	v_lshlrev_b64 v[96:97], 8, v[118:119]
	v_mov_b32_e32 v173, v161
	s_waitcnt lgkmcnt(0)
	v_lshl_add_u64 v[96:97], s[4:5], 0, v[96:97]
	v_lshl_add_u64 v[96:97], v[96:97], 0, v[172:173]
	v_mov_b32_e32 v96, v144
	v_mov_b32_e32 v97, v145
	s_waitcnt vmcnt(0)
	v_pk_mul_f32 v[98:99], v[104:105], v[96:97] op_sel:[0,1] op_sel_hi:[0,0]
	v_pk_fma_f32 v[100:101], v[120:121], v[96:97], v[98:99] neg_lo:[0,0,1] neg_hi:[0,0,1]
	v_pk_fma_f32 v[96:97], v[120:121], v[96:97], v[98:99] op_sel_hi:[0,1,1]
	v_mov_b32_e32 v101, v97
	v_pk_mul_f32 v[96:97], v[174:175], v[100:101] op_sel_hi:[0,1]

.LBB0_1528:
	v_add_u32_e32 v98, 17, v209
	s_andn2_b64 vcc, exec, s[4:5]
	v_min_i32_e32 v186, 0x7fff, v98
	s_cbranch_vccnz .LBB0_1530
	s_load_dwordx2 s[4:5], s[0:1], 0x148
	v_ashrrev_i32_e32 v187, 31, v186
	v_lshlrev_b64 v[96:97], 8, v[186:187]
	v_mov_b32_e32 v173, v161
	v_mov_b32_e32 v98, v105
	s_waitcnt lgkmcnt(0)
	v_lshl_add_u64 v[96:97], s[4:5], 0, v[96:97]
	v_lshl_add_u64 v[96:97], v[96:97], 0, v[172:173]
	v_mov_b32_e32 v96, v146
	v_mov_b32_e32 v97, v147
	v_mov_b32_e32 v100, v121
	s_waitcnt vmcnt(0)
	v_pk_mul_f32 v[98:99], v[98:99], v[96:97] op_sel:[0,1] op_sel_hi:[0,0]
	v_pk_fma_f32 v[102:103], v[100:101], v[96:97], v[98:99] op_sel_hi:[0,1,1] neg_lo:[0,0,1] neg_hi:[0,0,1]
	v_pk_fma_f32 v[96:97], v[100:101], v[96:97], v[98:99] op_sel_hi:[0,1,1]
	v_mov_b32_e32 v103, v97
	v_pk_mul_f32 v[96:97], v[174:175], v[102:103] op_sel_hi:[0,1]

.LBB0_1534:
	v_add_u32_e32 v98, 18, v209
	s_andn2_b64 vcc, exec, s[4:5]
	v_min_i32_e32 v120, 0x7fff, v98
	s_cbranch_vccnz .LBB0_1536
	s_load_dwordx2 s[4:5], s[0:1], 0x148
	v_ashrrev_i32_e32 v121, 31, v120
	v_lshlrev_b64 v[96:97], 8, v[120:121]
	v_mov_b32_e32 v173, v161
	s_waitcnt lgkmcnt(0)
	v_lshl_add_u64 v[96:97], s[4:5], 0, v[96:97]
	v_lshl_add_u64 v[96:97], v[96:97], 0, v[172:173]
	v_mov_b32_e32 v96, v148
	v_mov_b32_e32 v97, v149
	s_waitcnt vmcnt(0)
	v_pk_mul_f32 v[98:99], v[106:107], v[96:97] op_sel:[0,1] op_sel_hi:[0,0]
	v_pk_fma_f32 v[100:101], v[122:123], v[96:97], v[98:99] neg_lo:[0,0,1] neg_hi:[0,0,1]
	v_pk_fma_f32 v[96:97], v[122:123], v[96:97], v[98:99] op_sel_hi:[0,1,1]
	v_mov_b32_e32 v101, v97
	v_pk_mul_f32 v[96:97], v[174:175], v[100:101] op_sel_hi:[0,1]

.LBB0_1540:
	v_add_u32_e32 v98, 19, v209
	s_andn2_b64 vcc, exec, s[4:5]
	v_min_i32_e32 v188, 0x7fff, v98
	s_cbranch_vccnz .LBB0_1542
	s_load_dwordx2 s[4:5], s[0:1], 0x148
	v_ashrrev_i32_e32 v189, 31, v188
	v_lshlrev_b64 v[96:97], 8, v[188:189]
	v_mov_b32_e32 v173, v161
	v_mov_b32_e32 v98, v107
	s_waitcnt lgkmcnt(0)
	v_lshl_add_u64 v[96:97], s[4:5], 0, v[96:97]
	v_lshl_add_u64 v[96:97], v[96:97], 0, v[172:173]
	v_mov_b32_e32 v96, v150
	v_mov_b32_e32 v97, v151
	v_mov_b32_e32 v100, v123
	s_waitcnt vmcnt(0)
	v_pk_mul_f32 v[98:99], v[98:99], v[96:97] op_sel:[0,1] op_sel_hi:[0,0]
	v_pk_fma_f32 v[102:103], v[100:101], v[96:97], v[98:99] op_sel_hi:[0,1,1] neg_lo:[0,0,1] neg_hi:[0,0,1]
	v_pk_fma_f32 v[96:97], v[100:101], v[96:97], v[98:99] op_sel_hi:[0,1,1]
	v_mov_b32_e32 v103, v97
	v_pk_mul_f32 v[96:97], v[174:175], v[102:103] op_sel_hi:[0,1]

.LBB0_1546:
	v_add_u32_e32 v98, 24, v209
	s_andn2_b64 vcc, exec, s[4:5]
	v_min_i32_e32 v122, 0x7fff, v98
	s_cbranch_vccnz .LBB0_1548
	s_load_dwordx2 s[4:5], s[0:1], 0x148
	v_ashrrev_i32_e32 v123, 31, v122
	v_lshlrev_b64 v[96:97], 8, v[122:123]
	v_mov_b32_e32 v173, v161
	s_waitcnt lgkmcnt(0)
	v_lshl_add_u64 v[96:97], s[4:5], 0, v[96:97]
	v_lshl_add_u64 v[96:97], v[96:97], 0, v[172:173]
	v_mov_b32_e32 v96, v152
	v_mov_b32_e32 v97, v153
	s_waitcnt vmcnt(0)
	v_pk_mul_f32 v[98:99], v[108:109], v[96:97] op_sel:[0,1] op_sel_hi:[0,0]
	v_pk_fma_f32 v[100:101], v[124:125], v[96:97], v[98:99] neg_lo:[0,0,1] neg_hi:[0,0,1]
	v_pk_fma_f32 v[96:97], v[124:125], v[96:97], v[98:99] op_sel_hi:[0,1,1]
	v_mov_b32_e32 v101, v97
	v_pk_mul_f32 v[96:97], v[174:175], v[100:101] op_sel_hi:[0,1]

.LBB0_1552:
	v_add_u32_e32 v98, 25, v209
	s_andn2_b64 vcc, exec, s[4:5]
	v_min_i32_e32 v190, 0x7fff, v98
	s_cbranch_vccnz .LBB0_1554
	s_load_dwordx2 s[4:5], s[0:1], 0x148
	v_ashrrev_i32_e32 v191, 31, v190
	v_lshlrev_b64 v[96:97], 8, v[190:191]
	v_mov_b32_e32 v173, v161
	v_mov_b32_e32 v98, v109
	s_waitcnt lgkmcnt(0)
	v_lshl_add_u64 v[96:97], s[4:5], 0, v[96:97]
	v_lshl_add_u64 v[96:97], v[96:97], 0, v[172:173]
	v_mov_b32_e32 v96, v154
	v_mov_b32_e32 v97, v155
	v_mov_b32_e32 v100, v125
	s_waitcnt vmcnt(0)
	v_pk_mul_f32 v[98:99], v[98:99], v[96:97] op_sel:[0,1] op_sel_hi:[0,0]
	v_pk_fma_f32 v[102:103], v[100:101], v[96:97], v[98:99] op_sel_hi:[0,1,1] neg_lo:[0,0,1] neg_hi:[0,0,1]
	v_pk_fma_f32 v[96:97], v[100:101], v[96:97], v[98:99] op_sel_hi:[0,1,1]
	v_mov_b32_e32 v103, v97
	v_pk_mul_f32 v[96:97], v[174:175], v[102:103] op_sel_hi:[0,1]

.LBB0_1558:
	v_add_u32_e32 v98, 26, v209
	s_andn2_b64 vcc, exec, s[4:5]
	v_min_i32_e32 v108, 0x7fff, v98
	s_cbranch_vccnz .LBB0_1560
	s_load_dwordx2 s[4:5], s[0:1], 0x148
	v_ashrrev_i32_e32 v109, 31, v108
	v_lshlrev_b64 v[96:97], 8, v[108:109]
	v_mov_b32_e32 v173, v161
	s_waitcnt lgkmcnt(0)
	v_lshl_add_u64 v[96:97], s[4:5], 0, v[96:97]
	v_lshl_add_u64 v[96:97], v[96:97], 0, v[172:173]
	v_mov_b32_e32 v96, v156
	v_mov_b32_e32 v97, v157
	s_waitcnt vmcnt(0)
	v_pk_mul_f32 v[98:99], v[110:111], v[96:97] op_sel:[0,1] op_sel_hi:[0,0]
	v_pk_fma_f32 v[100:101], v[126:127], v[96:97], v[98:99] neg_lo:[0,0,1] neg_hi:[0,0,1]
	v_pk_fma_f32 v[96:97], v[126:127], v[96:97], v[98:99] op_sel_hi:[0,1,1]
	v_mov_b32_e32 v101, v97
	v_pk_mul_f32 v[96:97], v[174:175], v[100:101] op_sel_hi:[0,1]

.LBB0_1564:
	v_add_u32_e32 v98, 27, v209
	s_andn2_b64 vcc, exec, s[4:5]
	v_min_i32_e32 v124, 0x7fff, v98
	s_cbranch_vccnz .LBB0_1566
	s_load_dwordx2 s[4:5], s[0:1], 0x148
	v_ashrrev_i32_e32 v125, 31, v124
	v_lshlrev_b64 v[96:97], 8, v[124:125]
	v_mov_b32_e32 v173, v161
	v_mov_b32_e32 v98, v111
	s_waitcnt lgkmcnt(0)
	v_lshl_add_u64 v[96:97], s[4:5], 0, v[96:97]
	v_lshl_add_u64 v[96:97], v[96:97], 0, v[172:173]
	v_mov_b32_e32 v96, v158
	v_mov_b32_e32 v97, v159
	v_mov_b32_e32 v100, v127
	s_waitcnt vmcnt(0)
	v_pk_mul_f32 v[98:99], v[98:99], v[96:97] op_sel:[0,1] op_sel_hi:[0,0]
	v_pk_fma_f32 v[102:103], v[100:101], v[96:97], v[98:99] op_sel_hi:[0,1,1] neg_lo:[0,0,1] neg_hi:[0,0,1]
	v_pk_fma_f32 v[96:97], v[100:101], v[96:97], v[98:99] op_sel_hi:[0,1,1]
	v_mov_b32_e32 v103, v97
	v_pk_mul_f32 v[96:97], v[174:175], v[102:103] op_sel_hi:[0,1]

.LBB0_1626:
	s_andn2_b64 vcc, exec, s[60:61]
	v_cndmask_b32_e64 v96, 1.0, v206, s[8:9]
	s_cbranch_vccnz .LBB0_1628
	s_load_dwordx2 s[8:9], s[0:1], 0x148
	v_lshlrev_b64 v[98:99], 8, v[176:177]
	v_mov_b32_e32 v173, v161
	s_waitcnt lgkmcnt(0)
	v_lshl_add_u64 v[98:99], s[8:9], 0, v[98:99]
	v_lshl_add_u64 v[98:99], v[98:99], 0, v[172:173]
	global_load_dwordx2 v[128:129], v[98:99], off
	global_load_dwordx2 v[130:131], v[98:99], off offset:256
	global_load_dwordx2 v[132:133], v[98:99], off offset:512
	global_load_dwordx2 v[134:135], v[98:99], off offset:768
	global_load_dwordx2 v[136:137], v[98:99], off offset:2048
	global_load_dwordx2 v[138:139], v[98:99], off offset:2304
	global_load_dwordx2 v[140:141], v[98:99], off offset:2560
	global_load_dwordx2 v[142:143], v[98:99], off offset:2816
	s_mov_b64 s[98:99], 0x1000
	v_lshl_add_u64 v[158:159], v[98:99], 0, s[98:99]
	global_load_dwordx2 v[144:145], v[158:159], off offset:0
	global_load_dwordx2 v[146:147], v[158:159], off offset:256
	global_load_dwordx2 v[148:149], v[158:159], off offset:512
	global_load_dwordx2 v[150:151], v[158:159], off offset:768
	global_load_dwordx2 v[152:153], v[158:159], off offset:2048
	global_load_dwordx2 v[154:155], v[158:159], off offset:2304
	global_load_dwordx2 v[156:157], v[158:159], off offset:2560
	global_load_dwordx2 v[158:159], v[158:159], off offset:2816
	s_waitcnt vmcnt(0)
	v_mov_b32_e32 v98, v128
	v_mov_b32_e32 v99, v129
	v_pk_mul_f32 v[110:111], v[64:65], v[98:99] op_sel:[0,1] op_sel_hi:[0,0]
	v_pk_fma_f32 v[176:177], v[80:81], v[98:99], v[110:111] neg_lo:[0,0,1] neg_hi:[0,0,1]
	v_pk_fma_f32 v[98:99], v[80:81], v[98:99], v[110:111] op_sel_hi:[0,1,1]
	v_mov_b32_e32 v177, v99
	v_pk_mul_f32 v[98:99], v[96:97], v[176:177] op_sel_hi:[0,1]

.LBB0_1632:
	s_andn2_b64 vcc, exec, s[58:59]
	s_cbranch_vccnz .LBB0_1634
	s_load_dwordx2 s[58:59], s[0:1], 0x148
	v_ashrrev_i32_e32 v179, 31, v178
	v_lshlrev_b64 v[98:99], 8, v[178:179]
	v_mov_b32_e32 v173, v161
	s_waitcnt lgkmcnt(0)
	v_lshl_add_u64 v[98:99], s[58:59], 0, v[98:99]
	v_lshl_add_u64 v[98:99], v[98:99], 0, v[172:173]
	v_mov_b32_e32 v98, v130
	v_mov_b32_e32 v99, v131
	s_waitcnt vmcnt(0)
	v_pk_mul_f32 v[64:65], v[64:65], v[98:99] op_sel:[1,1] op_sel_hi:[1,0]
	s_nop 0
	v_pk_fma_f32 v[110:111], v[80:81], v[98:99], v[64:65] op_sel:[1,0,0] neg_lo:[0,0,1] neg_hi:[0,0,1]
	v_pk_fma_f32 v[64:65], v[80:81], v[98:99], v[64:65] op_sel:[1,0,0]
	s_nop 0
	v_mov_b32_e32 v111, v65
	v_pk_mul_f32 v[98:99], v[96:97], v[110:111] op_sel_hi:[0,1]

.LBB0_1638:
	s_andn2_b64 vcc, exec, s[58:59]
	s_cbranch_vccnz .LBB0_1640
	s_load_dwordx2 s[58:59], s[0:1], 0x148
	v_ashrrev_i32_e32 v113, 31, v112
	v_lshlrev_b64 v[64:65], 8, v[112:113]
	v_mov_b32_e32 v173, v161
	s_waitcnt lgkmcnt(0)
	v_lshl_add_u64 v[64:65], s[58:59], 0, v[64:65]
	v_lshl_add_u64 v[64:65], v[64:65], 0, v[172:173]
	v_mov_b32_e32 v64, v132
	v_mov_b32_e32 v65, v133
	s_waitcnt vmcnt(0)
	v_pk_mul_f32 v[80:81], v[66:67], v[64:65] op_sel:[0,1] op_sel_hi:[0,0]
	v_pk_fma_f32 v[98:99], v[82:83], v[64:65], v[80:81] neg_lo:[0,0,1] neg_hi:[0,0,1]
	v_pk_fma_f32 v[64:65], v[82:83], v[64:65], v[80:81] op_sel_hi:[0,1,1]
	v_mov_b32_e32 v99, v65
	v_pk_mul_f32 v[64:65], v[96:97], v[98:99] op_sel_hi:[0,1]

.LBB0_1644:
	s_andn2_b64 vcc, exec, s[58:59]
	s_cbranch_vccnz .LBB0_1646
	s_load_dwordx2 s[58:59], s[0:1], 0x148
	v_ashrrev_i32_e32 v181, 31, v180
	v_lshlrev_b64 v[64:65], 8, v[180:181]
	v_mov_b32_e32 v173, v161
	v_mov_b32_e32 v66, v67
	s_waitcnt lgkmcnt(0)
	v_lshl_add_u64 v[64:65], s[58:59], 0, v[64:65]
	v_lshl_add_u64 v[64:65], v[64:65], 0, v[172:173]
	v_mov_b32_e32 v64, v134
	v_mov_b32_e32 v65, v135
	v_mov_b32_e32 v80, v83
	s_waitcnt vmcnt(0)
	v_pk_mul_f32 v[66:67], v[66:67], v[64:65] op_sel:[0,1] op_sel_hi:[0,0]
	v_pk_fma_f32 v[82:83], v[80:81], v[64:65], v[66:67] op_sel_hi:[0,1,1] neg_lo:[0,0,1] neg_hi:[0,0,1]
	v_pk_fma_f32 v[64:65], v[80:81], v[64:65], v[66:67] op_sel_hi:[0,1,1]
	v_mov_b32_e32 v83, v65
	v_pk_mul_f32 v[64:65], v[96:97], v[82:83] op_sel_hi:[0,1]

.LBB0_1650:
	s_andn2_b64 vcc, exec, s[58:59]
	s_cbranch_vccnz .LBB0_1652
	s_load_dwordx2 s[58:59], s[0:1], 0x148
	v_ashrrev_i32_e32 v115, 31, v114
	v_lshlrev_b64 v[64:65], 8, v[114:115]
	v_mov_b32_e32 v173, v161
	s_waitcnt lgkmcnt(0)
	v_lshl_add_u64 v[64:65], s[58:59], 0, v[64:65]
	v_lshl_add_u64 v[64:65], v[64:65], 0, v[172:173]
	v_mov_b32_e32 v64, v136
	v_mov_b32_e32 v65, v137
	s_waitcnt vmcnt(0)
	v_pk_mul_f32 v[66:67], v[68:69], v[64:65] op_sel:[0,1] op_sel_hi:[0,0]
	v_pk_fma_f32 v[80:81], v[84:85], v[64:65], v[66:67] neg_lo:[0,0,1] neg_hi:[0,0,1]
	v_pk_fma_f32 v[64:65], v[84:85], v[64:65], v[66:67] op_sel_hi:[0,1,1]
	v_mov_b32_e32 v81, v65
	v_pk_mul_f32 v[64:65], v[96:97], v[80:81] op_sel_hi:[0,1]

.LBB0_1656:
	s_andn2_b64 vcc, exec, s[58:59]
	s_cbranch_vccnz .LBB0_1658
	s_load_dwordx2 s[58:59], s[0:1], 0x148
	v_ashrrev_i32_e32 v183, 31, v182
	v_lshlrev_b64 v[64:65], 8, v[182:183]
	v_mov_b32_e32 v173, v161
	v_mov_b32_e32 v66, v69
	s_waitcnt lgkmcnt(0)
	v_lshl_add_u64 v[64:65], s[58:59], 0, v[64:65]
	v_lshl_add_u64 v[64:65], v[64:65], 0, v[172:173]
	v_mov_b32_e32 v64, v138
	v_mov_b32_e32 v65, v139
	v_mov_b32_e32 v68, v85
	s_waitcnt vmcnt(0)
	v_pk_mul_f32 v[66:67], v[66:67], v[64:65] op_sel:[0,1] op_sel_hi:[0,0]
	v_pk_fma_f32 v[80:81], v[68:69], v[64:65], v[66:67] op_sel_hi:[0,1,1] neg_lo:[0,0,1] neg_hi:[0,0,1]
	v_pk_fma_f32 v[64:65], v[68:69], v[64:65], v[66:67] op_sel_hi:[0,1,1]
	v_mov_b32_e32 v81, v65
	v_pk_mul_f32 v[64:65], v[96:97], v[80:81] op_sel_hi:[0,1]

.LBB0_1662:
	s_andn2_b64 vcc, exec, s[58:59]
	s_cbranch_vccnz .LBB0_1664
	s_load_dwordx2 s[58:59], s[0:1], 0x148
	v_ashrrev_i32_e32 v117, 31, v116
	v_lshlrev_b64 v[64:65], 8, v[116:117]
	v_mov_b32_e32 v173, v161
	s_waitcnt lgkmcnt(0)
	v_lshl_add_u64 v[64:65], s[58:59], 0, v[64:65]
	v_lshl_add_u64 v[64:65], v[64:65], 0, v[172:173]
	v_mov_b32_e32 v64, v140
	v_mov_b32_e32 v65, v141
	s_waitcnt vmcnt(0)
	v_pk_mul_f32 v[66:67], v[70:71], v[64:65] op_sel:[0,1] op_sel_hi:[0,0]
	v_pk_fma_f32 v[68:69], v[86:87], v[64:65], v[66:67] neg_lo:[0,0,1] neg_hi:[0,0,1]
	v_pk_fma_f32 v[64:65], v[86:87], v[64:65], v[66:67] op_sel_hi:[0,1,1]
	v_mov_b32_e32 v69, v65
	v_pk_mul_f32 v[64:65], v[96:97], v[68:69] op_sel_hi:[0,1]

.LBB0_1668:
	s_andn2_b64 vcc, exec, s[58:59]
	s_cbranch_vccnz .LBB0_1670
	s_load_dwordx2 s[58:59], s[0:1], 0x148
	v_ashrrev_i32_e32 v185, 31, v184
	v_lshlrev_b64 v[64:65], 8, v[184:185]
	v_mov_b32_e32 v173, v161
	v_mov_b32_e32 v66, v71
	s_waitcnt lgkmcnt(0)
	v_lshl_add_u64 v[64:65], s[58:59], 0, v[64:65]
	v_lshl_add_u64 v[64:65], v[64:65], 0, v[172:173]
	v_mov_b32_e32 v64, v142
	v_mov_b32_e32 v65, v143
	v_mov_b32_e32 v68, v87
	s_waitcnt vmcnt(0)
	v_pk_mul_f32 v[66:67], v[66:67], v[64:65] op_sel:[0,1] op_sel_hi:[0,0]
	v_pk_fma_f32 v[70:71], v[68:69], v[64:65], v[66:67] op_sel_hi:[0,1,1] neg_lo:[0,0,1] neg_hi:[0,0,1]
	v_pk_fma_f32 v[64:65], v[68:69], v[64:65], v[66:67] op_sel_hi:[0,1,1]
	v_mov_b32_e32 v71, v65
	v_pk_mul_f32 v[64:65], v[96:97], v[70:71] op_sel_hi:[0,1]

.LBB0_1674:
	s_andn2_b64 vcc, exec, s[58:59]
	s_cbranch_vccnz .LBB0_1676
	s_load_dwordx2 s[58:59], s[0:1], 0x148
	v_ashrrev_i32_e32 v119, 31, v118
	v_lshlrev_b64 v[64:65], 8, v[118:119]
	v_mov_b32_e32 v173, v161
	s_waitcnt lgkmcnt(0)
	v_lshl_add_u64 v[64:65], s[58:59], 0, v[64:65]
	v_lshl_add_u64 v[64:65], v[64:65], 0, v[172:173]
	v_mov_b32_e32 v64, v144
	v_mov_b32_e32 v65, v145
	s_waitcnt vmcnt(0)
	v_pk_mul_f32 v[66:67], v[72:73], v[64:65] op_sel:[0,1] op_sel_hi:[0,0]
	v_pk_fma_f32 v[68:69], v[88:89], v[64:65], v[66:67] neg_lo:[0,0,1] neg_hi:[0,0,1]
	v_pk_fma_f32 v[64:65], v[88:89], v[64:65], v[66:67] op_sel_hi:[0,1,1]
	v_mov_b32_e32 v69, v65
	v_pk_mul_f32 v[64:65], v[96:97], v[68:69] op_sel_hi:[0,1]

.LBB0_1680:
	s_andn2_b64 vcc, exec, s[58:59]
	s_cbranch_vccnz .LBB0_1682
	s_load_dwordx2 s[58:59], s[0:1], 0x148
	v_ashrrev_i32_e32 v187, 31, v186
	v_lshlrev_b64 v[64:65], 8, v[186:187]
	v_mov_b32_e32 v173, v161
	v_mov_b32_e32 v66, v73
	s_waitcnt lgkmcnt(0)
	v_lshl_add_u64 v[64:65], s[58:59], 0, v[64:65]
	v_lshl_add_u64 v[64:65], v[64:65], 0, v[172:173]
	v_mov_b32_e32 v64, v146
	v_mov_b32_e32 v65, v147
	v_mov_b32_e32 v68, v89
	s_waitcnt vmcnt(0)
	v_pk_mul_f32 v[66:67], v[66:67], v[64:65] op_sel:[0,1] op_sel_hi:[0,0]
	v_pk_fma_f32 v[70:71], v[68:69], v[64:65], v[66:67] op_sel_hi:[0,1,1] neg_lo:[0,0,1] neg_hi:[0,0,1]
	v_pk_fma_f32 v[64:65], v[68:69], v[64:65], v[66:67] op_sel_hi:[0,1,1]
	v_mov_b32_e32 v71, v65
	v_pk_mul_f32 v[64:65], v[96:97], v[70:71] op_sel_hi:[0,1]

.LBB0_1686:
	s_andn2_b64 vcc, exec, s[58:59]
	s_cbranch_vccnz .LBB0_1688
	s_load_dwordx2 s[58:59], s[0:1], 0x148
	v_ashrrev_i32_e32 v121, 31, v120
	v_lshlrev_b64 v[64:65], 8, v[120:121]
	v_mov_b32_e32 v173, v161
	s_waitcnt lgkmcnt(0)
	v_lshl_add_u64 v[64:65], s[58:59], 0, v[64:65]
	v_lshl_add_u64 v[64:65], v[64:65], 0, v[172:173]
	v_mov_b32_e32 v64, v148
	v_mov_b32_e32 v65, v149
	s_waitcnt vmcnt(0)
	v_pk_mul_f32 v[66:67], v[74:75], v[64:65] op_sel:[0,1] op_sel_hi:[0,0]
	v_pk_fma_f32 v[68:69], v[90:91], v[64:65], v[66:67] neg_lo:[0,0,1] neg_hi:[0,0,1]
	v_pk_fma_f32 v[64:65], v[90:91], v[64:65], v[66:67] op_sel_hi:[0,1,1]
	v_mov_b32_e32 v69, v65
	v_pk_mul_f32 v[64:65], v[96:97], v[68:69] op_sel_hi:[0,1]

.LBB0_1692:
	s_andn2_b64 vcc, exec, s[58:59]
	s_cbranch_vccnz .LBB0_1694
	s_load_dwordx2 s[58:59], s[0:1], 0x148
	v_ashrrev_i32_e32 v189, 31, v188
	v_lshlrev_b64 v[64:65], 8, v[188:189]
	v_mov_b32_e32 v173, v161
	v_mov_b32_e32 v66, v75
	s_waitcnt lgkmcnt(0)
	v_lshl_add_u64 v[64:65], s[58:59], 0, v[64:65]
	v_lshl_add_u64 v[64:65], v[64:65], 0, v[172:173]
	v_mov_b32_e32 v64, v150
	v_mov_b32_e32 v65, v151
	v_mov_b32_e32 v68, v91
	s_waitcnt vmcnt(0)
	v_pk_mul_f32 v[66:67], v[66:67], v[64:65] op_sel:[0,1] op_sel_hi:[0,0]
	v_pk_fma_f32 v[70:71], v[68:69], v[64:65], v[66:67] op_sel_hi:[0,1,1] neg_lo:[0,0,1] neg_hi:[0,0,1]
	v_pk_fma_f32 v[64:65], v[68:69], v[64:65], v[66:67] op_sel_hi:[0,1,1]
	v_mov_b32_e32 v71, v65
	v_pk_mul_f32 v[64:65], v[96:97], v[70:71] op_sel_hi:[0,1]

.LBB0_1698:
	s_andn2_b64 vcc, exec, s[58:59]
	s_cbranch_vccnz .LBB0_1700
	s_load_dwordx2 s[58:59], s[0:1], 0x148
	v_ashrrev_i32_e32 v123, 31, v122
	v_lshlrev_b64 v[64:65], 8, v[122:123]
	v_mov_b32_e32 v173, v161
	s_waitcnt lgkmcnt(0)
	v_lshl_add_u64 v[64:65], s[58:59], 0, v[64:65]
	v_lshl_add_u64 v[64:65], v[64:65], 0, v[172:173]
	v_mov_b32_e32 v64, v152
	v_mov_b32_e32 v65, v153
	s_waitcnt vmcnt(0)
	v_pk_mul_f32 v[66:67], v[76:77], v[64:65] op_sel:[0,1] op_sel_hi:[0,0]
	v_pk_fma_f32 v[68:69], v[92:93], v[64:65], v[66:67] neg_lo:[0,0,1] neg_hi:[0,0,1]
	v_pk_fma_f32 v[64:65], v[92:93], v[64:65], v[66:67] op_sel_hi:[0,1,1]
	v_mov_b32_e32 v69, v65
	v_pk_mul_f32 v[64:65], v[96:97], v[68:69] op_sel_hi:[0,1]

.LBB0_1704:
	s_andn2_b64 vcc, exec, s[58:59]
	s_cbranch_vccnz .LBB0_1706
	s_load_dwordx2 s[58:59], s[0:1], 0x148
	v_ashrrev_i32_e32 v191, 31, v190
	v_lshlrev_b64 v[64:65], 8, v[190:191]
	v_mov_b32_e32 v173, v161
	v_mov_b32_e32 v66, v77
	s_waitcnt lgkmcnt(0)
	v_lshl_add_u64 v[64:65], s[58:59], 0, v[64:65]
	v_lshl_add_u64 v[64:65], v[64:65], 0, v[172:173]
	v_mov_b32_e32 v64, v154
	v_mov_b32_e32 v65, v155
	v_mov_b32_e32 v68, v93
	s_waitcnt vmcnt(0)
	v_pk_mul_f32 v[66:67], v[66:67], v[64:65] op_sel:[0,1] op_sel_hi:[0,0]
	v_pk_fma_f32 v[70:71], v[68:69], v[64:65], v[66:67] op_sel_hi:[0,1,1] neg_lo:[0,0,1] neg_hi:[0,0,1]
	v_pk_fma_f32 v[64:65], v[68:69], v[64:65], v[66:67] op_sel_hi:[0,1,1]
	v_mov_b32_e32 v71, v65
	v_pk_mul_f32 v[64:65], v[96:97], v[70:71] op_sel_hi:[0,1]

.LBB0_1710:
	s_andn2_b64 vcc, exec, s[58:59]
	s_cbranch_vccnz .LBB0_1712
	s_load_dwordx2 s[58:59], s[0:1], 0x148
	v_ashrrev_i32_e32 v109, 31, v108
	v_lshlrev_b64 v[64:65], 8, v[108:109]
	v_mov_b32_e32 v173, v161
	s_waitcnt lgkmcnt(0)
	v_lshl_add_u64 v[64:65], s[58:59], 0, v[64:65]
	v_lshl_add_u64 v[64:65], v[64:65], 0, v[172:173]
	v_mov_b32_e32 v64, v156
	v_mov_b32_e32 v65, v157
	s_waitcnt vmcnt(0)
	v_pk_mul_f32 v[66:67], v[78:79], v[64:65] op_sel:[0,1] op_sel_hi:[0,0]
	v_pk_fma_f32 v[68:69], v[94:95], v[64:65], v[66:67] neg_lo:[0,0,1] neg_hi:[0,0,1]
	v_pk_fma_f32 v[64:65], v[94:95], v[64:65], v[66:67] op_sel_hi:[0,1,1]
	v_mov_b32_e32 v69, v65
	v_pk_mul_f32 v[64:65], v[96:97], v[68:69] op_sel_hi:[0,1]

.LBB0_1716:
	s_andn2_b64 vcc, exec, s[58:59]
	s_cbranch_vccnz .LBB0_1718
	s_load_dwordx2 s[58:59], s[0:1], 0x148
	v_ashrrev_i32_e32 v125, 31, v124
	v_lshlrev_b64 v[64:65], 8, v[124:125]
	v_mov_b32_e32 v173, v161
	v_mov_b32_e32 v66, v79
	s_waitcnt lgkmcnt(0)
	v_lshl_add_u64 v[64:65], s[58:59], 0, v[64:65]
	v_lshl_add_u64 v[64:65], v[64:65], 0, v[172:173]
	v_mov_b32_e32 v64, v158
	v_mov_b32_e32 v65, v159
	v_mov_b32_e32 v68, v95
	s_waitcnt vmcnt(0)
	v_pk_mul_f32 v[66:67], v[66:67], v[64:65] op_sel:[0,1] op_sel_hi:[0,0]
	v_pk_fma_f32 v[70:71], v[68:69], v[64:65], v[66:67] op_sel_hi:[0,1,1] neg_lo:[0,0,1] neg_hi:[0,0,1]
	v_pk_fma_f32 v[64:65], v[68:69], v[64:65], v[66:67] op_sel_hi:[0,1,1]
	v_mov_b32_e32 v71, v65
	v_pk_mul_f32 v[64:65], v[96:97], v[70:71] op_sel_hi:[0,1]

.LBB0_1778:
	s_or_b32 s16, s77, 32
	v_add_u32_e32 v80, s16, v208
	v_min_i32_e32 v66, 0x7fff, v80
	s_andn2_b64 vcc, exec, s[14:15]
	v_ashrrev_i32_e32 v67, 31, v66
	s_cbranch_vccnz .LBB0_1780
	s_load_dwordx2 s[14:15], s[0:1], 0x148
	v_lshlrev_b64 v[64:65], 8, v[66:67]
	v_mov_b32_e32 v173, v161
	s_waitcnt lgkmcnt(0)
	v_lshl_add_u64 v[64:65], s[14:15], 0, v[64:65]
	v_lshl_add_u64 v[64:65], v[64:65], 0, v[172:173]
	global_load_dwordx2 v[128:129], v[64:65], off
	global_load_dwordx2 v[130:131], v[64:65], off offset:256
	global_load_dwordx2 v[132:133], v[64:65], off offset:512
	global_load_dwordx2 v[134:135], v[64:65], off offset:768
	global_load_dwordx2 v[136:137], v[64:65], off offset:2048
	global_load_dwordx2 v[138:139], v[64:65], off offset:2304
	global_load_dwordx2 v[140:141], v[64:65], off offset:2560
	global_load_dwordx2 v[142:143], v[64:65], off offset:2816
	s_mov_b64 s[98:99], 0x1000
	v_lshl_add_u64 v[158:159], v[64:65], 0, s[98:99]
	global_load_dwordx2 v[144:145], v[158:159], off offset:0
	global_load_dwordx2 v[146:147], v[158:159], off offset:256
	global_load_dwordx2 v[148:149], v[158:159], off offset:512
	global_load_dwordx2 v[150:151], v[158:159], off offset:768
	global_load_dwordx2 v[152:153], v[158:159], off offset:2048
	global_load_dwordx2 v[154:155], v[158:159], off offset:2304
	global_load_dwordx2 v[156:157], v[158:159], off offset:2560
	global_load_dwordx2 v[158:159], v[158:159], off offset:2816
	s_waitcnt vmcnt(0)
	v_mov_b32_e32 v64, v128
	v_mov_b32_e32 v65, v129
	v_pk_mul_f32 v[68:69], v[32:33], v[64:65] op_sel:[0,1] op_sel_hi:[0,0]
	v_pk_fma_f32 v[70:71], v[48:49], v[64:65], v[68:69] neg_lo:[0,0,1] neg_hi:[0,0,1]
	v_pk_fma_f32 v[64:65], v[48:49], v[64:65], v[68:69] op_sel_hi:[0,1,1]
	v_mov_b32_e32 v71, v65
	v_pk_mul_f32 v[64:65], v[174:175], v[70:71] op_sel_hi:[0,1]

.LBB0_1784:
	v_or_b32_e32 v64, 1, v80
	s_andn2_b64 vcc, exec, s[14:15]
	v_min_i32_e32 v64, 0x7fff, v64
	s_cbranch_vccnz .LBB0_1786
	s_load_dwordx2 s[14:15], s[0:1], 0x148
	v_ashrrev_i32_e32 v65, 31, v64
	v_lshlrev_b64 v[68:69], 8, v[64:65]
	v_mov_b32_e32 v173, v161
	s_waitcnt lgkmcnt(0)
	v_lshl_add_u64 v[68:69], s[14:15], 0, v[68:69]
	v_lshl_add_u64 v[68:69], v[68:69], 0, v[172:173]
	v_mov_b32_e32 v68, v130
	v_mov_b32_e32 v69, v131
	s_waitcnt vmcnt(0)
	v_pk_mul_f32 v[32:33], v[32:33], v[68:69] op_sel:[1,1] op_sel_hi:[1,0]
	s_nop 0
	v_pk_fma_f32 v[70:71], v[48:49], v[68:69], v[32:33] op_sel:[1,0,0] neg_lo:[0,0,1] neg_hi:[0,0,1]
	v_pk_fma_f32 v[32:33], v[48:49], v[68:69], v[32:33] op_sel:[1,0,0]
	s_nop 0
	v_mov_b32_e32 v71, v33
	v_pk_mul_f32 v[68:69], v[174:175], v[70:71] op_sel_hi:[0,1]

.LBB0_1790:
	v_or_b32_e32 v48, 2, v80
	s_andn2_b64 vcc, exec, s[14:15]
	v_min_i32_e32 v48, 0x7fff, v48
	s_cbranch_vccnz .LBB0_1792
	s_load_dwordx2 s[14:15], s[0:1], 0x148
	v_ashrrev_i32_e32 v49, 31, v48
	v_lshlrev_b64 v[32:33], 8, v[48:49]
	v_mov_b32_e32 v173, v161
	s_waitcnt lgkmcnt(0)
	v_lshl_add_u64 v[32:33], s[14:15], 0, v[32:33]
	v_lshl_add_u64 v[32:33], v[32:33], 0, v[172:173]
	v_mov_b32_e32 v32, v132
	v_mov_b32_e32 v33, v133
	s_waitcnt vmcnt(0)
	v_pk_mul_f32 v[68:69], v[34:35], v[32:33] op_sel:[0,1] op_sel_hi:[0,0]
	v_pk_fma_f32 v[70:71], v[50:51], v[32:33], v[68:69] neg_lo:[0,0,1] neg_hi:[0,0,1]
	v_pk_fma_f32 v[32:33], v[50:51], v[32:33], v[68:69] op_sel_hi:[0,1,1]
	v_mov_b32_e32 v71, v33
	v_pk_mul_f32 v[32:33], v[174:175], v[70:71] op_sel_hi:[0,1]

.LBB0_1796:
	v_or_b32_e32 v34, 3, v80
	s_andn2_b64 vcc, exec, s[14:15]
	v_min_i32_e32 v68, 0x7fff, v34
	s_cbranch_vccnz .LBB0_1798
	s_load_dwordx2 s[14:15], s[0:1], 0x148
	v_ashrrev_i32_e32 v69, 31, v68
	v_lshlrev_b64 v[32:33], 8, v[68:69]
	v_mov_b32_e32 v173, v161
	v_mov_b32_e32 v34, v35
	s_waitcnt lgkmcnt(0)
	v_lshl_add_u64 v[32:33], s[14:15], 0, v[32:33]
	v_lshl_add_u64 v[32:33], v[32:33], 0, v[172:173]
	v_mov_b32_e32 v32, v134
	v_mov_b32_e32 v33, v135
	v_mov_b32_e32 v50, v51
	s_waitcnt vmcnt(0)
	v_pk_mul_f32 v[34:35], v[34:35], v[32:33] op_sel:[0,1] op_sel_hi:[0,0]
	v_pk_fma_f32 v[70:71], v[50:51], v[32:33], v[34:35] op_sel_hi:[0,1,1] neg_lo:[0,0,1] neg_hi:[0,0,1]
	v_pk_fma_f32 v[32:33], v[50:51], v[32:33], v[34:35] op_sel_hi:[0,1,1]
	v_mov_b32_e32 v71, v33
	v_pk_mul_f32 v[32:33], v[174:175], v[70:71] op_sel_hi:[0,1]

.LBB0_1802:
	v_add_u32_e32 v34, 8, v80
	s_andn2_b64 vcc, exec, s[14:15]
	v_min_i32_e32 v50, 0x7fff, v34
	s_cbranch_vccnz .LBB0_1804
	s_load_dwordx2 s[14:15], s[0:1], 0x148
	v_ashrrev_i32_e32 v51, 31, v50
	v_lshlrev_b64 v[32:33], 8, v[50:51]
	v_mov_b32_e32 v173, v161
	s_waitcnt lgkmcnt(0)
	v_lshl_add_u64 v[32:33], s[14:15], 0, v[32:33]
	v_lshl_add_u64 v[32:33], v[32:33], 0, v[172:173]
	v_mov_b32_e32 v32, v136
	v_mov_b32_e32 v33, v137
	s_waitcnt vmcnt(0)
	v_pk_mul_f32 v[34:35], v[36:37], v[32:33] op_sel:[0,1] op_sel_hi:[0,0]
	v_pk_fma_f32 v[70:71], v[52:53], v[32:33], v[34:35] neg_lo:[0,0,1] neg_hi:[0,0,1]
	v_pk_fma_f32 v[32:33], v[52:53], v[32:33], v[34:35] op_sel_hi:[0,1,1]
	v_mov_b32_e32 v71, v33
	v_pk_mul_f32 v[32:33], v[174:175], v[70:71] op_sel_hi:[0,1]

.LBB0_1808:
	v_add_u32_e32 v34, 9, v80
	s_andn2_b64 vcc, exec, s[14:15]
	v_min_i32_e32 v70, 0x7fff, v34
	s_cbranch_vccnz .LBB0_1810
	s_load_dwordx2 s[14:15], s[0:1], 0x148
	v_ashrrev_i32_e32 v71, 31, v70
	v_lshlrev_b64 v[32:33], 8, v[70:71]
	v_mov_b32_e32 v173, v161
	v_mov_b32_e32 v34, v37
	s_waitcnt lgkmcnt(0)
	v_lshl_add_u64 v[32:33], s[14:15], 0, v[32:33]
	v_lshl_add_u64 v[32:33], v[32:33], 0, v[172:173]
	v_mov_b32_e32 v32, v138
	v_mov_b32_e32 v33, v139
	v_mov_b32_e32 v36, v53
	s_waitcnt vmcnt(0)
	v_pk_mul_f32 v[34:35], v[34:35], v[32:33] op_sel:[0,1] op_sel_hi:[0,0]
	v_pk_fma_f32 v[52:53], v[36:37], v[32:33], v[34:35] op_sel_hi:[0,1,1] neg_lo:[0,0,1] neg_hi:[0,0,1]
	v_pk_fma_f32 v[32:33], v[36:37], v[32:33], v[34:35] op_sel_hi:[0,1,1]
	v_mov_b32_e32 v53, v33
	v_pk_mul_f32 v[32:33], v[174:175], v[52:53] op_sel_hi:[0,1]

.LBB0_1814:
	v_add_u32_e32 v34, 10, v80
	s_andn2_b64 vcc, exec, s[14:15]
	v_min_i32_e32 v52, 0x7fff, v34
	s_cbranch_vccnz .LBB0_1816
	s_load_dwordx2 s[14:15], s[0:1], 0x148
	v_ashrrev_i32_e32 v53, 31, v52
	v_lshlrev_b64 v[32:33], 8, v[52:53]
	v_mov_b32_e32 v173, v161
	s_waitcnt lgkmcnt(0)
	v_lshl_add_u64 v[32:33], s[14:15], 0, v[32:33]
	v_lshl_add_u64 v[32:33], v[32:33], 0, v[172:173]
	v_mov_b32_e32 v32, v140
	v_mov_b32_e32 v33, v141
	s_waitcnt vmcnt(0)
	v_pk_mul_f32 v[34:35], v[38:39], v[32:33] op_sel:[0,1] op_sel_hi:[0,0]
	v_pk_fma_f32 v[36:37], v[54:55], v[32:33], v[34:35] neg_lo:[0,0,1] neg_hi:[0,0,1]
	v_pk_fma_f32 v[32:33], v[54:55], v[32:33], v[34:35] op_sel_hi:[0,1,1]
	v_mov_b32_e32 v37, v33
	v_pk_mul_f32 v[32:33], v[174:175], v[36:37] op_sel_hi:[0,1]

.LBB0_1820:
	v_add_u32_e32 v34, 11, v80
	s_andn2_b64 vcc, exec, s[14:15]
	v_min_i32_e32 v72, 0x7fff, v34
	s_cbranch_vccnz .LBB0_1822
	s_load_dwordx2 s[14:15], s[0:1], 0x148
	v_ashrrev_i32_e32 v73, 31, v72
	v_lshlrev_b64 v[32:33], 8, v[72:73]
	v_mov_b32_e32 v173, v161
	v_mov_b32_e32 v34, v39
	s_waitcnt lgkmcnt(0)
	v_lshl_add_u64 v[32:33], s[14:15], 0, v[32:33]
	v_lshl_add_u64 v[32:33], v[32:33], 0, v[172:173]
	v_mov_b32_e32 v32, v142
	v_mov_b32_e32 v33, v143
	v_mov_b32_e32 v36, v55
	s_waitcnt vmcnt(0)
	v_pk_mul_f32 v[34:35], v[34:35], v[32:33] op_sel:[0,1] op_sel_hi:[0,0]
	v_pk_fma_f32 v[38:39], v[36:37], v[32:33], v[34:35] op_sel_hi:[0,1,1] neg_lo:[0,0,1] neg_hi:[0,0,1]
	v_pk_fma_f32 v[32:33], v[36:37], v[32:33], v[34:35] op_sel_hi:[0,1,1]
	v_mov_b32_e32 v39, v33
	v_pk_mul_f32 v[32:33], v[174:175], v[38:39] op_sel_hi:[0,1]

.LBB0_1826:
	v_add_u32_e32 v34, 16, v80
	s_andn2_b64 vcc, exec, s[14:15]
	v_min_i32_e32 v54, 0x7fff, v34
	s_cbranch_vccnz .LBB0_1828
	s_load_dwordx2 s[14:15], s[0:1], 0x148
	v_ashrrev_i32_e32 v55, 31, v54
	v_lshlrev_b64 v[32:33], 8, v[54:55]
	v_mov_b32_e32 v173, v161
	s_waitcnt lgkmcnt(0)
	v_lshl_add_u64 v[32:33], s[14:15], 0, v[32:33]
	v_lshl_add_u64 v[32:33], v[32:33], 0, v[172:173]
	v_mov_b32_e32 v32, v144
	v_mov_b32_e32 v33, v145
	s_waitcnt vmcnt(0)
	v_pk_mul_f32 v[34:35], v[40:41], v[32:33] op_sel:[0,1] op_sel_hi:[0,0]
	v_pk_fma_f32 v[36:37], v[56:57], v[32:33], v[34:35] neg_lo:[0,0,1] neg_hi:[0,0,1]
	v_pk_fma_f32 v[32:33], v[56:57], v[32:33], v[34:35] op_sel_hi:[0,1,1]
	v_mov_b32_e32 v37, v33
	v_pk_mul_f32 v[32:33], v[174:175], v[36:37] op_sel_hi:[0,1]

.LBB0_1832:
	v_add_u32_e32 v34, 17, v80
	s_andn2_b64 vcc, exec, s[14:15]
	v_min_i32_e32 v74, 0x7fff, v34
	s_cbranch_vccnz .LBB0_1834
	s_load_dwordx2 s[14:15], s[0:1], 0x148
	v_ashrrev_i32_e32 v75, 31, v74
	v_lshlrev_b64 v[32:33], 8, v[74:75]
	v_mov_b32_e32 v173, v161
	v_mov_b32_e32 v34, v41
	s_waitcnt lgkmcnt(0)
	v_lshl_add_u64 v[32:33], s[14:15], 0, v[32:33]
	v_lshl_add_u64 v[32:33], v[32:33], 0, v[172:173]
	v_mov_b32_e32 v32, v146
	v_mov_b32_e32 v33, v147
	v_mov_b32_e32 v36, v57
	s_waitcnt vmcnt(0)
	v_pk_mul_f32 v[34:35], v[34:35], v[32:33] op_sel:[0,1] op_sel_hi:[0,0]
	v_pk_fma_f32 v[38:39], v[36:37], v[32:33], v[34:35] op_sel_hi:[0,1,1] neg_lo:[0,0,1] neg_hi:[0,0,1]
	v_pk_fma_f32 v[32:33], v[36:37], v[32:33], v[34:35] op_sel_hi:[0,1,1]
	v_mov_b32_e32 v39, v33
	v_pk_mul_f32 v[32:33], v[174:175], v[38:39] op_sel_hi:[0,1]

.LBB0_1838:
	v_add_u32_e32 v34, 18, v80
	s_andn2_b64 vcc, exec, s[14:15]
	v_min_i32_e32 v56, 0x7fff, v34
	s_cbranch_vccnz .LBB0_1840
	s_load_dwordx2 s[14:15], s[0:1], 0x148
	v_ashrrev_i32_e32 v57, 31, v56
	v_lshlrev_b64 v[32:33], 8, v[56:57]
	v_mov_b32_e32 v173, v161
	s_waitcnt lgkmcnt(0)
	v_lshl_add_u64 v[32:33], s[14:15], 0, v[32:33]
	v_lshl_add_u64 v[32:33], v[32:33], 0, v[172:173]
	v_mov_b32_e32 v32, v148
	v_mov_b32_e32 v33, v149
	s_waitcnt vmcnt(0)
	v_pk_mul_f32 v[34:35], v[42:43], v[32:33] op_sel:[0,1] op_sel_hi:[0,0]
	v_pk_fma_f32 v[36:37], v[58:59], v[32:33], v[34:35] neg_lo:[0,0,1] neg_hi:[0,0,1]
	v_pk_fma_f32 v[32:33], v[58:59], v[32:33], v[34:35] op_sel_hi:[0,1,1]
	v_mov_b32_e32 v37, v33
	v_pk_mul_f32 v[32:33], v[174:175], v[36:37] op_sel_hi:[0,1]

.LBB0_1844:
	v_add_u32_e32 v34, 19, v80
	s_andn2_b64 vcc, exec, s[14:15]
	v_min_i32_e32 v76, 0x7fff, v34
	s_cbranch_vccnz .LBB0_1846
	s_load_dwordx2 s[14:15], s[0:1], 0x148
	v_ashrrev_i32_e32 v77, 31, v76
	v_lshlrev_b64 v[32:33], 8, v[76:77]
	v_mov_b32_e32 v173, v161
	v_mov_b32_e32 v34, v43
	s_waitcnt lgkmcnt(0)
	v_lshl_add_u64 v[32:33], s[14:15], 0, v[32:33]
	v_lshl_add_u64 v[32:33], v[32:33], 0, v[172:173]
	v_mov_b32_e32 v32, v150
	v_mov_b32_e32 v33, v151
	v_mov_b32_e32 v36, v59
	s_waitcnt vmcnt(0)
	v_pk_mul_f32 v[34:35], v[34:35], v[32:33] op_sel:[0,1] op_sel_hi:[0,0]
	v_pk_fma_f32 v[38:39], v[36:37], v[32:33], v[34:35] op_sel_hi:[0,1,1] neg_lo:[0,0,1] neg_hi:[0,0,1]
	v_pk_fma_f32 v[32:33], v[36:37], v[32:33], v[34:35] op_sel_hi:[0,1,1]
	v_mov_b32_e32 v39, v33
	v_pk_mul_f32 v[32:33], v[174:175], v[38:39] op_sel_hi:[0,1]

.LBB0_1850:
	v_add_u32_e32 v34, 24, v80
	s_andn2_b64 vcc, exec, s[14:15]
	v_min_i32_e32 v58, 0x7fff, v34
	s_cbranch_vccnz .LBB0_1852
	s_load_dwordx2 s[14:15], s[0:1], 0x148
	v_ashrrev_i32_e32 v59, 31, v58
	v_lshlrev_b64 v[32:33], 8, v[58:59]
	v_mov_b32_e32 v173, v161
	s_waitcnt lgkmcnt(0)
	v_lshl_add_u64 v[32:33], s[14:15], 0, v[32:33]
	v_lshl_add_u64 v[32:33], v[32:33], 0, v[172:173]
	v_mov_b32_e32 v32, v152
	v_mov_b32_e32 v33, v153
	s_waitcnt vmcnt(0)
	v_pk_mul_f32 v[34:35], v[44:45], v[32:33] op_sel:[0,1] op_sel_hi:[0,0]
	v_pk_fma_f32 v[36:37], v[60:61], v[32:33], v[34:35] neg_lo:[0,0,1] neg_hi:[0,0,1]
	v_pk_fma_f32 v[32:33], v[60:61], v[32:33], v[34:35] op_sel_hi:[0,1,1]
	v_mov_b32_e32 v37, v33
	v_pk_mul_f32 v[32:33], v[174:175], v[36:37] op_sel_hi:[0,1]

.LBB0_1856:
	v_add_u32_e32 v34, 25, v80
	s_andn2_b64 vcc, exec, s[14:15]
	v_min_i32_e32 v78, 0x7fff, v34
	s_cbranch_vccnz .LBB0_1858
	s_load_dwordx2 s[14:15], s[0:1], 0x148
	v_ashrrev_i32_e32 v79, 31, v78
	v_lshlrev_b64 v[32:33], 8, v[78:79]
	v_mov_b32_e32 v173, v161
	v_mov_b32_e32 v34, v45
	s_waitcnt lgkmcnt(0)
	v_lshl_add_u64 v[32:33], s[14:15], 0, v[32:33]
	v_lshl_add_u64 v[32:33], v[32:33], 0, v[172:173]
	v_mov_b32_e32 v32, v154
	v_mov_b32_e32 v33, v155
	v_mov_b32_e32 v36, v61
	s_waitcnt vmcnt(0)
	v_pk_mul_f32 v[34:35], v[34:35], v[32:33] op_sel:[0,1] op_sel_hi:[0,0]
	v_pk_fma_f32 v[38:39], v[36:37], v[32:33], v[34:35] op_sel_hi:[0,1,1] neg_lo:[0,0,1] neg_hi:[0,0,1]
	v_pk_fma_f32 v[32:33], v[36:37], v[32:33], v[34:35] op_sel_hi:[0,1,1]
	v_mov_b32_e32 v39, v33
	v_pk_mul_f32 v[32:33], v[174:175], v[38:39] op_sel_hi:[0,1]

.LBB0_1862:
	v_add_u32_e32 v34, 26, v80
	s_andn2_b64 vcc, exec, s[14:15]
	v_min_i32_e32 v44, 0x7fff, v34
	s_cbranch_vccnz .LBB0_1864
	s_load_dwordx2 s[14:15], s[0:1], 0x148
	v_ashrrev_i32_e32 v45, 31, v44
	v_lshlrev_b64 v[32:33], 8, v[44:45]
	v_mov_b32_e32 v173, v161
	s_waitcnt lgkmcnt(0)
	v_lshl_add_u64 v[32:33], s[14:15], 0, v[32:33]
	v_lshl_add_u64 v[32:33], v[32:33], 0, v[172:173]
	v_mov_b32_e32 v32, v156
	v_mov_b32_e32 v33, v157
	s_waitcnt vmcnt(0)
	v_pk_mul_f32 v[34:35], v[46:47], v[32:33] op_sel:[0,1] op_sel_hi:[0,0]
	v_pk_fma_f32 v[36:37], v[62:63], v[32:33], v[34:35] neg_lo:[0,0,1] neg_hi:[0,0,1]
	v_pk_fma_f32 v[32:33], v[62:63], v[32:33], v[34:35] op_sel_hi:[0,1,1]
	v_mov_b32_e32 v37, v33
	v_pk_mul_f32 v[32:33], v[174:175], v[36:37] op_sel_hi:[0,1]

.LBB0_1868:
	v_add_u32_e32 v34, 27, v80
	s_andn2_b64 vcc, exec, s[6:7]
	v_min_i32_e32 v60, 0x7fff, v34
	s_cbranch_vccnz .LBB0_1870
	s_load_dwordx2 s[2:3], s[0:1], 0x148
	v_ashrrev_i32_e32 v61, 31, v60
	v_lshlrev_b64 v[32:33], 8, v[60:61]
	v_mov_b32_e32 v173, v161
	v_mov_b32_e32 v34, v47
	s_waitcnt lgkmcnt(0)
	v_lshl_add_u64 v[32:33], s[2:3], 0, v[32:33]
	v_lshl_add_u64 v[32:33], v[32:33], 0, v[172:173]
	v_mov_b32_e32 v32, v158
	v_mov_b32_e32 v33, v159
	v_mov_b32_e32 v36, v63
	s_waitcnt vmcnt(0)
	v_pk_mul_f32 v[34:35], v[34:35], v[32:33] op_sel:[0,1] op_sel_hi:[0,0]
	v_pk_fma_f32 v[38:39], v[36:37], v[32:33], v[34:35] op_sel_hi:[0,1,1] neg_lo:[0,0,1] neg_hi:[0,0,1]
	v_pk_fma_f32 v[32:33], v[36:37], v[32:33], v[34:35] op_sel_hi:[0,1,1]
	v_mov_b32_e32 v39, v33
	v_pk_mul_f32 v[32:33], v[174:175], v[38:39] op_sel_hi:[0,1]

.LBB0_1931:
	s_load_dwordx2 s[12:13], s[0:1], 0x148
	v_lshlrev_b64 v[32:33], 8, v[66:67]
	v_mov_b32_e32 v173, v161
	s_waitcnt lgkmcnt(0)
	v_lshl_add_u64 v[32:33], s[12:13], 0, v[32:33]
	v_lshl_add_u64 v[32:33], v[32:33], 0, v[172:173]
	global_load_dwordx2 v[128:129], v[32:33], off
	global_load_dwordx2 v[130:131], v[32:33], off offset:256
	global_load_dwordx2 v[132:133], v[32:33], off offset:512
	global_load_dwordx2 v[134:135], v[32:33], off offset:768
	global_load_dwordx2 v[136:137], v[32:33], off offset:2048
	global_load_dwordx2 v[138:139], v[32:33], off offset:2304
	global_load_dwordx2 v[140:141], v[32:33], off offset:2560
	global_load_dwordx2 v[142:143], v[32:33], off offset:2816
	s_mov_b64 s[98:99], 0x1000
	v_lshl_add_u64 v[158:159], v[32:33], 0, s[98:99]
	global_load_dwordx2 v[144:145], v[158:159], off offset:0
	global_load_dwordx2 v[146:147], v[158:159], off offset:256
	global_load_dwordx2 v[148:149], v[158:159], off offset:512
	global_load_dwordx2 v[150:151], v[158:159], off offset:768
	global_load_dwordx2 v[152:153], v[158:159], off offset:2048
	global_load_dwordx2 v[154:155], v[158:159], off offset:2304
	global_load_dwordx2 v[156:157], v[158:159], off offset:2560
	global_load_dwordx2 v[158:159], v[158:159], off offset:2816
	s_waitcnt vmcnt(0)
	v_mov_b32_e32 v32, v128
	v_mov_b32_e32 v33, v129
	v_pk_mul_f32 v[34:35], v[0:1], v[32:33] op_sel:[0,1] op_sel_hi:[0,0]
	v_pk_fma_f32 v[46:47], v[16:17], v[32:33], v[34:35] neg_lo:[0,0,1] neg_hi:[0,0,1]
	v_pk_fma_f32 v[32:33], v[16:17], v[32:33], v[34:35] op_sel_hi:[0,1,1]
	v_mov_b32_e32 v47, v33
	v_pk_mul_f32 v[32:33], v[96:97], v[46:47] op_sel_hi:[0,1]

.LBB0_1936:
	s_andn2_b64 vcc, exec, s[12:13]
	s_cbranch_vccnz .LBB0_1938
	s_load_dwordx2 s[12:13], s[0:1], 0x148
	v_ashrrev_i32_e32 v65, 31, v64
	v_lshlrev_b64 v[32:33], 8, v[64:65]
	v_mov_b32_e32 v173, v161
	s_waitcnt lgkmcnt(0)
	v_lshl_add_u64 v[32:33], s[12:13], 0, v[32:33]
	v_lshl_add_u64 v[32:33], v[32:33], 0, v[172:173]
	v_mov_b32_e32 v32, v130
	v_mov_b32_e32 v33, v131
	s_waitcnt vmcnt(0)
	v_pk_mul_f32 v[0:1], v[0:1], v[32:33] op_sel:[1,1] op_sel_hi:[1,0]
	s_nop 0
	v_pk_fma_f32 v[34:35], v[16:17], v[32:33], v[0:1] op_sel:[1,0,0] neg_lo:[0,0,1] neg_hi:[0,0,1]
	v_pk_fma_f32 v[0:1], v[16:17], v[32:33], v[0:1] op_sel:[1,0,0]
	s_nop 0
	v_mov_b32_e32 v35, v1
	v_pk_mul_f32 v[32:33], v[96:97], v[34:35] op_sel_hi:[0,1]

.LBB0_1942:
	s_andn2_b64 vcc, exec, s[12:13]
	s_cbranch_vccnz .LBB0_1944
	s_load_dwordx2 s[12:13], s[0:1], 0x148
	v_ashrrev_i32_e32 v49, 31, v48
	v_lshlrev_b64 v[0:1], 8, v[48:49]
	v_mov_b32_e32 v173, v161
	s_waitcnt lgkmcnt(0)
	v_lshl_add_u64 v[0:1], s[12:13], 0, v[0:1]
	v_lshl_add_u64 v[0:1], v[0:1], 0, v[172:173]
	v_mov_b32_e32 v0, v132
	v_mov_b32_e32 v1, v133
	s_waitcnt vmcnt(0)
	v_pk_mul_f32 v[16:17], v[2:3], v[0:1] op_sel:[0,1] op_sel_hi:[0,0]
	v_pk_fma_f32 v[32:33], v[18:19], v[0:1], v[16:17] neg_lo:[0,0,1] neg_hi:[0,0,1]
	v_pk_fma_f32 v[0:1], v[18:19], v[0:1], v[16:17] op_sel_hi:[0,1,1]
	v_mov_b32_e32 v33, v1
	v_pk_mul_f32 v[0:1], v[96:97], v[32:33] op_sel_hi:[0,1]

.LBB0_1948:
	s_andn2_b64 vcc, exec, s[12:13]
	s_cbranch_vccnz .LBB0_1950
	s_load_dwordx2 s[12:13], s[0:1], 0x148
	v_ashrrev_i32_e32 v69, 31, v68
	v_lshlrev_b64 v[0:1], 8, v[68:69]
	v_mov_b32_e32 v173, v161
	v_mov_b32_e32 v2, v3
	s_waitcnt lgkmcnt(0)
	v_lshl_add_u64 v[0:1], s[12:13], 0, v[0:1]
	v_lshl_add_u64 v[0:1], v[0:1], 0, v[172:173]
	v_mov_b32_e32 v0, v134
	v_mov_b32_e32 v1, v135
	v_mov_b32_e32 v16, v19
	s_waitcnt vmcnt(0)
	v_pk_mul_f32 v[2:3], v[2:3], v[0:1] op_sel:[0,1] op_sel_hi:[0,0]
	v_pk_fma_f32 v[18:19], v[16:17], v[0:1], v[2:3] op_sel_hi:[0,1,1] neg_lo:[0,0,1] neg_hi:[0,0,1]
	v_pk_fma_f32 v[0:1], v[16:17], v[0:1], v[2:3] op_sel_hi:[0,1,1]
	v_mov_b32_e32 v19, v1
	v_pk_mul_f32 v[0:1], v[96:97], v[18:19] op_sel_hi:[0,1]

.LBB0_1954:
	s_andn2_b64 vcc, exec, s[12:13]
	s_cbranch_vccnz .LBB0_1956
	s_load_dwordx2 s[12:13], s[0:1], 0x148
	v_ashrrev_i32_e32 v51, 31, v50
	v_lshlrev_b64 v[0:1], 8, v[50:51]
	v_mov_b32_e32 v173, v161
	s_waitcnt lgkmcnt(0)
	v_lshl_add_u64 v[0:1], s[12:13], 0, v[0:1]
	v_lshl_add_u64 v[0:1], v[0:1], 0, v[172:173]
	v_mov_b32_e32 v0, v136
	v_mov_b32_e32 v1, v137
	s_waitcnt vmcnt(0)
	v_pk_mul_f32 v[2:3], v[4:5], v[0:1] op_sel:[0,1] op_sel_hi:[0,0]
	v_pk_fma_f32 v[16:17], v[20:21], v[0:1], v[2:3] neg_lo:[0,0,1] neg_hi:[0,0,1]
	v_pk_fma_f32 v[0:1], v[20:21], v[0:1], v[2:3] op_sel_hi:[0,1,1]
	v_mov_b32_e32 v17, v1
	v_pk_mul_f32 v[0:1], v[96:97], v[16:17] op_sel_hi:[0,1]

.LBB0_1960:
	s_andn2_b64 vcc, exec, s[12:13]
	s_cbranch_vccnz .LBB0_1962
	s_load_dwordx2 s[12:13], s[0:1], 0x148
	v_ashrrev_i32_e32 v71, 31, v70
	v_lshlrev_b64 v[0:1], 8, v[70:71]
	v_mov_b32_e32 v173, v161
	v_mov_b32_e32 v2, v5
	s_waitcnt lgkmcnt(0)
	v_lshl_add_u64 v[0:1], s[12:13], 0, v[0:1]
	v_lshl_add_u64 v[0:1], v[0:1], 0, v[172:173]
	v_mov_b32_e32 v0, v138
	v_mov_b32_e32 v1, v139
	v_mov_b32_e32 v4, v21
	s_waitcnt vmcnt(0)
	v_pk_mul_f32 v[2:3], v[2:3], v[0:1] op_sel:[0,1] op_sel_hi:[0,0]
	v_pk_fma_f32 v[16:17], v[4:5], v[0:1], v[2:3] op_sel_hi:[0,1,1] neg_lo:[0,0,1] neg_hi:[0,0,1]
	v_pk_fma_f32 v[0:1], v[4:5], v[0:1], v[2:3] op_sel_hi:[0,1,1]
	v_mov_b32_e32 v17, v1
	v_pk_mul_f32 v[0:1], v[96:97], v[16:17] op_sel_hi:[0,1]

.LBB0_1966:
	s_andn2_b64 vcc, exec, s[12:13]
	s_cbranch_vccnz .LBB0_1968
	s_load_dwordx2 s[12:13], s[0:1], 0x148
	v_ashrrev_i32_e32 v53, 31, v52
	v_lshlrev_b64 v[0:1], 8, v[52:53]
	v_mov_b32_e32 v173, v161
	s_waitcnt lgkmcnt(0)
	v_lshl_add_u64 v[0:1], s[12:13], 0, v[0:1]
	v_lshl_add_u64 v[0:1], v[0:1], 0, v[172:173]
	v_mov_b32_e32 v0, v140
	v_mov_b32_e32 v1, v141
	s_waitcnt vmcnt(0)
	v_pk_mul_f32 v[2:3], v[6:7], v[0:1] op_sel:[0,1] op_sel_hi:[0,0]
	v_pk_fma_f32 v[4:5], v[22:23], v[0:1], v[2:3] neg_lo:[0,0,1] neg_hi:[0,0,1]
	v_pk_fma_f32 v[0:1], v[22:23], v[0:1], v[2:3] op_sel_hi:[0,1,1]
	v_mov_b32_e32 v5, v1
	v_pk_mul_f32 v[0:1], v[96:97], v[4:5] op_sel_hi:[0,1]

.LBB0_1972:
	s_andn2_b64 vcc, exec, s[12:13]
	s_cbranch_vccnz .LBB0_1974
	s_load_dwordx2 s[12:13], s[0:1], 0x148
	v_ashrrev_i32_e32 v73, 31, v72
	v_lshlrev_b64 v[0:1], 8, v[72:73]
	v_mov_b32_e32 v173, v161
	v_mov_b32_e32 v2, v7
	s_waitcnt lgkmcnt(0)
	v_lshl_add_u64 v[0:1], s[12:13], 0, v[0:1]
	v_lshl_add_u64 v[0:1], v[0:1], 0, v[172:173]
	v_mov_b32_e32 v0, v142
	v_mov_b32_e32 v1, v143
	v_mov_b32_e32 v4, v23
	s_waitcnt vmcnt(0)
	v_pk_mul_f32 v[2:3], v[2:3], v[0:1] op_sel:[0,1] op_sel_hi:[0,0]
	v_pk_fma_f32 v[6:7], v[4:5], v[0:1], v[2:3] op_sel_hi:[0,1,1] neg_lo:[0,0,1] neg_hi:[0,0,1]
	v_pk_fma_f32 v[0:1], v[4:5], v[0:1], v[2:3] op_sel_hi:[0,1,1]
	v_mov_b32_e32 v7, v1
	v_pk_mul_f32 v[0:1], v[96:97], v[6:7] op_sel_hi:[0,1]

.LBB0_1978:
	s_andn2_b64 vcc, exec, s[12:13]
	s_cbranch_vccnz .LBB0_1980
	s_load_dwordx2 s[12:13], s[0:1], 0x148
	v_ashrrev_i32_e32 v55, 31, v54
	v_lshlrev_b64 v[0:1], 8, v[54:55]
	v_mov_b32_e32 v173, v161
	s_waitcnt lgkmcnt(0)
	v_lshl_add_u64 v[0:1], s[12:13], 0, v[0:1]
	v_lshl_add_u64 v[0:1], v[0:1], 0, v[172:173]
	v_mov_b32_e32 v0, v144
	v_mov_b32_e32 v1, v145
	s_waitcnt vmcnt(0)
	v_pk_mul_f32 v[2:3], v[8:9], v[0:1] op_sel:[0,1] op_sel_hi:[0,0]
	v_pk_fma_f32 v[4:5], v[24:25], v[0:1], v[2:3] neg_lo:[0,0,1] neg_hi:[0,0,1]
	v_pk_fma_f32 v[0:1], v[24:25], v[0:1], v[2:3] op_sel_hi:[0,1,1]
	v_mov_b32_e32 v5, v1
	v_pk_mul_f32 v[0:1], v[96:97], v[4:5] op_sel_hi:[0,1]

.LBB0_1984:
	s_andn2_b64 vcc, exec, s[12:13]
	s_cbranch_vccnz .LBB0_1986
	s_load_dwordx2 s[12:13], s[0:1], 0x148
	v_ashrrev_i32_e32 v75, 31, v74
	v_lshlrev_b64 v[0:1], 8, v[74:75]
	v_mov_b32_e32 v173, v161
	v_mov_b32_e32 v2, v9
	s_waitcnt lgkmcnt(0)
	v_lshl_add_u64 v[0:1], s[12:13], 0, v[0:1]
	v_lshl_add_u64 v[0:1], v[0:1], 0, v[172:173]
	v_mov_b32_e32 v0, v146
	v_mov_b32_e32 v1, v147
	v_mov_b32_e32 v4, v25
	s_waitcnt vmcnt(0)
	v_pk_mul_f32 v[2:3], v[2:3], v[0:1] op_sel:[0,1] op_sel_hi:[0,0]
	v_pk_fma_f32 v[6:7], v[4:5], v[0:1], v[2:3] op_sel_hi:[0,1,1] neg_lo:[0,0,1] neg_hi:[0,0,1]
	v_pk_fma_f32 v[0:1], v[4:5], v[0:1], v[2:3] op_sel_hi:[0,1,1]
	v_mov_b32_e32 v7, v1
	v_pk_mul_f32 v[0:1], v[96:97], v[6:7] op_sel_hi:[0,1]

.LBB0_1990:
	s_andn2_b64 vcc, exec, s[12:13]
	s_cbranch_vccnz .LBB0_1992
	s_load_dwordx2 s[12:13], s[0:1], 0x148
	v_ashrrev_i32_e32 v57, 31, v56
	v_lshlrev_b64 v[0:1], 8, v[56:57]
	v_mov_b32_e32 v173, v161
	s_waitcnt lgkmcnt(0)
	v_lshl_add_u64 v[0:1], s[12:13], 0, v[0:1]
	v_lshl_add_u64 v[0:1], v[0:1], 0, v[172:173]
	v_mov_b32_e32 v0, v148
	v_mov_b32_e32 v1, v149
	s_waitcnt vmcnt(0)
	v_pk_mul_f32 v[2:3], v[10:11], v[0:1] op_sel:[0,1] op_sel_hi:[0,0]
	v_pk_fma_f32 v[4:5], v[26:27], v[0:1], v[2:3] neg_lo:[0,0,1] neg_hi:[0,0,1]
	v_pk_fma_f32 v[0:1], v[26:27], v[0:1], v[2:3] op_sel_hi:[0,1,1]
	v_mov_b32_e32 v5, v1
	v_pk_mul_f32 v[0:1], v[96:97], v[4:5] op_sel_hi:[0,1]

.LBB0_1996:
	s_andn2_b64 vcc, exec, s[12:13]
	s_cbranch_vccnz .LBB0_1998
	s_load_dwordx2 s[12:13], s[0:1], 0x148
	v_ashrrev_i32_e32 v77, 31, v76
	v_lshlrev_b64 v[0:1], 8, v[76:77]
	v_mov_b32_e32 v173, v161
	v_mov_b32_e32 v2, v11
	s_waitcnt lgkmcnt(0)
	v_lshl_add_u64 v[0:1], s[12:13], 0, v[0:1]
	v_lshl_add_u64 v[0:1], v[0:1], 0, v[172:173]
	v_mov_b32_e32 v0, v150
	v_mov_b32_e32 v1, v151
	v_mov_b32_e32 v4, v27
	s_waitcnt vmcnt(0)
	v_pk_mul_f32 v[2:3], v[2:3], v[0:1] op_sel:[0,1] op_sel_hi:[0,0]
	v_pk_fma_f32 v[6:7], v[4:5], v[0:1], v[2:3] op_sel_hi:[0,1,1] neg_lo:[0,0,1] neg_hi:[0,0,1]
	v_pk_fma_f32 v[0:1], v[4:5], v[0:1], v[2:3] op_sel_hi:[0,1,1]
	v_mov_b32_e32 v7, v1
	v_pk_mul_f32 v[0:1], v[96:97], v[6:7] op_sel_hi:[0,1]

.LBB0_2002:
	s_andn2_b64 vcc, exec, s[12:13]
	s_cbranch_vccnz .LBB0_2004
	s_load_dwordx2 s[12:13], s[0:1], 0x148
	v_ashrrev_i32_e32 v59, 31, v58
	v_lshlrev_b64 v[0:1], 8, v[58:59]
	v_mov_b32_e32 v173, v161
	s_waitcnt lgkmcnt(0)
	v_lshl_add_u64 v[0:1], s[12:13], 0, v[0:1]
	v_lshl_add_u64 v[0:1], v[0:1], 0, v[172:173]
	v_mov_b32_e32 v0, v152
	v_mov_b32_e32 v1, v153
	s_waitcnt vmcnt(0)
	v_pk_mul_f32 v[2:3], v[12:13], v[0:1] op_sel:[0,1] op_sel_hi:[0,0]
	v_pk_fma_f32 v[4:5], v[28:29], v[0:1], v[2:3] neg_lo:[0,0,1] neg_hi:[0,0,1]
	v_pk_fma_f32 v[0:1], v[28:29], v[0:1], v[2:3] op_sel_hi:[0,1,1]
	v_mov_b32_e32 v5, v1
	v_pk_mul_f32 v[0:1], v[96:97], v[4:5] op_sel_hi:[0,1]

.LBB0_2008:
	s_andn2_b64 vcc, exec, s[12:13]
	s_cbranch_vccnz .LBB0_2010
	s_load_dwordx2 s[12:13], s[0:1], 0x148
	v_ashrrev_i32_e32 v79, 31, v78
	v_lshlrev_b64 v[0:1], 8, v[78:79]
	v_mov_b32_e32 v173, v161
	v_mov_b32_e32 v2, v13
	s_waitcnt lgkmcnt(0)
	v_lshl_add_u64 v[0:1], s[12:13], 0, v[0:1]
	v_lshl_add_u64 v[0:1], v[0:1], 0, v[172:173]
	v_mov_b32_e32 v0, v154
	v_mov_b32_e32 v1, v155
	v_mov_b32_e32 v4, v29
	s_waitcnt vmcnt(0)
	v_pk_mul_f32 v[2:3], v[2:3], v[0:1] op_sel:[0,1] op_sel_hi:[0,0]
	v_pk_fma_f32 v[6:7], v[4:5], v[0:1], v[2:3] op_sel_hi:[0,1,1] neg_lo:[0,0,1] neg_hi:[0,0,1]
	v_pk_fma_f32 v[0:1], v[4:5], v[0:1], v[2:3] op_sel_hi:[0,1,1]
	v_mov_b32_e32 v7, v1
	v_pk_mul_f32 v[0:1], v[96:97], v[6:7] op_sel_hi:[0,1]

.LBB0_2014:
	s_andn2_b64 vcc, exec, s[12:13]
	s_cbranch_vccnz .LBB0_2016
	s_load_dwordx2 s[12:13], s[0:1], 0x148
	v_ashrrev_i32_e32 v45, 31, v44
	v_lshlrev_b64 v[0:1], 8, v[44:45]
	v_mov_b32_e32 v173, v161
	s_waitcnt lgkmcnt(0)
	v_lshl_add_u64 v[0:1], s[12:13], 0, v[0:1]
	v_lshl_add_u64 v[0:1], v[0:1], 0, v[172:173]
	v_mov_b32_e32 v0, v156
	v_mov_b32_e32 v1, v157
	s_waitcnt vmcnt(0)
	v_pk_mul_f32 v[2:3], v[14:15], v[0:1] op_sel:[0,1] op_sel_hi:[0,0]
	v_pk_fma_f32 v[4:5], v[30:31], v[0:1], v[2:3] neg_lo:[0,0,1] neg_hi:[0,0,1]
	v_pk_fma_f32 v[0:1], v[30:31], v[0:1], v[2:3] op_sel_hi:[0,1,1]
	v_mov_b32_e32 v5, v1
	v_pk_mul_f32 v[0:1], v[96:97], v[4:5] op_sel_hi:[0,1]

.LBB0_2020:
	s_andn2_b64 vcc, exec, s[8:9]
	s_cbranch_vccnz .LBB0_2022
	s_load_dwordx2 s[4:5], s[0:1], 0x148
	v_ashrrev_i32_e32 v61, 31, v60
	v_lshlrev_b64 v[0:1], 8, v[60:61]
	v_mov_b32_e32 v173, v161
	v_mov_b32_e32 v2, v15
	s_waitcnt lgkmcnt(0)
	v_lshl_add_u64 v[0:1], s[4:5], 0, v[0:1]
	v_lshl_add_u64 v[0:1], v[0:1], 0, v[172:173]
	v_mov_b32_e32 v0, v158
	v_mov_b32_e32 v1, v159
	v_mov_b32_e32 v4, v31
	s_waitcnt vmcnt(0)
	v_pk_mul_f32 v[2:3], v[2:3], v[0:1] op_sel:[0,1] op_sel_hi:[0,0]
	v_pk_fma_f32 v[6:7], v[4:5], v[0:1], v[2:3] op_sel_hi:[0,1,1] neg_lo:[0,0,1] neg_hi:[0,0,1]
	v_pk_fma_f32 v[0:1], v[4:5], v[0:1], v[2:3] op_sel_hi:[0,1,1]
	v_mov_b32_e32 v7, v1
	v_pk_mul_f32 v[0:1], v[96:97], v[6:7] op_sel_hi:[0,1]

.LBB0_2131:
	s_cmp_gt_i32 s44, 8
	s_waitcnt lgkmcnt(0)
	s_cselect_b64 s[2:3], -1, 0
	s_cmp_lt_i32 s45, 9
	s_cselect_b64 s[4:5], -1, 0
	s_or_b64 s[2:3], s[2:3], s[4:5]
	s_and_b64 vcc, exec, s[2:3]
	s_cbranch_vccnz .LBB0_2211
	s_cmp_lt_u32 s70, 256
	s_cbranch_scc1 .Lprio_skip_8
	s_setprio 3
.Lprio_skip_8:
	v_mbcnt_hi_u32_b32 v91, -1, v210
	v_mov_b32_e32 v0, v91
	s_and_b32 s3, s42, 7
	v_add_u32_e32 v1, s70, v0
	s_cmp_lg_u32 s3, 0
	v_readfirstlane_b32 s2, v1
	s_mov_b32 s24, s22
	s_cbranch_scc0 .LBB0_2134
	s_cmpk_gt_i32 s24, 0x7ff
	s_cbranch_scc0 .LBB0_2135
	s_branch .LBB0_2157

.LBB0_2157:
	s_setprio 0
	s_cmp_lt_i32 s45, 10
	s_cbranch_scc1 .LBB0_2211
	s_waitcnt vmcnt(0)
	v_cmp_eq_u32_e32 vcc, 0, v91
	s_and_b64 s[4:5], s[46:47], vcc
	s_waitcnt vmcnt(63) expcnt(7) lgkmcnt(15)
	s_barrier
	s_and_saveexec_b64 s[2:3], s[4:5]
	s_cbranch_execz .LBB0_2210
	v_mov_b32_e32 v0, 0x24400
	s_waitcnt vmcnt(0) expcnt(0) lgkmcnt(0)
	ds_read_b32 v2, v0
	v_mov_b32_e32 v0, 0x24404
	ds_read_b32 v0, v0
	s_waitcnt lgkmcnt(1)
	v_cmp_ne_u32_e32 vcc, 0, v2
	s_cbranch_vccnz .LBB0_2174
	s_add_u32 s4, s40, 0x1000
	s_addc_u32 s5, s41, 0
	s_add_u32 s6, s40, 0x1100
	s_addc_u32 s7, s41, 0
	s_add_u32 s8, s40, 0x1200
	s_addc_u32 s9, s41, 0
	s_mul_i32 s18, s43, s33
	s_add_u32 s10, s40, 0x1300
	s_mul_i32 s18, s18, s42
	s_addc_u32 s11, s41, 0
	s_mov_b32 s19, 1
	v_mov_b32_e32 v16, 0
	s_branch .LBB0_2162

.LBB0_4361:
	s_cmp_gt_i32 s44, 15
	s_cselect_b64 s[2:3], -1, 0
	s_cmp_lt_i32 s45, 16
	s_cselect_b64 s[4:5], -1, 0
	s_or_b64 s[2:3], s[2:3], s[4:5]
	s_and_b64 vcc, exec, s[2:3]
	s_cbranch_vccnz .LBB0_4470
	s_cmp_lt_u32 s70, 256
	s_cbranch_scc1 .Lprio_skip_15
	s_setprio 3
.Lprio_skip_15:
	v_mbcnt_hi_u32_b32 v169, -1, v210
	v_mov_b32_e32 v0, v169
	s_mov_b32 s21, 0
	v_add_u32_e32 v1, s70, v0
	s_cmpk_gt_i32 s22, 0x7ff
	v_readfirstlane_b32 s2, v1
	s_cbranch_scc1 .LBB0_4416
	s_abs_i32 s60, s42
	s_waitcnt lgkmcnt(0)
	v_cvt_f32_u32_e32 v4, s60
	v_and_b32_e32 v3, 64, v169
	v_xor_b32_e32 v2, 32, v169
	v_add_u32_e32 v3, 64, v3
	v_cmp_lt_i32_e32 vcc, v2, v3
	v_rcp_iflag_f32_e32 v3, v4
	s_ashr_i32 s56, s42, 31
	v_cndmask_b32_e32 v2, v169, v2, vcc
	v_lshlrev_b32_e32 v175, 2, v2
	v_mul_f32_e32 v2, 0x4f7ffffe, v3
	v_cvt_u32_f32_e32 v2, v2
	s_lshr_b32 s3, s56, 27
	s_add_i32 s3, s42, s3
	s_ashr_i32 s58, s2, 7
	s_lshr_b32 s2, s2, 1
	s_ashr_i32 s57, s3, 5
	s_and_b32 s59, s2, 32
	s_load_dwordx2 s[24:25], s[0:1], 0x190
	s_load_dwordx2 s[2:3], s[0:1], 0x1d8
	s_load_dwordx2 s[26:27], s[0:1], 0x200
	s_load_dwordx4 s[16:19], s[0:1], 0x1f0
	s_sub_i32 s4, 0, s60
	v_readfirstlane_b32 s5, v2
	s_mul_i32 s4, s4, s5
	s_mul_hi_u32 s4, s5, s4
	s_add_i32 s61, s5, s4
	s_waitcnt lgkmcnt(0)
	s_add_u32 s30, s16, 0x2000
	v_and_b32_e32 v168, 31, v0
	v_lshrrev_b32_e32 v0, 2, v0
	s_addc_u32 s31, s17, 0
	v_mov_b32_e32 v1, 0
	v_and_b32_e32 v0, 8, v0
	s_add_u32 s34, s18, 0x2000
	s_mov_b64 s[28:29], 0x2000
	s_addc_u32 s35, s19, 0
	v_lshlrev_b32_e32 v170, 1, v0
	v_mov_b32_e32 v171, v1
	s_movk_i32 s62, 0x60
	v_mov_b64_e32 v[172:173], s[2:3]
	v_mov_b32_e32 v182, 0x60
	v_lshlrev_b32_e32 v183, 3, v168
	s_movk_i32 s63, 0x90
	s_movk_i32 s64, 0xc0
	s_movk_i32 s65, 0xff
	s_mov_b32 s66, 0xff800000
	s_mov_b64 s[36:37], 0x8000
	v_mov_b32_e32 v184, 0x3cf
	v_mov_b32_e32 v185, 0xff800000
	v_mov_b32_e32 v186, 0x7f800000
	s_mov_b32 s67, s22
	s_mov_b32 s68, s22
	s_branch .LBB0_4365

.LBB0_4416:
	s_setprio 0
	s_cmp_lt_i32 s45, 17
	s_cbranch_scc1 .LBB0_4470
	s_waitcnt vmcnt(0)
	v_cmp_eq_u32_e32 vcc, 0, v169
	s_and_b64 s[4:5], s[46:47], vcc
	s_waitcnt lgkmcnt(0)
	s_barrier
	s_and_saveexec_b64 s[2:3], s[4:5]
	s_cbranch_execz .LBB0_4469
	v_mov_b32_e32 v0, 0x24400
	s_waitcnt vmcnt(0) expcnt(0) lgkmcnt(0)
	ds_read_b32 v2, v0
	v_mov_b32_e32 v0, 0x24404
	ds_read_b32 v0, v0
	s_waitcnt lgkmcnt(1)
	v_cmp_ne_u32_e32 vcc, 0, v2
	s_cbranch_vccnz .LBB0_4433
	s_add_u32 s4, s40, 0x1000
	s_addc_u32 s5, s41, 0
	s_add_u32 s6, s40, 0x1100
	s_addc_u32 s7, s41, 0
	s_add_u32 s8, s40, 0x1200
	s_addc_u32 s9, s41, 0
	s_mul_i32 s18, s43, s33
	s_add_u32 s10, s40, 0x1300
	s_mul_i32 s18, s18, s42
	s_addc_u32 s11, s41, 0
	s_mov_b32 s19, 1
	v_mov_b32_e32 v16, 0
	s_branch .LBB0_4421

.LBB0_5559:
	s_cmp_gt_i32 s44, 20
	s_waitcnt lgkmcnt(0)
	s_cselect_b64 s[2:3], -1, 0
	s_cmp_lt_i32 s45, 21
	s_cselect_b64 s[4:5], -1, 0
	s_or_b64 s[2:3], s[2:3], s[4:5]
	s_and_b64 vcc, exec, s[2:3]
	s_cbranch_vccnz .LBB0_5632
	s_cmp_lt_u32 s70, 256
	s_cbranch_scc1 .Lprio_skip_20
	s_setprio 3

.LBB0_5578:
	s_setprio 0
	s_cmp_lt_i32 s45, 22
	s_cbranch_scc1 .LBB0_5632
	s_waitcnt vmcnt(0)
	v_cmp_eq_u32_e32 vcc, 0, v178
	s_and_b64 s[4:5], s[46:47], vcc
	s_waitcnt vmcnt(63) expcnt(7) lgkmcnt(15)
	s_barrier
	s_and_saveexec_b64 s[2:3], s[4:5]
	s_cbranch_execz .LBB0_5631
	v_mov_b32_e32 v0, 0x24400
	s_waitcnt vmcnt(0) expcnt(0) lgkmcnt(0)
	ds_read_b32 v2, v0
	v_mov_b32_e32 v0, 0x24404
	ds_read_b32 v0, v0
	s_waitcnt lgkmcnt(1)
	v_cmp_ne_u32_e32 vcc, 0, v2
	s_cbranch_vccnz .LBB0_5595
	s_add_u32 s4, s40, 0x1000
	s_addc_u32 s5, s41, 0
	s_add_u32 s6, s40, 0x1100
	s_addc_u32 s7, s41, 0
	s_add_u32 s8, s40, 0x1200
	s_addc_u32 s9, s41, 0
	s_mul_i32 s18, s43, s33
	s_add_u32 s10, s40, 0x1300
	s_mul_i32 s18, s18, s42
	s_addc_u32 s11, s41, 0
	s_mov_b32 s19, 1
	v_mov_b32_e32 v16, 0
	s_branch .LBB0_5583

	.amdhsa_kernel _Z4mega6Paramsii
		.amdhsa_group_segment_fixed_size 148496
		.amdhsa_private_segment_fixed_size 0
		.amdhsa_kernarg_size 808
		.amdhsa_user_sgpr_count 2
		.amdhsa_user_sgpr_dispatch_ptr 0
		.amdhsa_user_sgpr_queue_ptr 0
		.amdhsa_user_sgpr_kernarg_segment_ptr 1
		.amdhsa_user_sgpr_dispatch_id 0
		.amdhsa_user_sgpr_kernarg_preload_length 0
		.amdhsa_user_sgpr_kernarg_preload_offset 0
		.amdhsa_user_sgpr_private_segment_size 0
		.amdhsa_uses_dynamic_stack 0
		.amdhsa_enable_private_segment 0
		.amdhsa_system_sgpr_workgroup_id_x 1
		.amdhsa_system_sgpr_workgroup_id_y 0
		.amdhsa_system_sgpr_workgroup_id_z 0
		.amdhsa_system_sgpr_workgroup_info 0
		.amdhsa_system_vgpr_workitem_id 2
		.amdhsa_next_free_vgpr 256
		.amdhsa_next_free_sgpr 100
		.amdhsa_accum_offset 256
		.amdhsa_reserve_vcc 1
		.amdhsa_float_round_mode_32 0
		.amdhsa_float_round_mode_16_64 0
		.amdhsa_float_denorm_mode_32 3
		.amdhsa_float_denorm_mode_16_64 3
		.amdhsa_dx10_clamp 1
		.amdhsa_ieee_mode 1
		.amdhsa_fp16_overflow 0
		.amdhsa_tg_split 0
		.amdhsa_exception_fp_ieee_invalid_op 0
		.amdhsa_exception_fp_denorm_src 0
		.amdhsa_exception_fp_ieee_div_zero 0
		.amdhsa_exception_fp_ieee_overflow 0
		.amdhsa_exception_fp_ieee_underflow 0
		.amdhsa_exception_fp_ieee_inexact 0
		.amdhsa_exception_int_div_zero 0
	.end_amdhsa_kernel

amdhsa.kernels:
  - .agpr_count:     0
    .args:
      - .offset:         0
        .size:           544
        .value_kind:     by_value
      - .offset:         544
        .size:           4
        .value_kind:     by_value
      - .offset:         548
        .size:           4
        .value_kind:     by_value
      - .offset:         552
        .size:           4
        .value_kind:     hidden_block_count_x
      - .offset:         556
        .size:           4
        .value_kind:     hidden_block_count_y
      - .offset:         560
        .size:           4
        .value_kind:     hidden_block_count_z
      - .offset:         564
        .size:           2
        .value_kind:     hidden_group_size_x
      - .offset:         566
        .size:           2
        .value_kind:     hidden_group_size_y
      - .offset:         568
        .size:           2
        .value_kind:     hidden_group_size_z
      - .offset:         570
        .size:           2
        .value_kind:     hidden_remainder_x
      - .offset:         572
        .size:           2
        .value_kind:     hidden_remainder_y
      - .offset:         574
        .size:           2
        .value_kind:     hidden_remainder_z
      - .offset:         592
        .size:           8
        .value_kind:     hidden_global_offset_x
      - .offset:         600
        .size:           8
        .value_kind:     hidden_global_offset_y
      - .offset:         608
        .size:           8
        .value_kind:     hidden_global_offset_z
      - .offset:         616
        .size:           2
        .value_kind:     hidden_grid_dims
      - .offset:         640
        .size:           8
        .value_kind:     hidden_multigrid_sync_arg
    .group_segment_fixed_size: 148496
    .kernarg_segment_align: 8
    .kernarg_segment_size: 808
    .language:       OpenCL C
    .language_version:
      - 2
      - 0
    .max_flat_workgroup_size: 512
    .name:           _Z4mega6Paramsii
    .private_segment_fixed_size: 0
    .sgpr_count:     106
    .sgpr_spill_count: 0
    .symbol:         _Z4mega6Paramsii.kd
    .uniform_work_group_size: 1
    .uses_dynamic_stack: false
    .vgpr_count:     256
    .vgpr_spill_count: 0
    .wavefront_size: 64
